# K-loop DMA issue order: B-operand pieces before A-operand pieces
# baseline (speedup 1.0000x reference)
.LBB0_49:
	v_lshrrev_b32_e32 v2, 6, v134
	v_lshlrev_b32_e32 v3, 4, v134
	v_bfe_u32 v0, v134, 3, 3
	v_and_b32_e32 v3, 0x70, v3
	v_and_b32_e32 v4, 8, v2
	v_or3_b32 v135, v3, v4, v0
	v_ashrrev_i32_e32 v0, 7, v134
	v_bfi_b32 v136, -8, v0, v2
	v_mul_u32_u24_e32 v0, 0x5a000, v135
	v_mov_b64_e32 v[2:3], s[58:59]
	s_mov_b32 s2, 0xb4000
	v_lshlrev_b32_e32 v0, 1, v0
	v_mad_i64_i32 v[6:7], s[2:3], v136, s2, v[2:3]
	v_mov_b32_e32 v2, v163
	v_lshl_add_u64 v[4:5], s[78:79], 0, v[0:1]
	s_nop 0
	v_ashrrev_i32_e32 v3, 3, v2
	v_lshlrev_b32_e32 v0, 4, v2
	v_mad_i64_i32 v[4:5], s[2:3], v3, s38, v[4:5]
	v_and_b32_e32 v0, 0x70, v0
	v_lshl_add_u64 v[130:131], v[4:5], 0, v[0:1]
	v_add_co_u32_e32 v32, vcc, s39, v130
	v_mad_i64_i32 v[4:5], s[2:3], v3, s38, v[6:7]
	v_lshl_add_u64 v[132:133], v[4:5], 0, v[0:1]
	v_and_b32_e32 v110, 7, v163
	v_bfe_u32 v111, v163, 4, 3
	v_xor_b32_e32 v111, v111, v110
	v_sub_u32_e32 v111, v111, v110
	v_lshlrev_b32_e32 v111, 4, v111
	v_lshrrev_b32_e32 v112, 6, v163
	v_lshlrev_b32_e32 v112, 10, v112
	v_readfirstlane_b32 s2, v130
	v_readfirstlane_b32 s3, v131
	v_readfirstlane_b32 s4, v132
	v_readfirstlane_b32 s5, v133
	v_readfirstlane_b32 s6, v112
	s_nop 3
	v_subrev_u32_e32 v98, s2, v130
	v_subrev_u32_e32 v102, s4, v132
	v_add_u32_e32 v98, v98, v111
	v_add_u32_e32 v102, v102, v111
	v_add_u32_e32 v99, 0x2d000, v98
	v_add_u32_e32 v103, 0x2d000, v102
	v_add_u32_e32 v100, 0x5a000, v98
	v_add_u32_e32 v104, 0x5a000, v102
	v_add_u32_e32 v101, 0x87000, v98
	v_add_u32_e32 v105, 0x87000, v102
	v_lshlrev_b32_e32 v110, 3, v163
	v_lshlrev_b32_e32 v111, 7, v163
	v_and_b32_e32 v112, 0x2000, v111
	v_and_b32_e32 v111, 0x780, v111
	v_and_b32_e32 v107, 64, v110
	v_xor_b32_e32 v110, v110, v163
	v_and_b32_e32 v110, 48, v110
	v_or3_b32 v110, v111, v107, v110
	v_lshlrev_b32_e32 v111, 6, v163
	v_and_b32_e32 v111, 0xffffe000, v111
	v_or_b32_e32 v108, v110, v112
	v_or_b32_e32 v106, v110, v111
	v_xor_b32_e32 v107, 64, v106
	v_xor_b32_e32 v109, 64, v108
	s_add_u32 m0, s6, 0x4000
	s_nop 0
	global_load_lds_dwordx4 v102, s[4:5]
	s_add_u32 m0, s6, 0x5000
	s_nop 0
	global_load_lds_dwordx4 v103, s[4:5]
	s_add_u32 m0, s6, 0x6000
	s_nop 0
	global_load_lds_dwordx4 v104, s[4:5]
	s_add_u32 m0, s6, 0x7000
	s_nop 0
	global_load_lds_dwordx4 v105, s[4:5]
	s_mov_b32 m0, s6
	s_nop 0
	global_load_lds_dwordx4 v98, s[2:3]
	s_add_u32 m0, s6, 0x1000
	s_nop 0
	global_load_lds_dwordx4 v99, s[2:3]
	s_add_u32 m0, s6, 0x2000
	s_nop 0
	global_load_lds_dwordx4 v100, s[2:3]
	s_add_u32 m0, s6, 0x3000
	s_nop 0
	global_load_lds_dwordx4 v101, s[2:3]
	s_waitcnt vmcnt(0)
	s_add_u32 s2, s2, 0x80
	s_addc_u32 s3, s3, 0
	s_add_u32 s4, s4, 0x80
	s_addc_u32 s5, s5, 0
	s_barrier
	s_add_u32 m0, s6, 0xc000
	ds_read_b128 v[142:145], v106
	ds_read_b128 v[158:161], v108 offset:16384
	s_nop 0
	global_load_lds_dwordx4 v102, s[4:5]
	s_add_u32 m0, s6, 0xd000
	ds_read_b128 v[182:185], v108 offset:18432
	ds_read_b128 v[186:189], v108 offset:20480
	s_nop 0
	global_load_lds_dwordx4 v103, s[4:5]
	s_add_u32 m0, s6, 0xe000
	ds_read_b128 v[206:209], v108 offset:22528
	ds_read_b128 v[146:149], v106 offset:2048
	s_nop 0
	global_load_lds_dwordx4 v104, s[4:5]
	s_add_u32 m0, s6, 0xf000
	ds_read_b128 v[150:153], v106 offset:4096
	ds_read_b128 v[154:157], v106 offset:6144
	s_nop 0
	global_load_lds_dwordx4 v105, s[4:5]
	s_add_u32 m0, s6, 0x8000
	s_nop 0
	global_load_lds_dwordx4 v98, s[2:3]
	s_add_u32 m0, s6, 0x9000
	s_nop 0
	global_load_lds_dwordx4 v99, s[2:3]
	s_add_u32 m0, s6, 0xa000
	s_nop 0
	global_load_lds_dwordx4 v100, s[2:3]
	s_add_u32 m0, s6, 0xb000
	s_nop 0
	global_load_lds_dwordx4 v101, s[2:3]
	s_add_u32 s2, s2, 0x80
	s_addc_u32 s3, s3, 0
	s_add_u32 s4, s4, 0x80
	s_addc_u32 s5, s5, 0
	s_waitcnt lgkmcnt(0)
	v_mfma_f32_16x16x32_bf16 v[94:97], v[158:161], v[142:145], 0
	ds_read_b128 v[34:37], v107
	ds_read_b128 v[54:57], v109 offset:16384
	v_mfma_f32_16x16x32_bf16 v[90:93], v[182:185], v[142:145], 0
	v_mfma_f32_16x16x32_bf16 v[86:89], v[186:189], v[142:145], 0
	ds_read_b128 v[62:65], v109 offset:18432
	ds_read_b128 v[66:69], v109 offset:20480
	v_mfma_f32_16x16x32_bf16 v[82:85], v[206:209], v[142:145], 0
	v_mfma_f32_16x16x32_bf16 v[74:77], v[158:161], v[146:149], 0
	ds_read_b128 v[78:81], v109 offset:22528
	ds_read_b128 v[38:41], v107 offset:2048
	v_mfma_f32_16x16x32_bf16 v[70:73], v[182:185], v[146:149], 0
	v_mfma_f32_16x16x32_bf16 v[58:61], v[186:189], v[146:149], 0
	ds_read_b128 v[46:49], v107 offset:4096
	ds_read_b128 v[50:53], v107 offset:6144
	v_mfma_f32_16x16x32_bf16 v[42:45], v[206:209], v[146:149], 0
	v_mfma_f32_16x16x32_bf16 v[30:33], v[158:161], v[150:153], 0
	v_mfma_f32_16x16x32_bf16 v[26:29], v[182:185], v[150:153], 0
	v_mfma_f32_16x16x32_bf16 v[22:25], v[186:189], v[150:153], 0
	v_mfma_f32_16x16x32_bf16 v[18:21], v[206:209], v[150:153], 0
	v_mfma_f32_16x16x32_bf16 v[14:17], v[158:161], v[154:157], 0
	v_mfma_f32_16x16x32_bf16 v[10:13], v[182:185], v[154:157], 0
	v_mfma_f32_16x16x32_bf16 v[6:9], v[186:189], v[154:157], 0
	v_mfma_f32_16x16x32_bf16 v[2:5], v[206:209], v[154:157], 0
	s_waitcnt vmcnt(0) lgkmcnt(0)
	s_barrier
	s_movk_i32 s7, 21
.Lg10_loop:
	v_mfma_f32_16x16x32_bf16 v[94:97], v[54:57], v[34:37], v[94:97]
	s_add_u32 m0, s6, 0x4000
	ds_read_b128 v[142:145], v106 offset:32768
	ds_read_b128 v[158:161], v108 offset:49152
	v_mfma_f32_16x16x32_bf16 v[90:93], v[62:65], v[34:37], v[90:93]
	global_load_lds_dwordx4 v102, s[4:5]
	v_mfma_f32_16x16x32_bf16 v[86:89], v[66:69], v[34:37], v[86:89]
	s_add_u32 m0, s6, 0x5000
	ds_read_b128 v[182:185], v108 offset:51200
	ds_read_b128 v[186:189], v108 offset:53248
	v_mfma_f32_16x16x32_bf16 v[82:85], v[78:81], v[34:37], v[82:85]
	global_load_lds_dwordx4 v103, s[4:5]
	v_mfma_f32_16x16x32_bf16 v[74:77], v[54:57], v[38:41], v[74:77]
	s_add_u32 m0, s6, 0x6000
	ds_read_b128 v[206:209], v108 offset:55296
	ds_read_b128 v[146:149], v106 offset:34816
	v_mfma_f32_16x16x32_bf16 v[70:73], v[62:65], v[38:41], v[70:73]
	global_load_lds_dwordx4 v104, s[4:5]
	v_mfma_f32_16x16x32_bf16 v[58:61], v[66:69], v[38:41], v[58:61]
	s_add_u32 m0, s6, 0x7000
	ds_read_b128 v[150:153], v106 offset:36864
	ds_read_b128 v[154:157], v106 offset:38912
	v_mfma_f32_16x16x32_bf16 v[42:45], v[78:81], v[38:41], v[42:45]
	global_load_lds_dwordx4 v105, s[4:5]
	v_mfma_f32_16x16x32_bf16 v[30:33], v[54:57], v[46:49], v[30:33]
	s_mov_b32 m0, s6
	v_mfma_f32_16x16x32_bf16 v[26:29], v[62:65], v[46:49], v[26:29]
	global_load_lds_dwordx4 v98, s[2:3]
	v_mfma_f32_16x16x32_bf16 v[22:25], v[66:69], v[46:49], v[22:25]
	s_add_u32 m0, s6, 0x1000
	v_mfma_f32_16x16x32_bf16 v[18:21], v[78:81], v[46:49], v[18:21]
	global_load_lds_dwordx4 v99, s[2:3]
	v_mfma_f32_16x16x32_bf16 v[14:17], v[54:57], v[50:53], v[14:17]
	s_add_u32 m0, s6, 0x2000
	v_mfma_f32_16x16x32_bf16 v[10:13], v[62:65], v[50:53], v[10:13]
	global_load_lds_dwordx4 v100, s[2:3]
	v_mfma_f32_16x16x32_bf16 v[6:9], v[66:69], v[50:53], v[6:9]
	s_add_u32 m0, s6, 0x3000
	v_mfma_f32_16x16x32_bf16 v[2:5], v[78:81], v[50:53], v[2:5]
	global_load_lds_dwordx4 v101, s[2:3]
	s_add_u32 s2, s2, 0x80
	s_addc_u32 s3, s3, 0
	s_add_u32 s4, s4, 0x80
	s_addc_u32 s5, s5, 0
	s_waitcnt lgkmcnt(0)
	v_mfma_f32_16x16x32_bf16 v[94:97], v[158:161], v[142:145], v[94:97]
	ds_read_b128 v[34:37], v107 offset:32768
	ds_read_b128 v[54:57], v109 offset:49152
	v_mfma_f32_16x16x32_bf16 v[90:93], v[182:185], v[142:145], v[90:93]
	v_mfma_f32_16x16x32_bf16 v[86:89], v[186:189], v[142:145], v[86:89]
	ds_read_b128 v[62:65], v109 offset:51200
	ds_read_b128 v[66:69], v109 offset:53248
	v_mfma_f32_16x16x32_bf16 v[82:85], v[206:209], v[142:145], v[82:85]
	v_mfma_f32_16x16x32_bf16 v[74:77], v[158:161], v[146:149], v[74:77]
	ds_read_b128 v[78:81], v109 offset:55296
	ds_read_b128 v[38:41], v107 offset:34816
	v_mfma_f32_16x16x32_bf16 v[70:73], v[182:185], v[146:149], v[70:73]
	v_mfma_f32_16x16x32_bf16 v[58:61], v[186:189], v[146:149], v[58:61]
	ds_read_b128 v[46:49], v107 offset:36864
	ds_read_b128 v[50:53], v107 offset:38912
	v_mfma_f32_16x16x32_bf16 v[42:45], v[206:209], v[146:149], v[42:45]
	v_mfma_f32_16x16x32_bf16 v[30:33], v[158:161], v[150:153], v[30:33]
	v_mfma_f32_16x16x32_bf16 v[26:29], v[182:185], v[150:153], v[26:29]
	v_mfma_f32_16x16x32_bf16 v[22:25], v[186:189], v[150:153], v[22:25]
	v_mfma_f32_16x16x32_bf16 v[18:21], v[206:209], v[150:153], v[18:21]
	v_mfma_f32_16x16x32_bf16 v[14:17], v[158:161], v[154:157], v[14:17]
	v_mfma_f32_16x16x32_bf16 v[10:13], v[182:185], v[154:157], v[10:13]
	v_mfma_f32_16x16x32_bf16 v[6:9], v[186:189], v[154:157], v[6:9]
	v_mfma_f32_16x16x32_bf16 v[2:5], v[206:209], v[154:157], v[2:5]
	s_waitcnt vmcnt(0) lgkmcnt(0)
	s_barrier
	v_mfma_f32_16x16x32_bf16 v[94:97], v[54:57], v[34:37], v[94:97]
	s_add_u32 m0, s6, 0xc000
	ds_read_b128 v[142:145], v106
	ds_read_b128 v[158:161], v108 offset:16384
	v_mfma_f32_16x16x32_bf16 v[90:93], v[62:65], v[34:37], v[90:93]
	global_load_lds_dwordx4 v102, s[4:5]
	v_mfma_f32_16x16x32_bf16 v[86:89], v[66:69], v[34:37], v[86:89]
	s_add_u32 m0, s6, 0xd000
	ds_read_b128 v[182:185], v108 offset:18432
	ds_read_b128 v[186:189], v108 offset:20480
	v_mfma_f32_16x16x32_bf16 v[82:85], v[78:81], v[34:37], v[82:85]
	global_load_lds_dwordx4 v103, s[4:5]
	v_mfma_f32_16x16x32_bf16 v[74:77], v[54:57], v[38:41], v[74:77]
	s_add_u32 m0, s6, 0xe000
	ds_read_b128 v[206:209], v108 offset:22528
	ds_read_b128 v[146:149], v106 offset:2048
	v_mfma_f32_16x16x32_bf16 v[70:73], v[62:65], v[38:41], v[70:73]
	global_load_lds_dwordx4 v104, s[4:5]
	v_mfma_f32_16x16x32_bf16 v[58:61], v[66:69], v[38:41], v[58:61]
	s_add_u32 m0, s6, 0xf000
	ds_read_b128 v[150:153], v106 offset:4096
	ds_read_b128 v[154:157], v106 offset:6144
	v_mfma_f32_16x16x32_bf16 v[42:45], v[78:81], v[38:41], v[42:45]
	global_load_lds_dwordx4 v105, s[4:5]
	v_mfma_f32_16x16x32_bf16 v[30:33], v[54:57], v[46:49], v[30:33]
	s_add_u32 m0, s6, 0x8000
	v_mfma_f32_16x16x32_bf16 v[26:29], v[62:65], v[46:49], v[26:29]
	global_load_lds_dwordx4 v98, s[2:3]
	v_mfma_f32_16x16x32_bf16 v[22:25], v[66:69], v[46:49], v[22:25]
	s_add_u32 m0, s6, 0x9000
	v_mfma_f32_16x16x32_bf16 v[18:21], v[78:81], v[46:49], v[18:21]
	global_load_lds_dwordx4 v99, s[2:3]
	v_mfma_f32_16x16x32_bf16 v[14:17], v[54:57], v[50:53], v[14:17]
	s_add_u32 m0, s6, 0xa000
	v_mfma_f32_16x16x32_bf16 v[10:13], v[62:65], v[50:53], v[10:13]
	global_load_lds_dwordx4 v100, s[2:3]
	v_mfma_f32_16x16x32_bf16 v[6:9], v[66:69], v[50:53], v[6:9]
	s_add_u32 m0, s6, 0xb000
	v_mfma_f32_16x16x32_bf16 v[2:5], v[78:81], v[50:53], v[2:5]
	global_load_lds_dwordx4 v101, s[2:3]
	s_add_u32 s2, s2, 0x80
	s_addc_u32 s3, s3, 0
	s_add_u32 s4, s4, 0x80
	s_addc_u32 s5, s5, 0
	s_waitcnt lgkmcnt(0)
	v_mfma_f32_16x16x32_bf16 v[94:97], v[158:161], v[142:145], v[94:97]
	ds_read_b128 v[34:37], v107
	ds_read_b128 v[54:57], v109 offset:16384
	v_mfma_f32_16x16x32_bf16 v[90:93], v[182:185], v[142:145], v[90:93]
	v_mfma_f32_16x16x32_bf16 v[86:89], v[186:189], v[142:145], v[86:89]
	ds_read_b128 v[62:65], v109 offset:18432
	ds_read_b128 v[66:69], v109 offset:20480
	v_mfma_f32_16x16x32_bf16 v[82:85], v[206:209], v[142:145], v[82:85]
	v_mfma_f32_16x16x32_bf16 v[74:77], v[158:161], v[146:149], v[74:77]
	ds_read_b128 v[78:81], v109 offset:22528
	ds_read_b128 v[38:41], v107 offset:2048
	v_mfma_f32_16x16x32_bf16 v[70:73], v[182:185], v[146:149], v[70:73]
	v_mfma_f32_16x16x32_bf16 v[58:61], v[186:189], v[146:149], v[58:61]
	ds_read_b128 v[46:49], v107 offset:4096
	ds_read_b128 v[50:53], v107 offset:6144
	v_mfma_f32_16x16x32_bf16 v[42:45], v[206:209], v[146:149], v[42:45]
	v_mfma_f32_16x16x32_bf16 v[30:33], v[158:161], v[150:153], v[30:33]
	v_mfma_f32_16x16x32_bf16 v[26:29], v[182:185], v[150:153], v[26:29]
	v_mfma_f32_16x16x32_bf16 v[22:25], v[186:189], v[150:153], v[22:25]
	v_mfma_f32_16x16x32_bf16 v[18:21], v[206:209], v[150:153], v[18:21]
	v_mfma_f32_16x16x32_bf16 v[14:17], v[158:161], v[154:157], v[14:17]
	v_mfma_f32_16x16x32_bf16 v[10:13], v[182:185], v[154:157], v[10:13]
	v_mfma_f32_16x16x32_bf16 v[6:9], v[186:189], v[154:157], v[6:9]
	v_mfma_f32_16x16x32_bf16 v[2:5], v[206:209], v[154:157], v[2:5]
	s_add_i32 s7, s7, -1
	s_waitcnt vmcnt(0) lgkmcnt(0)
	s_barrier
	s_cmp_lg_u32 s7, 0
	s_cbranch_scc1 .Lg10_loop
	v_mfma_f32_16x16x32_bf16 v[94:97], v[54:57], v[34:37], v[94:97]
	ds_read_b128 v[142:145], v106 offset:32768
	ds_read_b128 v[158:161], v108 offset:49152
	v_mfma_f32_16x16x32_bf16 v[90:93], v[62:65], v[34:37], v[90:93]
	v_mfma_f32_16x16x32_bf16 v[86:89], v[66:69], v[34:37], v[86:89]
	ds_read_b128 v[182:185], v108 offset:51200
	ds_read_b128 v[186:189], v108 offset:53248
	v_mfma_f32_16x16x32_bf16 v[82:85], v[78:81], v[34:37], v[82:85]
	v_mfma_f32_16x16x32_bf16 v[74:77], v[54:57], v[38:41], v[74:77]
	ds_read_b128 v[206:209], v108 offset:55296
	ds_read_b128 v[146:149], v106 offset:34816
	v_mfma_f32_16x16x32_bf16 v[70:73], v[62:65], v[38:41], v[70:73]
	v_mfma_f32_16x16x32_bf16 v[58:61], v[66:69], v[38:41], v[58:61]
	ds_read_b128 v[150:153], v106 offset:36864
	ds_read_b128 v[154:157], v106 offset:38912
	v_mfma_f32_16x16x32_bf16 v[42:45], v[78:81], v[38:41], v[42:45]
	v_mfma_f32_16x16x32_bf16 v[30:33], v[54:57], v[46:49], v[30:33]
	v_mfma_f32_16x16x32_bf16 v[26:29], v[62:65], v[46:49], v[26:29]
	v_mfma_f32_16x16x32_bf16 v[22:25], v[66:69], v[46:49], v[22:25]
	v_mfma_f32_16x16x32_bf16 v[18:21], v[78:81], v[46:49], v[18:21]
	v_mfma_f32_16x16x32_bf16 v[14:17], v[54:57], v[50:53], v[14:17]
	v_mfma_f32_16x16x32_bf16 v[10:13], v[62:65], v[50:53], v[10:13]
	v_mfma_f32_16x16x32_bf16 v[6:9], v[66:69], v[50:53], v[6:9]
	v_mfma_f32_16x16x32_bf16 v[2:5], v[78:81], v[50:53], v[2:5]
	s_waitcnt lgkmcnt(0)
	v_mfma_f32_16x16x32_bf16 v[94:97], v[158:161], v[142:145], v[94:97]
	ds_read_b128 v[34:37], v107 offset:32768
	ds_read_b128 v[54:57], v109 offset:49152
	v_mfma_f32_16x16x32_bf16 v[90:93], v[182:185], v[142:145], v[90:93]
	v_mfma_f32_16x16x32_bf16 v[86:89], v[186:189], v[142:145], v[86:89]
	ds_read_b128 v[62:65], v109 offset:51200
	ds_read_b128 v[66:69], v109 offset:53248
	v_mfma_f32_16x16x32_bf16 v[82:85], v[206:209], v[142:145], v[82:85]
	v_mfma_f32_16x16x32_bf16 v[74:77], v[158:161], v[146:149], v[74:77]
	ds_read_b128 v[78:81], v109 offset:55296
	ds_read_b128 v[38:41], v107 offset:34816
	v_mfma_f32_16x16x32_bf16 v[70:73], v[182:185], v[146:149], v[70:73]
	v_mfma_f32_16x16x32_bf16 v[58:61], v[186:189], v[146:149], v[58:61]
	ds_read_b128 v[46:49], v107 offset:36864
	ds_read_b128 v[50:53], v107 offset:38912
	v_mfma_f32_16x16x32_bf16 v[42:45], v[206:209], v[146:149], v[42:45]
	v_mfma_f32_16x16x32_bf16 v[30:33], v[158:161], v[150:153], v[30:33]
	v_mfma_f32_16x16x32_bf16 v[26:29], v[182:185], v[150:153], v[26:29]
	v_mfma_f32_16x16x32_bf16 v[22:25], v[186:189], v[150:153], v[22:25]
	v_mfma_f32_16x16x32_bf16 v[18:21], v[206:209], v[150:153], v[18:21]
	v_mfma_f32_16x16x32_bf16 v[14:17], v[158:161], v[154:157], v[14:17]
	v_mfma_f32_16x16x32_bf16 v[10:13], v[182:185], v[154:157], v[10:13]
	v_mfma_f32_16x16x32_bf16 v[6:9], v[186:189], v[154:157], v[6:9]
	v_mfma_f32_16x16x32_bf16 v[2:5], v[206:209], v[154:157], v[2:5]
	s_waitcnt lgkmcnt(0)
	s_barrier
	v_mfma_f32_16x16x32_bf16 v[94:97], v[54:57], v[34:37], v[94:97]
	v_mfma_f32_16x16x32_bf16 v[90:93], v[62:65], v[34:37], v[90:93]
	v_mfma_f32_16x16x32_bf16 v[86:89], v[66:69], v[34:37], v[86:89]
	v_mfma_f32_16x16x32_bf16 v[82:85], v[78:81], v[34:37], v[82:85]
	v_mfma_f32_16x16x32_bf16 v[74:77], v[54:57], v[38:41], v[74:77]
	v_mfma_f32_16x16x32_bf16 v[70:73], v[62:65], v[38:41], v[70:73]
	v_mfma_f32_16x16x32_bf16 v[58:61], v[66:69], v[38:41], v[58:61]
	v_mfma_f32_16x16x32_bf16 v[42:45], v[78:81], v[38:41], v[42:45]
	v_mfma_f32_16x16x32_bf16 v[30:33], v[54:57], v[46:49], v[30:33]
	v_mfma_f32_16x16x32_bf16 v[26:29], v[62:65], v[46:49], v[26:29]
	v_mfma_f32_16x16x32_bf16 v[22:25], v[66:69], v[46:49], v[22:25]
	v_mfma_f32_16x16x32_bf16 v[18:21], v[78:81], v[46:49], v[18:21]
	v_mfma_f32_16x16x32_bf16 v[14:17], v[54:57], v[50:53], v[14:17]
	v_mfma_f32_16x16x32_bf16 v[10:13], v[62:65], v[50:53], v[10:13]
	v_mfma_f32_16x16x32_bf16 v[6:9], v[66:69], v[50:53], v[6:9]
	v_mfma_f32_16x16x32_bf16 v[2:5], v[78:81], v[50:53], v[2:5]
	s_nop 7
	s_nop 2
	s_branch .LBB0_48

.LBB0_59:
	s_movk_i32 s2, 0x13ff
	v_and_b32_e32 v0, 7, v134
	v_cmp_lt_i32_e32 vcc, s2, v134
	s_and_saveexec_b64 s[2:3], vcc
	s_xor_b64 s[2:3], exec, s[2:3]
	v_add_u32_e32 v2, 0xffffec00, v134
	v_bfe_u32 v3, v134, 3, 4
	v_lshl_or_b32 v135, v0, 4, v3
	v_lshrrev_b32_e32 v0, 7, v2
	v_add_u32_e32 v136, 40, v0
	s_andn2_saveexec_b64 s[2:3], s[2:3]
	v_lshrrev_b32_e32 v3, 6, v134
	v_bfe_u32 v2, v134, 3, 3
	v_lshlrev_b32_e32 v0, 4, v0
	v_and_b32_e32 v4, 8, v3
	v_or3_b32 v135, v0, v4, v2
	v_ashrrev_i32_e32 v0, 7, v134
	v_bfi_b32 v136, -8, v0, v3
	s_or_b64 exec, exec, s[2:3]
	v_mov_b64_e32 v[2:3], s[80:81]
	s_mov_b32 s4, 0x44000
	v_mad_u64_u32 v[4:5], s[2:3], v135, s4, v[2:3]
	v_mov_b64_e32 v[2:3], s[56:57]
	v_mad_i64_i32 v[6:7], s[2:3], v136, s4, v[2:3]
	v_mov_b32_e32 v2, v163
	s_mov_b32 s4, 0x22000
	v_ashrrev_i32_e32 v3, 3, v2
	v_lshlrev_b32_e32 v0, 4, v2
	v_mad_i64_i32 v[4:5], s[2:3], v3, s43, v[4:5]
	v_and_b32_e32 v0, 0x70, v0
	v_lshl_add_u64 v[130:131], v[4:5], 0, v[0:1]
	v_mad_i64_i32 v[4:5], s[2:3], v3, s43, v[6:7]
	v_lshl_add_u64 v[132:133], v[4:5], 0, v[0:1]
	v_and_b32_e32 v110, 7, v163
	v_bfe_u32 v111, v163, 4, 3
	v_xor_b32_e32 v111, v111, v110
	v_sub_u32_e32 v111, v111, v110
	v_lshlrev_b32_e32 v111, 4, v111
	v_lshrrev_b32_e32 v112, 6, v163
	v_lshlrev_b32_e32 v112, 10, v112
	v_readfirstlane_b32 s2, v130
	v_readfirstlane_b32 s3, v131
	v_readfirstlane_b32 s4, v132
	v_readfirstlane_b32 s5, v133
	v_readfirstlane_b32 s6, v112
	s_nop 3
	v_subrev_u32_e32 v98, s2, v130
	v_subrev_u32_e32 v102, s4, v132
	v_add_u32_e32 v98, v98, v111
	v_add_u32_e32 v102, v102, v111
	v_add_u32_e32 v99, 0x11000, v98
	v_add_u32_e32 v103, 0x11000, v102
	v_add_u32_e32 v100, 0x22000, v98
	v_add_u32_e32 v104, 0x22000, v102
	v_add_u32_e32 v101, 0x33000, v98
	v_add_u32_e32 v105, 0x33000, v102
	v_lshlrev_b32_e32 v110, 3, v163
	v_lshlrev_b32_e32 v111, 7, v163
	v_and_b32_e32 v112, 0x2000, v111
	v_and_b32_e32 v111, 0x780, v111
	v_and_b32_e32 v107, 64, v110
	v_xor_b32_e32 v110, v110, v163
	v_and_b32_e32 v110, 48, v110
	v_or3_b32 v110, v111, v107, v110
	v_lshlrev_b32_e32 v111, 6, v163
	v_and_b32_e32 v111, 0xffffe000, v111
	v_or_b32_e32 v108, v110, v112
	v_or_b32_e32 v106, v110, v111
	v_xor_b32_e32 v107, 64, v106
	v_xor_b32_e32 v109, 64, v108
	s_add_u32 m0, s6, 0x4000
	s_nop 0
	global_load_lds_dwordx4 v102, s[4:5]
	s_add_u32 m0, s6, 0x5000
	s_nop 0
	global_load_lds_dwordx4 v103, s[4:5]
	s_add_u32 m0, s6, 0x6000
	s_nop 0
	global_load_lds_dwordx4 v104, s[4:5]
	s_add_u32 m0, s6, 0x7000
	s_nop 0
	global_load_lds_dwordx4 v105, s[4:5]
	s_mov_b32 m0, s6
	s_nop 0
	global_load_lds_dwordx4 v98, s[2:3]
	s_add_u32 m0, s6, 0x1000
	s_nop 0
	global_load_lds_dwordx4 v99, s[2:3]
	s_add_u32 m0, s6, 0x2000
	s_nop 0
	global_load_lds_dwordx4 v100, s[2:3]
	s_add_u32 m0, s6, 0x3000
	s_nop 0
	global_load_lds_dwordx4 v101, s[2:3]
	s_waitcnt vmcnt(0)
	s_add_u32 s2, s2, 0x80
	s_addc_u32 s3, s3, 0
	s_add_u32 s4, s4, 0x80
	s_addc_u32 s5, s5, 0
	s_barrier
	s_add_u32 m0, s6, 0xc000
	ds_read_b128 v[142:145], v106
	ds_read_b128 v[158:161], v108 offset:16384
	s_nop 0
	global_load_lds_dwordx4 v102, s[4:5]
	s_add_u32 m0, s6, 0xd000
	ds_read_b128 v[182:185], v108 offset:18432
	ds_read_b128 v[186:189], v108 offset:20480
	s_nop 0
	global_load_lds_dwordx4 v103, s[4:5]
	s_add_u32 m0, s6, 0xe000
	ds_read_b128 v[206:209], v108 offset:22528
	ds_read_b128 v[146:149], v106 offset:2048
	s_nop 0
	global_load_lds_dwordx4 v104, s[4:5]
	s_add_u32 m0, s6, 0xf000
	ds_read_b128 v[150:153], v106 offset:4096
	ds_read_b128 v[154:157], v106 offset:6144
	s_nop 0
	global_load_lds_dwordx4 v105, s[4:5]
	s_add_u32 m0, s6, 0x8000
	s_nop 0
	global_load_lds_dwordx4 v98, s[2:3]
	s_add_u32 m0, s6, 0x9000
	s_nop 0
	global_load_lds_dwordx4 v99, s[2:3]
	s_add_u32 m0, s6, 0xa000
	s_nop 0
	global_load_lds_dwordx4 v100, s[2:3]
	s_add_u32 m0, s6, 0xb000
	s_nop 0
	global_load_lds_dwordx4 v101, s[2:3]
	s_add_u32 s2, s2, 0x80
	s_addc_u32 s3, s3, 0
	s_add_u32 s4, s4, 0x80
	s_addc_u32 s5, s5, 0
	s_waitcnt lgkmcnt(0)
	v_mfma_f32_16x16x32_bf16 v[90:93], v[158:161], v[142:145], 0
	ds_read_b128 v[58:61], v107
	ds_read_b128 v[74:77], v109 offset:16384
	v_mfma_f32_16x16x32_bf16 v[54:57], v[182:185], v[142:145], 0
	v_mfma_f32_16x16x32_bf16 v[86:89], v[186:189], v[142:145], 0
	ds_read_b128 v[78:81], v109 offset:18432
	ds_read_b128 v[82:85], v109 offset:20480
	v_mfma_f32_16x16x32_bf16 v[50:53], v[206:209], v[142:145], 0
	v_mfma_f32_16x16x32_bf16 v[46:49], v[158:161], v[146:149], 0
	ds_read_b128 v[94:97], v109 offset:22528
	ds_read_b128 v[62:65], v107 offset:2048
	v_mfma_f32_16x16x32_bf16 v[38:41], v[182:185], v[146:149], 0
	v_mfma_f32_16x16x32_bf16 v[42:45], v[186:189], v[146:149], 0
	ds_read_b128 v[66:69], v107 offset:4096
	ds_read_b128 v[70:73], v107 offset:6144
	v_mfma_f32_16x16x32_bf16 v[34:37], v[206:209], v[146:149], 0
	v_mfma_f32_16x16x32_bf16 v[30:33], v[158:161], v[150:153], 0
	v_mfma_f32_16x16x32_bf16 v[22:25], v[182:185], v[150:153], 0
	v_mfma_f32_16x16x32_bf16 v[26:29], v[186:189], v[150:153], 0
	v_mfma_f32_16x16x32_bf16 v[18:21], v[206:209], v[150:153], 0
	v_mfma_f32_16x16x32_bf16 v[10:13], v[158:161], v[154:157], 0
	v_mfma_f32_16x16x32_bf16 v[2:5], v[182:185], v[154:157], 0
	v_mfma_f32_16x16x32_bf16 v[14:17], v[186:189], v[154:157], 0
	v_mfma_f32_16x16x32_bf16 v[6:9], v[206:209], v[154:157], 0
	s_waitcnt vmcnt(0) lgkmcnt(0)
	s_barrier
	s_movk_i32 s7, 7
.Lg9_loop:
	v_mfma_f32_16x16x32_bf16 v[90:93], v[74:77], v[58:61], v[90:93]
	s_add_u32 m0, s6, 0x4000
	ds_read_b128 v[142:145], v106 offset:32768
	ds_read_b128 v[158:161], v108 offset:49152
	v_mfma_f32_16x16x32_bf16 v[54:57], v[78:81], v[58:61], v[54:57]
	global_load_lds_dwordx4 v102, s[4:5]
	v_mfma_f32_16x16x32_bf16 v[86:89], v[82:85], v[58:61], v[86:89]
	s_add_u32 m0, s6, 0x5000
	ds_read_b128 v[182:185], v108 offset:51200
	ds_read_b128 v[186:189], v108 offset:53248
	v_mfma_f32_16x16x32_bf16 v[50:53], v[94:97], v[58:61], v[50:53]
	global_load_lds_dwordx4 v103, s[4:5]
	v_mfma_f32_16x16x32_bf16 v[46:49], v[74:77], v[62:65], v[46:49]
	s_add_u32 m0, s6, 0x6000
	ds_read_b128 v[206:209], v108 offset:55296
	ds_read_b128 v[146:149], v106 offset:34816
	v_mfma_f32_16x16x32_bf16 v[38:41], v[78:81], v[62:65], v[38:41]
	global_load_lds_dwordx4 v104, s[4:5]
	v_mfma_f32_16x16x32_bf16 v[42:45], v[82:85], v[62:65], v[42:45]
	s_add_u32 m0, s6, 0x7000
	ds_read_b128 v[150:153], v106 offset:36864
	ds_read_b128 v[154:157], v106 offset:38912
	v_mfma_f32_16x16x32_bf16 v[34:37], v[94:97], v[62:65], v[34:37]
	global_load_lds_dwordx4 v105, s[4:5]
	v_mfma_f32_16x16x32_bf16 v[30:33], v[74:77], v[66:69], v[30:33]
	s_mov_b32 m0, s6
	v_mfma_f32_16x16x32_bf16 v[22:25], v[78:81], v[66:69], v[22:25]
	global_load_lds_dwordx4 v98, s[2:3]
	v_mfma_f32_16x16x32_bf16 v[26:29], v[82:85], v[66:69], v[26:29]
	s_add_u32 m0, s6, 0x1000
	v_mfma_f32_16x16x32_bf16 v[18:21], v[94:97], v[66:69], v[18:21]
	global_load_lds_dwordx4 v99, s[2:3]
	v_mfma_f32_16x16x32_bf16 v[10:13], v[74:77], v[70:73], v[10:13]
	s_add_u32 m0, s6, 0x2000
	v_mfma_f32_16x16x32_bf16 v[2:5], v[78:81], v[70:73], v[2:5]
	global_load_lds_dwordx4 v100, s[2:3]
	v_mfma_f32_16x16x32_bf16 v[14:17], v[82:85], v[70:73], v[14:17]
	s_add_u32 m0, s6, 0x3000
	v_mfma_f32_16x16x32_bf16 v[6:9], v[94:97], v[70:73], v[6:9]
	global_load_lds_dwordx4 v101, s[2:3]
	s_add_u32 s2, s2, 0x80
	s_addc_u32 s3, s3, 0
	s_add_u32 s4, s4, 0x80
	s_addc_u32 s5, s5, 0
	s_waitcnt lgkmcnt(0)
	v_mfma_f32_16x16x32_bf16 v[90:93], v[158:161], v[142:145], v[90:93]
	ds_read_b128 v[58:61], v107 offset:32768
	ds_read_b128 v[74:77], v109 offset:49152
	v_mfma_f32_16x16x32_bf16 v[54:57], v[182:185], v[142:145], v[54:57]
	v_mfma_f32_16x16x32_bf16 v[86:89], v[186:189], v[142:145], v[86:89]
	ds_read_b128 v[78:81], v109 offset:51200
	ds_read_b128 v[82:85], v109 offset:53248
	v_mfma_f32_16x16x32_bf16 v[50:53], v[206:209], v[142:145], v[50:53]
	v_mfma_f32_16x16x32_bf16 v[46:49], v[158:161], v[146:149], v[46:49]
	ds_read_b128 v[94:97], v109 offset:55296
	ds_read_b128 v[62:65], v107 offset:34816
	v_mfma_f32_16x16x32_bf16 v[38:41], v[182:185], v[146:149], v[38:41]
	v_mfma_f32_16x16x32_bf16 v[42:45], v[186:189], v[146:149], v[42:45]
	ds_read_b128 v[66:69], v107 offset:36864
	ds_read_b128 v[70:73], v107 offset:38912
	v_mfma_f32_16x16x32_bf16 v[34:37], v[206:209], v[146:149], v[34:37]
	v_mfma_f32_16x16x32_bf16 v[30:33], v[158:161], v[150:153], v[30:33]
	v_mfma_f32_16x16x32_bf16 v[22:25], v[182:185], v[150:153], v[22:25]
	v_mfma_f32_16x16x32_bf16 v[26:29], v[186:189], v[150:153], v[26:29]
	v_mfma_f32_16x16x32_bf16 v[18:21], v[206:209], v[150:153], v[18:21]
	v_mfma_f32_16x16x32_bf16 v[10:13], v[158:161], v[154:157], v[10:13]
	v_mfma_f32_16x16x32_bf16 v[2:5], v[182:185], v[154:157], v[2:5]
	v_mfma_f32_16x16x32_bf16 v[14:17], v[186:189], v[154:157], v[14:17]
	v_mfma_f32_16x16x32_bf16 v[6:9], v[206:209], v[154:157], v[6:9]
	s_waitcnt vmcnt(0) lgkmcnt(0)
	s_barrier
	v_mfma_f32_16x16x32_bf16 v[90:93], v[74:77], v[58:61], v[90:93]
	s_add_u32 m0, s6, 0xc000
	ds_read_b128 v[142:145], v106
	ds_read_b128 v[158:161], v108 offset:16384
	v_mfma_f32_16x16x32_bf16 v[54:57], v[78:81], v[58:61], v[54:57]
	global_load_lds_dwordx4 v102, s[4:5]
	v_mfma_f32_16x16x32_bf16 v[86:89], v[82:85], v[58:61], v[86:89]
	s_add_u32 m0, s6, 0xd000
	ds_read_b128 v[182:185], v108 offset:18432
	ds_read_b128 v[186:189], v108 offset:20480
	v_mfma_f32_16x16x32_bf16 v[50:53], v[94:97], v[58:61], v[50:53]
	global_load_lds_dwordx4 v103, s[4:5]
	v_mfma_f32_16x16x32_bf16 v[46:49], v[74:77], v[62:65], v[46:49]
	s_add_u32 m0, s6, 0xe000
	ds_read_b128 v[206:209], v108 offset:22528
	ds_read_b128 v[146:149], v106 offset:2048
	v_mfma_f32_16x16x32_bf16 v[38:41], v[78:81], v[62:65], v[38:41]
	global_load_lds_dwordx4 v104, s[4:5]
	v_mfma_f32_16x16x32_bf16 v[42:45], v[82:85], v[62:65], v[42:45]
	s_add_u32 m0, s6, 0xf000
	ds_read_b128 v[150:153], v106 offset:4096
	ds_read_b128 v[154:157], v106 offset:6144
	v_mfma_f32_16x16x32_bf16 v[34:37], v[94:97], v[62:65], v[34:37]
	global_load_lds_dwordx4 v105, s[4:5]
	v_mfma_f32_16x16x32_bf16 v[30:33], v[74:77], v[66:69], v[30:33]
	s_add_u32 m0, s6, 0x8000
	v_mfma_f32_16x16x32_bf16 v[22:25], v[78:81], v[66:69], v[22:25]
	global_load_lds_dwordx4 v98, s[2:3]
	v_mfma_f32_16x16x32_bf16 v[26:29], v[82:85], v[66:69], v[26:29]
	s_add_u32 m0, s6, 0x9000
	v_mfma_f32_16x16x32_bf16 v[18:21], v[94:97], v[66:69], v[18:21]
	global_load_lds_dwordx4 v99, s[2:3]
	v_mfma_f32_16x16x32_bf16 v[10:13], v[74:77], v[70:73], v[10:13]
	s_add_u32 m0, s6, 0xa000
	v_mfma_f32_16x16x32_bf16 v[2:5], v[78:81], v[70:73], v[2:5]
	global_load_lds_dwordx4 v100, s[2:3]
	v_mfma_f32_16x16x32_bf16 v[14:17], v[82:85], v[70:73], v[14:17]
	s_add_u32 m0, s6, 0xb000
	v_mfma_f32_16x16x32_bf16 v[6:9], v[94:97], v[70:73], v[6:9]
	global_load_lds_dwordx4 v101, s[2:3]
	s_add_u32 s2, s2, 0x80
	s_addc_u32 s3, s3, 0
	s_add_u32 s4, s4, 0x80
	s_addc_u32 s5, s5, 0
	s_waitcnt lgkmcnt(0)
	v_mfma_f32_16x16x32_bf16 v[90:93], v[158:161], v[142:145], v[90:93]
	ds_read_b128 v[58:61], v107
	ds_read_b128 v[74:77], v109 offset:16384
	v_mfma_f32_16x16x32_bf16 v[54:57], v[182:185], v[142:145], v[54:57]
	v_mfma_f32_16x16x32_bf16 v[86:89], v[186:189], v[142:145], v[86:89]
	ds_read_b128 v[78:81], v109 offset:18432
	ds_read_b128 v[82:85], v109 offset:20480
	v_mfma_f32_16x16x32_bf16 v[50:53], v[206:209], v[142:145], v[50:53]
	v_mfma_f32_16x16x32_bf16 v[46:49], v[158:161], v[146:149], v[46:49]
	ds_read_b128 v[94:97], v109 offset:22528
	ds_read_b128 v[62:65], v107 offset:2048
	v_mfma_f32_16x16x32_bf16 v[38:41], v[182:185], v[146:149], v[38:41]
	v_mfma_f32_16x16x32_bf16 v[42:45], v[186:189], v[146:149], v[42:45]
	ds_read_b128 v[66:69], v107 offset:4096
	ds_read_b128 v[70:73], v107 offset:6144
	v_mfma_f32_16x16x32_bf16 v[34:37], v[206:209], v[146:149], v[34:37]
	v_mfma_f32_16x16x32_bf16 v[30:33], v[158:161], v[150:153], v[30:33]
	v_mfma_f32_16x16x32_bf16 v[22:25], v[182:185], v[150:153], v[22:25]
	v_mfma_f32_16x16x32_bf16 v[26:29], v[186:189], v[150:153], v[26:29]
	v_mfma_f32_16x16x32_bf16 v[18:21], v[206:209], v[150:153], v[18:21]
	v_mfma_f32_16x16x32_bf16 v[10:13], v[158:161], v[154:157], v[10:13]
	v_mfma_f32_16x16x32_bf16 v[2:5], v[182:185], v[154:157], v[2:5]
	v_mfma_f32_16x16x32_bf16 v[14:17], v[186:189], v[154:157], v[14:17]
	v_mfma_f32_16x16x32_bf16 v[6:9], v[206:209], v[154:157], v[6:9]
	s_add_i32 s7, s7, -1
	s_waitcnt vmcnt(0) lgkmcnt(0)
	s_barrier
	s_cmp_lg_u32 s7, 0
	s_cbranch_scc1 .Lg9_loop
	v_mfma_f32_16x16x32_bf16 v[90:93], v[74:77], v[58:61], v[90:93]
	ds_read_b128 v[142:145], v106 offset:32768
	ds_read_b128 v[158:161], v108 offset:49152
	v_mfma_f32_16x16x32_bf16 v[54:57], v[78:81], v[58:61], v[54:57]
	v_mfma_f32_16x16x32_bf16 v[86:89], v[82:85], v[58:61], v[86:89]
	ds_read_b128 v[182:185], v108 offset:51200
	ds_read_b128 v[186:189], v108 offset:53248
	v_mfma_f32_16x16x32_bf16 v[50:53], v[94:97], v[58:61], v[50:53]
	v_mfma_f32_16x16x32_bf16 v[46:49], v[74:77], v[62:65], v[46:49]
	ds_read_b128 v[206:209], v108 offset:55296
	ds_read_b128 v[146:149], v106 offset:34816
	v_mfma_f32_16x16x32_bf16 v[38:41], v[78:81], v[62:65], v[38:41]
	v_mfma_f32_16x16x32_bf16 v[42:45], v[82:85], v[62:65], v[42:45]
	ds_read_b128 v[150:153], v106 offset:36864
	ds_read_b128 v[154:157], v106 offset:38912
	v_mfma_f32_16x16x32_bf16 v[34:37], v[94:97], v[62:65], v[34:37]
	v_mfma_f32_16x16x32_bf16 v[30:33], v[74:77], v[66:69], v[30:33]
	v_mfma_f32_16x16x32_bf16 v[22:25], v[78:81], v[66:69], v[22:25]
	v_mfma_f32_16x16x32_bf16 v[26:29], v[82:85], v[66:69], v[26:29]
	v_mfma_f32_16x16x32_bf16 v[18:21], v[94:97], v[66:69], v[18:21]
	v_mfma_f32_16x16x32_bf16 v[10:13], v[74:77], v[70:73], v[10:13]
	v_mfma_f32_16x16x32_bf16 v[2:5], v[78:81], v[70:73], v[2:5]
	v_mfma_f32_16x16x32_bf16 v[14:17], v[82:85], v[70:73], v[14:17]
	v_mfma_f32_16x16x32_bf16 v[6:9], v[94:97], v[70:73], v[6:9]
	s_waitcnt lgkmcnt(0)
	v_mfma_f32_16x16x32_bf16 v[90:93], v[158:161], v[142:145], v[90:93]
	ds_read_b128 v[58:61], v107 offset:32768
	ds_read_b128 v[74:77], v109 offset:49152
	v_mfma_f32_16x16x32_bf16 v[54:57], v[182:185], v[142:145], v[54:57]
	v_mfma_f32_16x16x32_bf16 v[86:89], v[186:189], v[142:145], v[86:89]
	ds_read_b128 v[78:81], v109 offset:51200
	ds_read_b128 v[82:85], v109 offset:53248
	v_mfma_f32_16x16x32_bf16 v[50:53], v[206:209], v[142:145], v[50:53]
	v_mfma_f32_16x16x32_bf16 v[46:49], v[158:161], v[146:149], v[46:49]
	ds_read_b128 v[94:97], v109 offset:55296
	ds_read_b128 v[62:65], v107 offset:34816
	v_mfma_f32_16x16x32_bf16 v[38:41], v[182:185], v[146:149], v[38:41]
	v_mfma_f32_16x16x32_bf16 v[42:45], v[186:189], v[146:149], v[42:45]
	ds_read_b128 v[66:69], v107 offset:36864
	ds_read_b128 v[70:73], v107 offset:38912
	v_mfma_f32_16x16x32_bf16 v[34:37], v[206:209], v[146:149], v[34:37]
	v_mfma_f32_16x16x32_bf16 v[30:33], v[158:161], v[150:153], v[30:33]
	v_mfma_f32_16x16x32_bf16 v[22:25], v[182:185], v[150:153], v[22:25]
	v_mfma_f32_16x16x32_bf16 v[26:29], v[186:189], v[150:153], v[26:29]
	v_mfma_f32_16x16x32_bf16 v[18:21], v[206:209], v[150:153], v[18:21]
	v_mfma_f32_16x16x32_bf16 v[10:13], v[158:161], v[154:157], v[10:13]
	v_mfma_f32_16x16x32_bf16 v[2:5], v[182:185], v[154:157], v[2:5]
	v_mfma_f32_16x16x32_bf16 v[14:17], v[186:189], v[154:157], v[14:17]
	v_mfma_f32_16x16x32_bf16 v[6:9], v[206:209], v[154:157], v[6:9]
	s_waitcnt lgkmcnt(0)
	s_barrier
	v_mfma_f32_16x16x32_bf16 v[90:93], v[74:77], v[58:61], v[90:93]
	v_mfma_f32_16x16x32_bf16 v[54:57], v[78:81], v[58:61], v[54:57]
	v_mfma_f32_16x16x32_bf16 v[86:89], v[82:85], v[58:61], v[86:89]
	v_mfma_f32_16x16x32_bf16 v[50:53], v[94:97], v[58:61], v[50:53]
	v_mfma_f32_16x16x32_bf16 v[46:49], v[74:77], v[62:65], v[46:49]
	v_mfma_f32_16x16x32_bf16 v[38:41], v[78:81], v[62:65], v[38:41]
	v_mfma_f32_16x16x32_bf16 v[42:45], v[82:85], v[62:65], v[42:45]
	v_mfma_f32_16x16x32_bf16 v[34:37], v[94:97], v[62:65], v[34:37]
	v_mfma_f32_16x16x32_bf16 v[30:33], v[74:77], v[66:69], v[30:33]
	v_mfma_f32_16x16x32_bf16 v[22:25], v[78:81], v[66:69], v[22:25]
	v_mfma_f32_16x16x32_bf16 v[26:29], v[82:85], v[66:69], v[26:29]
	v_mfma_f32_16x16x32_bf16 v[18:21], v[94:97], v[66:69], v[18:21]
	v_mfma_f32_16x16x32_bf16 v[10:13], v[74:77], v[70:73], v[10:13]
	v_mfma_f32_16x16x32_bf16 v[2:5], v[78:81], v[70:73], v[2:5]
	v_mfma_f32_16x16x32_bf16 v[14:17], v[82:85], v[70:73], v[14:17]
	v_mfma_f32_16x16x32_bf16 v[6:9], v[94:97], v[70:73], v[6:9]
	s_nop 7
	s_nop 2
	s_mov_b32 s21, 0x33000
	s_branch .LBB0_58

.LBB0_82:
	v_lshrrev_b32_e32 v2, 6, v134
	v_lshlrev_b32_e32 v3, 4, v134
	v_bfe_u32 v0, v134, 3, 3
	v_and_b32_e32 v3, 0x70, v3
	v_and_b32_e32 v4, 8, v2
	v_or3_b32 v135, v3, v4, v0
	v_ashrrev_i32_e32 v0, 7, v134
	v_bfi_b32 v136, -8, v0, v2
	v_mul_u32_u24_e32 v0, 0x22000, v135
	v_mov_b64_e32 v[2:3], s[54:55]
	s_mov_b32 s2, 0x44000
	v_lshlrev_b32_e32 v0, 1, v0
	v_mad_i64_i32 v[6:7], s[2:3], v136, s2, v[2:3]
	v_mov_b32_e32 v2, v163
	v_lshl_add_u64 v[4:5], s[80:81], 0, v[0:1]
	s_mov_b32 s4, 0x22000
	v_ashrrev_i32_e32 v3, 3, v2
	v_lshlrev_b32_e32 v0, 4, v2
	v_mad_i64_i32 v[4:5], s[2:3], v3, s43, v[4:5]
	v_and_b32_e32 v0, 0x70, v0
	v_lshl_add_u64 v[130:131], v[4:5], 0, v[0:1]
	v_mad_i64_i32 v[4:5], s[2:3], v3, s43, v[6:7]
	v_lshl_add_u64 v[132:133], v[4:5], 0, v[0:1]
	v_and_b32_e32 v110, 7, v163
	v_bfe_u32 v111, v163, 4, 3
	v_xor_b32_e32 v111, v111, v110
	v_sub_u32_e32 v111, v111, v110
	v_lshlrev_b32_e32 v111, 4, v111
	v_lshrrev_b32_e32 v112, 6, v163
	v_lshlrev_b32_e32 v112, 10, v112
	v_readfirstlane_b32 s2, v130
	v_readfirstlane_b32 s3, v131
	v_readfirstlane_b32 s4, v132
	v_readfirstlane_b32 s5, v133
	v_readfirstlane_b32 s6, v112
	s_nop 3
	v_subrev_u32_e32 v98, s2, v130
	v_subrev_u32_e32 v102, s4, v132
	v_add_u32_e32 v98, v98, v111
	v_add_u32_e32 v102, v102, v111
	v_add_u32_e32 v99, 0x11000, v98
	v_add_u32_e32 v103, 0x11000, v102
	v_add_u32_e32 v100, 0x22000, v98
	v_add_u32_e32 v104, 0x22000, v102
	v_add_u32_e32 v101, 0x33000, v98
	v_add_u32_e32 v105, 0x33000, v102
	v_lshlrev_b32_e32 v110, 3, v163
	v_lshlrev_b32_e32 v111, 7, v163
	v_and_b32_e32 v112, 0x2000, v111
	v_and_b32_e32 v111, 0x780, v111
	v_and_b32_e32 v107, 64, v110
	v_xor_b32_e32 v110, v110, v163
	v_and_b32_e32 v110, 48, v110
	v_or3_b32 v110, v111, v107, v110
	v_lshlrev_b32_e32 v111, 6, v163
	v_and_b32_e32 v111, 0xffffe000, v111
	v_or_b32_e32 v108, v110, v112
	v_or_b32_e32 v106, v110, v111
	v_xor_b32_e32 v107, 64, v106
	v_xor_b32_e32 v109, 64, v108
	s_add_u32 m0, s6, 0x4000
	s_nop 0
	global_load_lds_dwordx4 v102, s[4:5]
	s_add_u32 m0, s6, 0x5000
	s_nop 0
	global_load_lds_dwordx4 v103, s[4:5]
	s_add_u32 m0, s6, 0x6000
	s_nop 0
	global_load_lds_dwordx4 v104, s[4:5]
	s_add_u32 m0, s6, 0x7000
	s_nop 0
	global_load_lds_dwordx4 v105, s[4:5]
	s_mov_b32 m0, s6
	s_nop 0
	global_load_lds_dwordx4 v98, s[2:3]
	s_add_u32 m0, s6, 0x1000
	s_nop 0
	global_load_lds_dwordx4 v99, s[2:3]
	s_add_u32 m0, s6, 0x2000
	s_nop 0
	global_load_lds_dwordx4 v100, s[2:3]
	s_add_u32 m0, s6, 0x3000
	s_nop 0
	global_load_lds_dwordx4 v101, s[2:3]
	s_waitcnt vmcnt(0)
	s_add_u32 s2, s2, 0x80
	s_addc_u32 s3, s3, 0
	s_add_u32 s4, s4, 0x80
	s_addc_u32 s5, s5, 0
	s_barrier
	s_add_u32 m0, s6, 0xc000
	ds_read_b128 v[142:145], v106
	ds_read_b128 v[158:161], v108 offset:16384
	s_nop 0
	global_load_lds_dwordx4 v102, s[4:5]
	s_add_u32 m0, s6, 0xd000
	ds_read_b128 v[182:185], v108 offset:18432
	ds_read_b128 v[186:189], v108 offset:20480
	s_nop 0
	global_load_lds_dwordx4 v103, s[4:5]
	s_add_u32 m0, s6, 0xe000
	ds_read_b128 v[206:209], v108 offset:22528
	ds_read_b128 v[146:149], v106 offset:2048
	s_nop 0
	global_load_lds_dwordx4 v104, s[4:5]
	s_add_u32 m0, s6, 0xf000
	ds_read_b128 v[150:153], v106 offset:4096
	ds_read_b128 v[154:157], v106 offset:6144
	s_nop 0
	global_load_lds_dwordx4 v105, s[4:5]
	s_add_u32 m0, s6, 0x8000
	s_nop 0
	global_load_lds_dwordx4 v98, s[2:3]
	s_add_u32 m0, s6, 0x9000
	s_nop 0
	global_load_lds_dwordx4 v99, s[2:3]
	s_add_u32 m0, s6, 0xa000
	s_nop 0
	global_load_lds_dwordx4 v100, s[2:3]
	s_add_u32 m0, s6, 0xb000
	s_nop 0
	global_load_lds_dwordx4 v101, s[2:3]
	s_add_u32 s2, s2, 0x80
	s_addc_u32 s3, s3, 0
	s_add_u32 s4, s4, 0x80
	s_addc_u32 s5, s5, 0
	s_waitcnt lgkmcnt(0)
	v_mfma_f32_16x16x32_bf16 v[94:97], v[158:161], v[142:145], 0
	ds_read_b128 v[34:37], v107
	ds_read_b128 v[54:57], v109 offset:16384
	v_mfma_f32_16x16x32_bf16 v[90:93], v[182:185], v[142:145], 0
	v_mfma_f32_16x16x32_bf16 v[86:89], v[186:189], v[142:145], 0
	ds_read_b128 v[62:65], v109 offset:18432
	ds_read_b128 v[66:69], v109 offset:20480
	v_mfma_f32_16x16x32_bf16 v[82:85], v[206:209], v[142:145], 0
	v_mfma_f32_16x16x32_bf16 v[74:77], v[158:161], v[146:149], 0
	ds_read_b128 v[78:81], v109 offset:22528
	ds_read_b128 v[38:41], v107 offset:2048
	v_mfma_f32_16x16x32_bf16 v[70:73], v[182:185], v[146:149], 0
	v_mfma_f32_16x16x32_bf16 v[58:61], v[186:189], v[146:149], 0
	ds_read_b128 v[46:49], v107 offset:4096
	ds_read_b128 v[50:53], v107 offset:6144
	v_mfma_f32_16x16x32_bf16 v[42:45], v[206:209], v[146:149], 0
	v_mfma_f32_16x16x32_bf16 v[30:33], v[158:161], v[150:153], 0
	v_mfma_f32_16x16x32_bf16 v[26:29], v[182:185], v[150:153], 0
	v_mfma_f32_16x16x32_bf16 v[22:25], v[186:189], v[150:153], 0
	v_mfma_f32_16x16x32_bf16 v[18:21], v[206:209], v[150:153], 0
	v_mfma_f32_16x16x32_bf16 v[14:17], v[158:161], v[154:157], 0
	v_mfma_f32_16x16x32_bf16 v[10:13], v[182:185], v[154:157], 0
	v_mfma_f32_16x16x32_bf16 v[6:9], v[186:189], v[154:157], 0
	v_mfma_f32_16x16x32_bf16 v[2:5], v[206:209], v[154:157], 0
	s_waitcnt vmcnt(0) lgkmcnt(0)
	s_barrier
	s_movk_i32 s7, 7
.Lg7_loop:
	v_mfma_f32_16x16x32_bf16 v[94:97], v[54:57], v[34:37], v[94:97]
	s_add_u32 m0, s6, 0x4000
	ds_read_b128 v[142:145], v106 offset:32768
	ds_read_b128 v[158:161], v108 offset:49152
	v_mfma_f32_16x16x32_bf16 v[90:93], v[62:65], v[34:37], v[90:93]
	global_load_lds_dwordx4 v102, s[4:5]
	v_mfma_f32_16x16x32_bf16 v[86:89], v[66:69], v[34:37], v[86:89]
	s_add_u32 m0, s6, 0x5000
	ds_read_b128 v[182:185], v108 offset:51200
	ds_read_b128 v[186:189], v108 offset:53248
	v_mfma_f32_16x16x32_bf16 v[82:85], v[78:81], v[34:37], v[82:85]
	global_load_lds_dwordx4 v103, s[4:5]
	v_mfma_f32_16x16x32_bf16 v[74:77], v[54:57], v[38:41], v[74:77]
	s_add_u32 m0, s6, 0x6000
	ds_read_b128 v[206:209], v108 offset:55296
	ds_read_b128 v[146:149], v106 offset:34816
	v_mfma_f32_16x16x32_bf16 v[70:73], v[62:65], v[38:41], v[70:73]
	global_load_lds_dwordx4 v104, s[4:5]
	v_mfma_f32_16x16x32_bf16 v[58:61], v[66:69], v[38:41], v[58:61]
	s_add_u32 m0, s6, 0x7000
	ds_read_b128 v[150:153], v106 offset:36864
	ds_read_b128 v[154:157], v106 offset:38912
	v_mfma_f32_16x16x32_bf16 v[42:45], v[78:81], v[38:41], v[42:45]
	global_load_lds_dwordx4 v105, s[4:5]
	v_mfma_f32_16x16x32_bf16 v[30:33], v[54:57], v[46:49], v[30:33]
	s_mov_b32 m0, s6
	v_mfma_f32_16x16x32_bf16 v[26:29], v[62:65], v[46:49], v[26:29]
	global_load_lds_dwordx4 v98, s[2:3]
	v_mfma_f32_16x16x32_bf16 v[22:25], v[66:69], v[46:49], v[22:25]
	s_add_u32 m0, s6, 0x1000
	v_mfma_f32_16x16x32_bf16 v[18:21], v[78:81], v[46:49], v[18:21]
	global_load_lds_dwordx4 v99, s[2:3]
	v_mfma_f32_16x16x32_bf16 v[14:17], v[54:57], v[50:53], v[14:17]
	s_add_u32 m0, s6, 0x2000
	v_mfma_f32_16x16x32_bf16 v[10:13], v[62:65], v[50:53], v[10:13]
	global_load_lds_dwordx4 v100, s[2:3]
	v_mfma_f32_16x16x32_bf16 v[6:9], v[66:69], v[50:53], v[6:9]
	s_add_u32 m0, s6, 0x3000
	v_mfma_f32_16x16x32_bf16 v[2:5], v[78:81], v[50:53], v[2:5]
	global_load_lds_dwordx4 v101, s[2:3]
	s_add_u32 s2, s2, 0x80
	s_addc_u32 s3, s3, 0
	s_add_u32 s4, s4, 0x80
	s_addc_u32 s5, s5, 0
	s_waitcnt lgkmcnt(0)
	v_mfma_f32_16x16x32_bf16 v[94:97], v[158:161], v[142:145], v[94:97]
	ds_read_b128 v[34:37], v107 offset:32768
	ds_read_b128 v[54:57], v109 offset:49152
	v_mfma_f32_16x16x32_bf16 v[90:93], v[182:185], v[142:145], v[90:93]
	v_mfma_f32_16x16x32_bf16 v[86:89], v[186:189], v[142:145], v[86:89]
	ds_read_b128 v[62:65], v109 offset:51200
	ds_read_b128 v[66:69], v109 offset:53248
	v_mfma_f32_16x16x32_bf16 v[82:85], v[206:209], v[142:145], v[82:85]
	v_mfma_f32_16x16x32_bf16 v[74:77], v[158:161], v[146:149], v[74:77]
	ds_read_b128 v[78:81], v109 offset:55296
	ds_read_b128 v[38:41], v107 offset:34816
	v_mfma_f32_16x16x32_bf16 v[70:73], v[182:185], v[146:149], v[70:73]
	v_mfma_f32_16x16x32_bf16 v[58:61], v[186:189], v[146:149], v[58:61]
	ds_read_b128 v[46:49], v107 offset:36864
	ds_read_b128 v[50:53], v107 offset:38912
	v_mfma_f32_16x16x32_bf16 v[42:45], v[206:209], v[146:149], v[42:45]
	v_mfma_f32_16x16x32_bf16 v[30:33], v[158:161], v[150:153], v[30:33]
	v_mfma_f32_16x16x32_bf16 v[26:29], v[182:185], v[150:153], v[26:29]
	v_mfma_f32_16x16x32_bf16 v[22:25], v[186:189], v[150:153], v[22:25]
	v_mfma_f32_16x16x32_bf16 v[18:21], v[206:209], v[150:153], v[18:21]
	v_mfma_f32_16x16x32_bf16 v[14:17], v[158:161], v[154:157], v[14:17]
	v_mfma_f32_16x16x32_bf16 v[10:13], v[182:185], v[154:157], v[10:13]
	v_mfma_f32_16x16x32_bf16 v[6:9], v[186:189], v[154:157], v[6:9]
	v_mfma_f32_16x16x32_bf16 v[2:5], v[206:209], v[154:157], v[2:5]
	s_waitcnt vmcnt(0) lgkmcnt(0)
	s_barrier
	v_mfma_f32_16x16x32_bf16 v[94:97], v[54:57], v[34:37], v[94:97]
	s_add_u32 m0, s6, 0xc000
	ds_read_b128 v[142:145], v106
	ds_read_b128 v[158:161], v108 offset:16384
	v_mfma_f32_16x16x32_bf16 v[90:93], v[62:65], v[34:37], v[90:93]
	global_load_lds_dwordx4 v102, s[4:5]
	v_mfma_f32_16x16x32_bf16 v[86:89], v[66:69], v[34:37], v[86:89]
	s_add_u32 m0, s6, 0xd000
	ds_read_b128 v[182:185], v108 offset:18432
	ds_read_b128 v[186:189], v108 offset:20480
	v_mfma_f32_16x16x32_bf16 v[82:85], v[78:81], v[34:37], v[82:85]
	global_load_lds_dwordx4 v103, s[4:5]
	v_mfma_f32_16x16x32_bf16 v[74:77], v[54:57], v[38:41], v[74:77]
	s_add_u32 m0, s6, 0xe000
	ds_read_b128 v[206:209], v108 offset:22528
	ds_read_b128 v[146:149], v106 offset:2048
	v_mfma_f32_16x16x32_bf16 v[70:73], v[62:65], v[38:41], v[70:73]
	global_load_lds_dwordx4 v104, s[4:5]
	v_mfma_f32_16x16x32_bf16 v[58:61], v[66:69], v[38:41], v[58:61]
	s_add_u32 m0, s6, 0xf000
	ds_read_b128 v[150:153], v106 offset:4096
	ds_read_b128 v[154:157], v106 offset:6144
	v_mfma_f32_16x16x32_bf16 v[42:45], v[78:81], v[38:41], v[42:45]
	global_load_lds_dwordx4 v105, s[4:5]
	v_mfma_f32_16x16x32_bf16 v[30:33], v[54:57], v[46:49], v[30:33]
	s_add_u32 m0, s6, 0x8000
	v_mfma_f32_16x16x32_bf16 v[26:29], v[62:65], v[46:49], v[26:29]
	global_load_lds_dwordx4 v98, s[2:3]
	v_mfma_f32_16x16x32_bf16 v[22:25], v[66:69], v[46:49], v[22:25]
	s_add_u32 m0, s6, 0x9000
	v_mfma_f32_16x16x32_bf16 v[18:21], v[78:81], v[46:49], v[18:21]
	global_load_lds_dwordx4 v99, s[2:3]
	v_mfma_f32_16x16x32_bf16 v[14:17], v[54:57], v[50:53], v[14:17]
	s_add_u32 m0, s6, 0xa000
	v_mfma_f32_16x16x32_bf16 v[10:13], v[62:65], v[50:53], v[10:13]
	global_load_lds_dwordx4 v100, s[2:3]
	v_mfma_f32_16x16x32_bf16 v[6:9], v[66:69], v[50:53], v[6:9]
	s_add_u32 m0, s6, 0xb000
	v_mfma_f32_16x16x32_bf16 v[2:5], v[78:81], v[50:53], v[2:5]
	global_load_lds_dwordx4 v101, s[2:3]
	s_add_u32 s2, s2, 0x80
	s_addc_u32 s3, s3, 0
	s_add_u32 s4, s4, 0x80
	s_addc_u32 s5, s5, 0
	s_waitcnt lgkmcnt(0)
	v_mfma_f32_16x16x32_bf16 v[94:97], v[158:161], v[142:145], v[94:97]
	ds_read_b128 v[34:37], v107
	ds_read_b128 v[54:57], v109 offset:16384
	v_mfma_f32_16x16x32_bf16 v[90:93], v[182:185], v[142:145], v[90:93]
	v_mfma_f32_16x16x32_bf16 v[86:89], v[186:189], v[142:145], v[86:89]
	ds_read_b128 v[62:65], v109 offset:18432
	ds_read_b128 v[66:69], v109 offset:20480
	v_mfma_f32_16x16x32_bf16 v[82:85], v[206:209], v[142:145], v[82:85]
	v_mfma_f32_16x16x32_bf16 v[74:77], v[158:161], v[146:149], v[74:77]
	ds_read_b128 v[78:81], v109 offset:22528
	ds_read_b128 v[38:41], v107 offset:2048
	v_mfma_f32_16x16x32_bf16 v[70:73], v[182:185], v[146:149], v[70:73]
	v_mfma_f32_16x16x32_bf16 v[58:61], v[186:189], v[146:149], v[58:61]
	ds_read_b128 v[46:49], v107 offset:4096
	ds_read_b128 v[50:53], v107 offset:6144
	v_mfma_f32_16x16x32_bf16 v[42:45], v[206:209], v[146:149], v[42:45]
	v_mfma_f32_16x16x32_bf16 v[30:33], v[158:161], v[150:153], v[30:33]
	v_mfma_f32_16x16x32_bf16 v[26:29], v[182:185], v[150:153], v[26:29]
	v_mfma_f32_16x16x32_bf16 v[22:25], v[186:189], v[150:153], v[22:25]
	v_mfma_f32_16x16x32_bf16 v[18:21], v[206:209], v[150:153], v[18:21]
	v_mfma_f32_16x16x32_bf16 v[14:17], v[158:161], v[154:157], v[14:17]
	v_mfma_f32_16x16x32_bf16 v[10:13], v[182:185], v[154:157], v[10:13]
	v_mfma_f32_16x16x32_bf16 v[6:9], v[186:189], v[154:157], v[6:9]
	v_mfma_f32_16x16x32_bf16 v[2:5], v[206:209], v[154:157], v[2:5]
	s_add_i32 s7, s7, -1
	s_waitcnt vmcnt(0) lgkmcnt(0)
	s_barrier
	s_cmp_lg_u32 s7, 0
	s_cbranch_scc1 .Lg7_loop
	v_mfma_f32_16x16x32_bf16 v[94:97], v[54:57], v[34:37], v[94:97]
	ds_read_b128 v[142:145], v106 offset:32768
	ds_read_b128 v[158:161], v108 offset:49152
	v_mfma_f32_16x16x32_bf16 v[90:93], v[62:65], v[34:37], v[90:93]
	v_mfma_f32_16x16x32_bf16 v[86:89], v[66:69], v[34:37], v[86:89]
	ds_read_b128 v[182:185], v108 offset:51200
	ds_read_b128 v[186:189], v108 offset:53248
	v_mfma_f32_16x16x32_bf16 v[82:85], v[78:81], v[34:37], v[82:85]
	v_mfma_f32_16x16x32_bf16 v[74:77], v[54:57], v[38:41], v[74:77]
	ds_read_b128 v[206:209], v108 offset:55296
	ds_read_b128 v[146:149], v106 offset:34816
	v_mfma_f32_16x16x32_bf16 v[70:73], v[62:65], v[38:41], v[70:73]
	v_mfma_f32_16x16x32_bf16 v[58:61], v[66:69], v[38:41], v[58:61]
	ds_read_b128 v[150:153], v106 offset:36864
	ds_read_b128 v[154:157], v106 offset:38912
	v_mfma_f32_16x16x32_bf16 v[42:45], v[78:81], v[38:41], v[42:45]
	v_mfma_f32_16x16x32_bf16 v[30:33], v[54:57], v[46:49], v[30:33]
	v_mfma_f32_16x16x32_bf16 v[26:29], v[62:65], v[46:49], v[26:29]
	v_mfma_f32_16x16x32_bf16 v[22:25], v[66:69], v[46:49], v[22:25]
	v_mfma_f32_16x16x32_bf16 v[18:21], v[78:81], v[46:49], v[18:21]
	v_mfma_f32_16x16x32_bf16 v[14:17], v[54:57], v[50:53], v[14:17]
	v_mfma_f32_16x16x32_bf16 v[10:13], v[62:65], v[50:53], v[10:13]
	v_mfma_f32_16x16x32_bf16 v[6:9], v[66:69], v[50:53], v[6:9]
	v_mfma_f32_16x16x32_bf16 v[2:5], v[78:81], v[50:53], v[2:5]
	s_waitcnt lgkmcnt(0)
	v_mfma_f32_16x16x32_bf16 v[94:97], v[158:161], v[142:145], v[94:97]
	ds_read_b128 v[34:37], v107 offset:32768
	ds_read_b128 v[54:57], v109 offset:49152
	v_mfma_f32_16x16x32_bf16 v[90:93], v[182:185], v[142:145], v[90:93]
	v_mfma_f32_16x16x32_bf16 v[86:89], v[186:189], v[142:145], v[86:89]
	ds_read_b128 v[62:65], v109 offset:51200
	ds_read_b128 v[66:69], v109 offset:53248
	v_mfma_f32_16x16x32_bf16 v[82:85], v[206:209], v[142:145], v[82:85]
	v_mfma_f32_16x16x32_bf16 v[74:77], v[158:161], v[146:149], v[74:77]
	ds_read_b128 v[78:81], v109 offset:55296
	ds_read_b128 v[38:41], v107 offset:34816
	v_mfma_f32_16x16x32_bf16 v[70:73], v[182:185], v[146:149], v[70:73]
	v_mfma_f32_16x16x32_bf16 v[58:61], v[186:189], v[146:149], v[58:61]
	ds_read_b128 v[46:49], v107 offset:36864
	ds_read_b128 v[50:53], v107 offset:38912
	v_mfma_f32_16x16x32_bf16 v[42:45], v[206:209], v[146:149], v[42:45]
	v_mfma_f32_16x16x32_bf16 v[30:33], v[158:161], v[150:153], v[30:33]
	v_mfma_f32_16x16x32_bf16 v[26:29], v[182:185], v[150:153], v[26:29]
	v_mfma_f32_16x16x32_bf16 v[22:25], v[186:189], v[150:153], v[22:25]
	v_mfma_f32_16x16x32_bf16 v[18:21], v[206:209], v[150:153], v[18:21]
	v_mfma_f32_16x16x32_bf16 v[14:17], v[158:161], v[154:157], v[14:17]
	v_mfma_f32_16x16x32_bf16 v[10:13], v[182:185], v[154:157], v[10:13]
	v_mfma_f32_16x16x32_bf16 v[6:9], v[186:189], v[154:157], v[6:9]
	v_mfma_f32_16x16x32_bf16 v[2:5], v[206:209], v[154:157], v[2:5]
	s_waitcnt lgkmcnt(0)
	s_barrier
	v_mfma_f32_16x16x32_bf16 v[94:97], v[54:57], v[34:37], v[94:97]
	v_mfma_f32_16x16x32_bf16 v[90:93], v[62:65], v[34:37], v[90:93]
	v_mfma_f32_16x16x32_bf16 v[86:89], v[66:69], v[34:37], v[86:89]
	v_mfma_f32_16x16x32_bf16 v[82:85], v[78:81], v[34:37], v[82:85]
	v_mfma_f32_16x16x32_bf16 v[74:77], v[54:57], v[38:41], v[74:77]
	v_mfma_f32_16x16x32_bf16 v[70:73], v[62:65], v[38:41], v[70:73]
	v_mfma_f32_16x16x32_bf16 v[58:61], v[66:69], v[38:41], v[58:61]
	v_mfma_f32_16x16x32_bf16 v[42:45], v[78:81], v[38:41], v[42:45]
	v_mfma_f32_16x16x32_bf16 v[30:33], v[54:57], v[46:49], v[30:33]
	v_mfma_f32_16x16x32_bf16 v[26:29], v[62:65], v[46:49], v[26:29]
	v_mfma_f32_16x16x32_bf16 v[22:25], v[66:69], v[46:49], v[22:25]
	v_mfma_f32_16x16x32_bf16 v[18:21], v[78:81], v[46:49], v[18:21]
	v_mfma_f32_16x16x32_bf16 v[14:17], v[54:57], v[50:53], v[14:17]
	v_mfma_f32_16x16x32_bf16 v[10:13], v[62:65], v[50:53], v[10:13]
	v_mfma_f32_16x16x32_bf16 v[6:9], v[66:69], v[50:53], v[6:9]
	v_mfma_f32_16x16x32_bf16 v[2:5], v[78:81], v[50:53], v[2:5]
	s_nop 7
	s_nop 2
	s_mov_b32 s21, 0x33000
	s_branch .LBB0_81

.LBB0_92:
	v_lshrrev_b32_e32 v2, 6, v177
	v_lshlrev_b32_e32 v3, 4, v177
	v_bfe_u32 v0, v177, 3, 3
	v_and_b32_e32 v3, 0x70, v3
	v_and_b32_e32 v4, 8, v2
	v_or3_b32 v185, v3, v4, v0
	v_ashrrev_i32_e32 v0, 7, v177
	v_bfi_b32 v104, -8, v0, v2
	v_mov_b64_e32 v[2:3], s[48:49]
	s_mov_b32 s2, 0x24000
	v_mov_b32_e32 v206, v163
	v_mov_b32_e32 v207, v163
	v_mul_u32_u24_e32 v182, 0x24000, v185
	v_mov_b32_e32 v183, v1
	v_mad_i64_i32 v[4:5], s[2:3], v104, s2, v[2:3]
	v_mov_b32_e32 v2, v163
	v_lshl_add_u64 v[98:99], s[82:83], 0, v[182:183]
	s_movk_i32 s4, 0x480
	v_ashrrev_i32_e32 v3, 3, v2
	v_lshlrev_b32_e32 v0, 4, v2
	v_mad_i64_i32 v[6:7], s[2:3], v3, s4, v[98:99]
	v_and_b32_e32 v0, 0x70, v0
	v_mad_i64_i32 v[4:5], s[2:3], v3, s4, v[4:5]
	v_lshl_add_u64 v[100:101], v[6:7], 0, v[0:1]
	s_mov_b32 s2, 0x9000
	v_lshl_add_u64 v[102:103], v[4:5], 0, v[0:1]
	v_and_b32_e32 v66, 7, v163
	v_bfe_u32 v67, v163, 4, 3
	v_xor_b32_e32 v67, v67, v66
	v_sub_u32_e32 v67, v67, v66
	v_lshlrev_b32_e32 v67, 4, v67
	v_lshrrev_b32_e32 v68, 6, v163
	v_lshlrev_b32_e32 v68, 10, v68
	v_readfirstlane_b32 s2, v100
	v_readfirstlane_b32 s3, v101
	v_readfirstlane_b32 s4, v102
	v_readfirstlane_b32 s5, v103
	v_readfirstlane_b32 s6, v68
	s_nop 3
	v_subrev_u32_e32 v105, s2, v100
	v_subrev_u32_e32 v109, s4, v102
	v_add_u32_e32 v105, v105, v67
	v_add_u32_e32 v109, v109, v67
	v_add_u32_e32 v106, 0x9000, v105
	v_add_u32_e32 v130, 0x9000, v109
	v_add_u32_e32 v107, 0x12000, v105
	v_add_u32_e32 v122, 0x12000, v109
	v_add_u32_e32 v108, 0x1b000, v105
	v_add_u32_e32 v123, 0x1b000, v109
	v_lshlrev_b32_e32 v66, 3, v163
	v_lshlrev_b32_e32 v67, 7, v163
	v_and_b32_e32 v68, 0x2000, v67
	v_and_b32_e32 v67, 0x780, v67
	v_and_b32_e32 v125, 64, v66
	v_xor_b32_e32 v66, v66, v163
	v_and_b32_e32 v66, 48, v66
	v_or3_b32 v66, v67, v125, v66
	v_lshlrev_b32_e32 v67, 6, v163
	v_and_b32_e32 v67, 0xffffe000, v67
	v_or_b32_e32 v126, v66, v68
	v_or_b32_e32 v124, v66, v67
	v_xor_b32_e32 v125, 64, v124
	v_xor_b32_e32 v127, 64, v126
	s_add_u32 m0, s6, 0x4000
	s_nop 0
	global_load_lds_dwordx4 v109, s[4:5]
	s_add_u32 m0, s6, 0x5000
	s_nop 0
	global_load_lds_dwordx4 v130, s[4:5]
	s_add_u32 m0, s6, 0x6000
	s_nop 0
	global_load_lds_dwordx4 v122, s[4:5]
	s_add_u32 m0, s6, 0x7000
	s_nop 0
	global_load_lds_dwordx4 v123, s[4:5]
	s_mov_b32 m0, s6
	s_nop 0
	global_load_lds_dwordx4 v105, s[2:3]
	s_add_u32 m0, s6, 0x1000
	s_nop 0
	global_load_lds_dwordx4 v106, s[2:3]
	s_add_u32 m0, s6, 0x2000
	s_nop 0
	global_load_lds_dwordx4 v107, s[2:3]
	s_add_u32 m0, s6, 0x3000
	s_nop 0
	global_load_lds_dwordx4 v108, s[2:3]
	s_add_u32 s2, s2, 0x80
	s_addc_u32 s3, s3, 0
	s_add_u32 s4, s4, 0x80
	s_addc_u32 s5, s5, 0
	s_waitcnt vmcnt(0)
	s_barrier
	ds_read_b128 v[34:37], v126 offset:16384
	ds_read_b128 v[42:45], v126 offset:18432
	ds_read_b128 v[50:53], v126 offset:20480
	ds_read_b128 v[58:61], v126 offset:22528
	ds_read_b128 v[110:113], v124
	ds_read_b128 v[114:117], v124 offset:2048
	s_add_u32 m0, s6, 0xc000
	s_waitcnt lgkmcnt(1)
	v_mfma_f32_16x16x32_bf16 v[94:97], v[34:37], v[110:113], 0
	v_mfma_f32_16x16x32_bf16 v[86:89], v[42:45], v[110:113], 0
	v_mfma_f32_16x16x32_bf16 v[78:81], v[50:53], v[110:113], 0
	v_mfma_f32_16x16x32_bf16 v[70:73], v[58:61], v[110:113], 0
	ds_read_b128 v[118:121], v124 offset:4096
	ds_read_b128 v[66:69], v127 offset:16384
	ds_read_b128 v[74:77], v127 offset:18432
	ds_read_b128 v[82:85], v127 offset:20480
	ds_read_b128 v[90:93], v127 offset:22528
	global_load_lds_dwordx4 v109, s[4:5]
	s_add_u32 m0, s6, 0xd000
	s_waitcnt lgkmcnt(5)
	v_mfma_f32_16x16x32_bf16 v[62:65], v[34:37], v[114:117], 0
	v_mfma_f32_16x16x32_bf16 v[54:57], v[42:45], v[114:117], 0
	v_mfma_f32_16x16x32_bf16 v[46:49], v[50:53], v[114:117], 0
	v_mfma_f32_16x16x32_bf16 v[38:41], v[58:61], v[114:117], 0
	ds_read_b128 v[110:113], v124 offset:6144
	global_load_lds_dwordx4 v130, s[4:5]
	s_add_u32 m0, s6, 0xe000
	s_waitcnt lgkmcnt(5)
	v_mfma_f32_16x16x32_bf16 v[30:33], v[34:37], v[118:121], 0
	v_mfma_f32_16x16x32_bf16 v[26:29], v[42:45], v[118:121], 0
	v_mfma_f32_16x16x32_bf16 v[22:25], v[50:53], v[118:121], 0
	v_mfma_f32_16x16x32_bf16 v[18:21], v[58:61], v[118:121], 0
	ds_read_b128 v[114:117], v125
	global_load_lds_dwordx4 v122, s[4:5]
	s_add_u32 m0, s6, 0xf000
	s_waitcnt lgkmcnt(1)
	v_mfma_f32_16x16x32_bf16 v[14:17], v[34:37], v[110:113], 0
	v_mfma_f32_16x16x32_bf16 v[10:13], v[42:45], v[110:113], 0
	v_mfma_f32_16x16x32_bf16 v[6:9], v[50:53], v[110:113], 0
	v_mfma_f32_16x16x32_bf16 v[2:5], v[58:61], v[110:113], 0
	ds_read_b128 v[118:121], v125 offset:2048
	global_load_lds_dwordx4 v123, s[4:5]
	s_add_u32 m0, s6, 0x8000
	s_waitcnt lgkmcnt(1)
	v_mfma_f32_16x16x32_bf16 v[94:97], v[66:69], v[114:117], v[94:97]
	v_mfma_f32_16x16x32_bf16 v[86:89], v[74:77], v[114:117], v[86:89]
	v_mfma_f32_16x16x32_bf16 v[78:81], v[82:85], v[114:117], v[78:81]
	v_mfma_f32_16x16x32_bf16 v[70:73], v[90:93], v[114:117], v[70:73]
	ds_read_b128 v[110:113], v125 offset:4096
	global_load_lds_dwordx4 v105, s[2:3]
	s_add_u32 m0, s6, 0x9000
	s_waitcnt lgkmcnt(1)
	v_mfma_f32_16x16x32_bf16 v[62:65], v[66:69], v[118:121], v[62:65]
	v_mfma_f32_16x16x32_bf16 v[54:57], v[74:77], v[118:121], v[54:57]
	v_mfma_f32_16x16x32_bf16 v[46:49], v[82:85], v[118:121], v[46:49]
	v_mfma_f32_16x16x32_bf16 v[38:41], v[90:93], v[118:121], v[38:41]
	ds_read_b128 v[114:117], v125 offset:6144
	global_load_lds_dwordx4 v106, s[2:3]
	s_add_u32 m0, s6, 0xa000
	s_waitcnt lgkmcnt(1)
	v_mfma_f32_16x16x32_bf16 v[30:33], v[66:69], v[110:113], v[30:33]
	v_mfma_f32_16x16x32_bf16 v[26:29], v[74:77], v[110:113], v[26:29]
	v_mfma_f32_16x16x32_bf16 v[22:25], v[82:85], v[110:113], v[22:25]
	v_mfma_f32_16x16x32_bf16 v[18:21], v[90:93], v[110:113], v[18:21]
	global_load_lds_dwordx4 v107, s[2:3]
	s_add_u32 m0, s6, 0xb000
	s_waitcnt lgkmcnt(0)
	v_mfma_f32_16x16x32_bf16 v[14:17], v[66:69], v[114:117], v[14:17]
	v_mfma_f32_16x16x32_bf16 v[10:13], v[74:77], v[114:117], v[10:13]
	v_mfma_f32_16x16x32_bf16 v[6:9], v[82:85], v[114:117], v[6:9]
	v_mfma_f32_16x16x32_bf16 v[2:5], v[90:93], v[114:117], v[2:5]
	global_load_lds_dwordx4 v108, s[2:3]
	s_add_u32 s2, s2, 0x80
	s_addc_u32 s3, s3, 0
	s_add_u32 s4, s4, 0x80
	s_addc_u32 s5, s5, 0
	s_waitcnt vmcnt(0) lgkmcnt(0)
	s_barrier
	ds_read_b128 v[34:37], v126 offset:49152
	ds_read_b128 v[42:45], v126 offset:51200
	ds_read_b128 v[50:53], v126 offset:53248
	ds_read_b128 v[58:61], v126 offset:55296
	ds_read_b128 v[110:113], v124 offset:32768
	ds_read_b128 v[114:117], v124 offset:34816
	s_add_u32 m0, s6, 0x4000
	s_waitcnt lgkmcnt(1)
	v_mfma_f32_16x16x32_bf16 v[94:97], v[34:37], v[110:113], v[94:97]
	v_mfma_f32_16x16x32_bf16 v[86:89], v[42:45], v[110:113], v[86:89]
	v_mfma_f32_16x16x32_bf16 v[78:81], v[50:53], v[110:113], v[78:81]
	v_mfma_f32_16x16x32_bf16 v[70:73], v[58:61], v[110:113], v[70:73]
	ds_read_b128 v[118:121], v124 offset:36864
	ds_read_b128 v[66:69], v127 offset:49152
	ds_read_b128 v[74:77], v127 offset:51200
	ds_read_b128 v[82:85], v127 offset:53248
	ds_read_b128 v[90:93], v127 offset:55296
	global_load_lds_dwordx4 v109, s[4:5]
	s_add_u32 m0, s6, 0x5000
	s_waitcnt lgkmcnt(5)
	v_mfma_f32_16x16x32_bf16 v[62:65], v[34:37], v[114:117], v[62:65]
	v_mfma_f32_16x16x32_bf16 v[54:57], v[42:45], v[114:117], v[54:57]
	v_mfma_f32_16x16x32_bf16 v[46:49], v[50:53], v[114:117], v[46:49]
	v_mfma_f32_16x16x32_bf16 v[38:41], v[58:61], v[114:117], v[38:41]
	ds_read_b128 v[110:113], v124 offset:38912
	global_load_lds_dwordx4 v130, s[4:5]
	s_add_u32 m0, s6, 0x6000
	s_waitcnt lgkmcnt(5)
	v_mfma_f32_16x16x32_bf16 v[30:33], v[34:37], v[118:121], v[30:33]
	v_mfma_f32_16x16x32_bf16 v[26:29], v[42:45], v[118:121], v[26:29]
	v_mfma_f32_16x16x32_bf16 v[22:25], v[50:53], v[118:121], v[22:25]
	v_mfma_f32_16x16x32_bf16 v[18:21], v[58:61], v[118:121], v[18:21]
	ds_read_b128 v[114:117], v125 offset:32768
	global_load_lds_dwordx4 v122, s[4:5]
	s_add_u32 m0, s6, 0x7000
	s_waitcnt lgkmcnt(1)
	v_mfma_f32_16x16x32_bf16 v[14:17], v[34:37], v[110:113], v[14:17]
	v_mfma_f32_16x16x32_bf16 v[10:13], v[42:45], v[110:113], v[10:13]
	v_mfma_f32_16x16x32_bf16 v[6:9], v[50:53], v[110:113], v[6:9]
	v_mfma_f32_16x16x32_bf16 v[2:5], v[58:61], v[110:113], v[2:5]
	ds_read_b128 v[118:121], v125 offset:34816
	global_load_lds_dwordx4 v123, s[4:5]
	s_mov_b32 m0, s6
	s_waitcnt lgkmcnt(1)
	v_mfma_f32_16x16x32_bf16 v[94:97], v[66:69], v[114:117], v[94:97]
	v_mfma_f32_16x16x32_bf16 v[86:89], v[74:77], v[114:117], v[86:89]
	v_mfma_f32_16x16x32_bf16 v[78:81], v[82:85], v[114:117], v[78:81]
	v_mfma_f32_16x16x32_bf16 v[70:73], v[90:93], v[114:117], v[70:73]
	ds_read_b128 v[110:113], v125 offset:36864
	global_load_lds_dwordx4 v105, s[2:3]
	s_add_u32 m0, s6, 0x1000
	s_waitcnt lgkmcnt(1)
	v_mfma_f32_16x16x32_bf16 v[62:65], v[66:69], v[118:121], v[62:65]
	v_mfma_f32_16x16x32_bf16 v[54:57], v[74:77], v[118:121], v[54:57]
	v_mfma_f32_16x16x32_bf16 v[46:49], v[82:85], v[118:121], v[46:49]
	v_mfma_f32_16x16x32_bf16 v[38:41], v[90:93], v[118:121], v[38:41]
	ds_read_b128 v[114:117], v125 offset:38912
	global_load_lds_dwordx4 v106, s[2:3]
	s_add_u32 m0, s6, 0x2000
	s_waitcnt lgkmcnt(1)
	v_mfma_f32_16x16x32_bf16 v[30:33], v[66:69], v[110:113], v[30:33]
	v_mfma_f32_16x16x32_bf16 v[26:29], v[74:77], v[110:113], v[26:29]
	v_mfma_f32_16x16x32_bf16 v[22:25], v[82:85], v[110:113], v[22:25]
	v_mfma_f32_16x16x32_bf16 v[18:21], v[90:93], v[110:113], v[18:21]
	global_load_lds_dwordx4 v107, s[2:3]
	s_add_u32 m0, s6, 0x3000
	s_waitcnt lgkmcnt(0)
	v_mfma_f32_16x16x32_bf16 v[14:17], v[66:69], v[114:117], v[14:17]
	v_mfma_f32_16x16x32_bf16 v[10:13], v[74:77], v[114:117], v[10:13]
	v_mfma_f32_16x16x32_bf16 v[6:9], v[82:85], v[114:117], v[6:9]
	v_mfma_f32_16x16x32_bf16 v[2:5], v[90:93], v[114:117], v[2:5]
	global_load_lds_dwordx4 v108, s[2:3]
	s_add_u32 s2, s2, 0x80
	s_addc_u32 s3, s3, 0
	s_add_u32 s4, s4, 0x80
	s_addc_u32 s5, s5, 0
	s_waitcnt vmcnt(0) lgkmcnt(0)
	s_barrier
	s_movk_i32 s7, 2
.Lm1_loop:
	ds_read_b128 v[34:37], v126 offset:16384
	ds_read_b128 v[42:45], v126 offset:18432
	ds_read_b128 v[50:53], v126 offset:20480
	ds_read_b128 v[58:61], v126 offset:22528
	ds_read_b128 v[110:113], v124
	ds_read_b128 v[114:117], v124 offset:2048
	s_add_u32 m0, s6, 0xc000
	s_waitcnt lgkmcnt(1)
	v_mfma_f32_16x16x32_bf16 v[94:97], v[34:37], v[110:113], v[94:97]
	v_mfma_f32_16x16x32_bf16 v[86:89], v[42:45], v[110:113], v[86:89]
	v_mfma_f32_16x16x32_bf16 v[78:81], v[50:53], v[110:113], v[78:81]
	v_mfma_f32_16x16x32_bf16 v[70:73], v[58:61], v[110:113], v[70:73]
	ds_read_b128 v[118:121], v124 offset:4096
	ds_read_b128 v[66:69], v127 offset:16384
	ds_read_b128 v[74:77], v127 offset:18432
	ds_read_b128 v[82:85], v127 offset:20480
	ds_read_b128 v[90:93], v127 offset:22528
	global_load_lds_dwordx4 v109, s[4:5]
	s_add_u32 m0, s6, 0xd000
	s_waitcnt lgkmcnt(5)
	v_mfma_f32_16x16x32_bf16 v[62:65], v[34:37], v[114:117], v[62:65]
	v_mfma_f32_16x16x32_bf16 v[54:57], v[42:45], v[114:117], v[54:57]
	v_mfma_f32_16x16x32_bf16 v[46:49], v[50:53], v[114:117], v[46:49]
	v_mfma_f32_16x16x32_bf16 v[38:41], v[58:61], v[114:117], v[38:41]
	ds_read_b128 v[110:113], v124 offset:6144
	global_load_lds_dwordx4 v130, s[4:5]
	s_add_u32 m0, s6, 0xe000
	s_waitcnt lgkmcnt(5)
	v_mfma_f32_16x16x32_bf16 v[30:33], v[34:37], v[118:121], v[30:33]
	v_mfma_f32_16x16x32_bf16 v[26:29], v[42:45], v[118:121], v[26:29]
	v_mfma_f32_16x16x32_bf16 v[22:25], v[50:53], v[118:121], v[22:25]
	v_mfma_f32_16x16x32_bf16 v[18:21], v[58:61], v[118:121], v[18:21]
	ds_read_b128 v[114:117], v125
	global_load_lds_dwordx4 v122, s[4:5]
	s_add_u32 m0, s6, 0xf000
	s_waitcnt lgkmcnt(1)
	v_mfma_f32_16x16x32_bf16 v[14:17], v[34:37], v[110:113], v[14:17]
	v_mfma_f32_16x16x32_bf16 v[10:13], v[42:45], v[110:113], v[10:13]
	v_mfma_f32_16x16x32_bf16 v[6:9], v[50:53], v[110:113], v[6:9]
	v_mfma_f32_16x16x32_bf16 v[2:5], v[58:61], v[110:113], v[2:5]
	ds_read_b128 v[118:121], v125 offset:2048
	global_load_lds_dwordx4 v123, s[4:5]
	s_add_u32 m0, s6, 0x8000
	s_waitcnt lgkmcnt(1)
	v_mfma_f32_16x16x32_bf16 v[94:97], v[66:69], v[114:117], v[94:97]
	v_mfma_f32_16x16x32_bf16 v[86:89], v[74:77], v[114:117], v[86:89]
	v_mfma_f32_16x16x32_bf16 v[78:81], v[82:85], v[114:117], v[78:81]
	v_mfma_f32_16x16x32_bf16 v[70:73], v[90:93], v[114:117], v[70:73]
	ds_read_b128 v[110:113], v125 offset:4096
	global_load_lds_dwordx4 v105, s[2:3]
	s_add_u32 m0, s6, 0x9000
	s_waitcnt lgkmcnt(1)
	v_mfma_f32_16x16x32_bf16 v[62:65], v[66:69], v[118:121], v[62:65]
	v_mfma_f32_16x16x32_bf16 v[54:57], v[74:77], v[118:121], v[54:57]
	v_mfma_f32_16x16x32_bf16 v[46:49], v[82:85], v[118:121], v[46:49]
	v_mfma_f32_16x16x32_bf16 v[38:41], v[90:93], v[118:121], v[38:41]
	ds_read_b128 v[114:117], v125 offset:6144
	global_load_lds_dwordx4 v106, s[2:3]
	s_add_u32 m0, s6, 0xa000
	s_waitcnt lgkmcnt(1)
	v_mfma_f32_16x16x32_bf16 v[30:33], v[66:69], v[110:113], v[30:33]
	v_mfma_f32_16x16x32_bf16 v[26:29], v[74:77], v[110:113], v[26:29]
	v_mfma_f32_16x16x32_bf16 v[22:25], v[82:85], v[110:113], v[22:25]
	v_mfma_f32_16x16x32_bf16 v[18:21], v[90:93], v[110:113], v[18:21]
	global_load_lds_dwordx4 v107, s[2:3]
	s_add_u32 m0, s6, 0xb000
	s_waitcnt lgkmcnt(0)
	v_mfma_f32_16x16x32_bf16 v[14:17], v[66:69], v[114:117], v[14:17]
	v_mfma_f32_16x16x32_bf16 v[10:13], v[74:77], v[114:117], v[10:13]
	v_mfma_f32_16x16x32_bf16 v[6:9], v[82:85], v[114:117], v[6:9]
	v_mfma_f32_16x16x32_bf16 v[2:5], v[90:93], v[114:117], v[2:5]
	global_load_lds_dwordx4 v108, s[2:3]
	s_add_u32 s2, s2, 0x80
	s_addc_u32 s3, s3, 0
	s_add_u32 s4, s4, 0x80
	s_addc_u32 s5, s5, 0
	s_waitcnt vmcnt(0) lgkmcnt(0)
	s_barrier
	ds_read_b128 v[34:37], v126 offset:49152
	ds_read_b128 v[42:45], v126 offset:51200
	ds_read_b128 v[50:53], v126 offset:53248
	ds_read_b128 v[58:61], v126 offset:55296
	ds_read_b128 v[110:113], v124 offset:32768
	ds_read_b128 v[114:117], v124 offset:34816
	s_add_u32 m0, s6, 0x4000
	s_waitcnt lgkmcnt(1)
	v_mfma_f32_16x16x32_bf16 v[94:97], v[34:37], v[110:113], v[94:97]
	v_mfma_f32_16x16x32_bf16 v[86:89], v[42:45], v[110:113], v[86:89]
	v_mfma_f32_16x16x32_bf16 v[78:81], v[50:53], v[110:113], v[78:81]
	v_mfma_f32_16x16x32_bf16 v[70:73], v[58:61], v[110:113], v[70:73]
	ds_read_b128 v[118:121], v124 offset:36864
	ds_read_b128 v[66:69], v127 offset:49152
	ds_read_b128 v[74:77], v127 offset:51200
	ds_read_b128 v[82:85], v127 offset:53248
	ds_read_b128 v[90:93], v127 offset:55296
	global_load_lds_dwordx4 v109, s[4:5]
	s_add_u32 m0, s6, 0x5000
	s_waitcnt lgkmcnt(5)
	v_mfma_f32_16x16x32_bf16 v[62:65], v[34:37], v[114:117], v[62:65]
	v_mfma_f32_16x16x32_bf16 v[54:57], v[42:45], v[114:117], v[54:57]
	v_mfma_f32_16x16x32_bf16 v[46:49], v[50:53], v[114:117], v[46:49]
	v_mfma_f32_16x16x32_bf16 v[38:41], v[58:61], v[114:117], v[38:41]
	ds_read_b128 v[110:113], v124 offset:38912
	global_load_lds_dwordx4 v130, s[4:5]
	s_add_u32 m0, s6, 0x6000
	s_waitcnt lgkmcnt(5)
	v_mfma_f32_16x16x32_bf16 v[30:33], v[34:37], v[118:121], v[30:33]
	v_mfma_f32_16x16x32_bf16 v[26:29], v[42:45], v[118:121], v[26:29]
	v_mfma_f32_16x16x32_bf16 v[22:25], v[50:53], v[118:121], v[22:25]
	v_mfma_f32_16x16x32_bf16 v[18:21], v[58:61], v[118:121], v[18:21]
	ds_read_b128 v[114:117], v125 offset:32768
	global_load_lds_dwordx4 v122, s[4:5]
	s_add_u32 m0, s6, 0x7000
	s_waitcnt lgkmcnt(1)
	v_mfma_f32_16x16x32_bf16 v[14:17], v[34:37], v[110:113], v[14:17]
	v_mfma_f32_16x16x32_bf16 v[10:13], v[42:45], v[110:113], v[10:13]
	v_mfma_f32_16x16x32_bf16 v[6:9], v[50:53], v[110:113], v[6:9]
	v_mfma_f32_16x16x32_bf16 v[2:5], v[58:61], v[110:113], v[2:5]
	ds_read_b128 v[118:121], v125 offset:34816
	global_load_lds_dwordx4 v123, s[4:5]
	s_mov_b32 m0, s6
	s_waitcnt lgkmcnt(1)
	v_mfma_f32_16x16x32_bf16 v[94:97], v[66:69], v[114:117], v[94:97]
	v_mfma_f32_16x16x32_bf16 v[86:89], v[74:77], v[114:117], v[86:89]
	v_mfma_f32_16x16x32_bf16 v[78:81], v[82:85], v[114:117], v[78:81]
	v_mfma_f32_16x16x32_bf16 v[70:73], v[90:93], v[114:117], v[70:73]
	ds_read_b128 v[110:113], v125 offset:36864
	global_load_lds_dwordx4 v105, s[2:3]
	s_add_u32 m0, s6, 0x1000
	s_waitcnt lgkmcnt(1)
	v_mfma_f32_16x16x32_bf16 v[62:65], v[66:69], v[118:121], v[62:65]
	v_mfma_f32_16x16x32_bf16 v[54:57], v[74:77], v[118:121], v[54:57]
	v_mfma_f32_16x16x32_bf16 v[46:49], v[82:85], v[118:121], v[46:49]
	v_mfma_f32_16x16x32_bf16 v[38:41], v[90:93], v[118:121], v[38:41]
	ds_read_b128 v[114:117], v125 offset:38912
	global_load_lds_dwordx4 v106, s[2:3]
	s_add_u32 m0, s6, 0x2000
	s_waitcnt lgkmcnt(1)
	v_mfma_f32_16x16x32_bf16 v[30:33], v[66:69], v[110:113], v[30:33]
	v_mfma_f32_16x16x32_bf16 v[26:29], v[74:77], v[110:113], v[26:29]
	v_mfma_f32_16x16x32_bf16 v[22:25], v[82:85], v[110:113], v[22:25]
	v_mfma_f32_16x16x32_bf16 v[18:21], v[90:93], v[110:113], v[18:21]
	global_load_lds_dwordx4 v107, s[2:3]
	s_add_u32 m0, s6, 0x3000
	s_waitcnt lgkmcnt(0)
	v_mfma_f32_16x16x32_bf16 v[14:17], v[66:69], v[114:117], v[14:17]
	v_mfma_f32_16x16x32_bf16 v[10:13], v[74:77], v[114:117], v[10:13]
	v_mfma_f32_16x16x32_bf16 v[6:9], v[82:85], v[114:117], v[6:9]
	v_mfma_f32_16x16x32_bf16 v[2:5], v[90:93], v[114:117], v[2:5]
	global_load_lds_dwordx4 v108, s[2:3]
	s_add_u32 s2, s2, 0x80
	s_addc_u32 s3, s3, 0
	s_add_u32 s4, s4, 0x80
	s_addc_u32 s5, s5, 0
	s_add_i32 s7, s7, -1
	s_waitcnt vmcnt(0) lgkmcnt(0)
	s_barrier
	s_cmp_lg_u32 s7, 0
	s_cbranch_scc1 .Lm1_loop
	ds_read_b128 v[34:37], v126 offset:16384
	ds_read_b128 v[42:45], v126 offset:18432
	ds_read_b128 v[50:53], v126 offset:20480
	ds_read_b128 v[58:61], v126 offset:22528
	ds_read_b128 v[110:113], v124
	ds_read_b128 v[114:117], v124 offset:2048
	s_add_u32 m0, s6, 0xc000
	s_waitcnt lgkmcnt(1)
	v_mfma_f32_16x16x32_bf16 v[94:97], v[34:37], v[110:113], v[94:97]
	v_mfma_f32_16x16x32_bf16 v[86:89], v[42:45], v[110:113], v[86:89]
	v_mfma_f32_16x16x32_bf16 v[78:81], v[50:53], v[110:113], v[78:81]
	v_mfma_f32_16x16x32_bf16 v[70:73], v[58:61], v[110:113], v[70:73]
	ds_read_b128 v[118:121], v124 offset:4096
	ds_read_b128 v[66:69], v127 offset:16384
	ds_read_b128 v[74:77], v127 offset:18432
	ds_read_b128 v[82:85], v127 offset:20480
	ds_read_b128 v[90:93], v127 offset:22528
	global_load_lds_dwordx4 v109, s[4:5]
	s_add_u32 m0, s6, 0xd000
	s_waitcnt lgkmcnt(5)
	v_mfma_f32_16x16x32_bf16 v[62:65], v[34:37], v[114:117], v[62:65]
	v_mfma_f32_16x16x32_bf16 v[54:57], v[42:45], v[114:117], v[54:57]
	v_mfma_f32_16x16x32_bf16 v[46:49], v[50:53], v[114:117], v[46:49]
	v_mfma_f32_16x16x32_bf16 v[38:41], v[58:61], v[114:117], v[38:41]
	ds_read_b128 v[110:113], v124 offset:6144
	global_load_lds_dwordx4 v130, s[4:5]
	s_add_u32 m0, s6, 0xe000
	s_waitcnt lgkmcnt(5)
	v_mfma_f32_16x16x32_bf16 v[30:33], v[34:37], v[118:121], v[30:33]
	v_mfma_f32_16x16x32_bf16 v[26:29], v[42:45], v[118:121], v[26:29]
	v_mfma_f32_16x16x32_bf16 v[22:25], v[50:53], v[118:121], v[22:25]
	v_mfma_f32_16x16x32_bf16 v[18:21], v[58:61], v[118:121], v[18:21]
	ds_read_b128 v[114:117], v125
	global_load_lds_dwordx4 v122, s[4:5]
	s_add_u32 m0, s6, 0xf000
	s_waitcnt lgkmcnt(1)
	v_mfma_f32_16x16x32_bf16 v[14:17], v[34:37], v[110:113], v[14:17]
	v_mfma_f32_16x16x32_bf16 v[10:13], v[42:45], v[110:113], v[10:13]
	v_mfma_f32_16x16x32_bf16 v[6:9], v[50:53], v[110:113], v[6:9]
	v_mfma_f32_16x16x32_bf16 v[2:5], v[58:61], v[110:113], v[2:5]
	ds_read_b128 v[118:121], v125 offset:2048
	global_load_lds_dwordx4 v123, s[4:5]
	s_add_u32 m0, s6, 0x8000
	s_waitcnt lgkmcnt(1)
	v_mfma_f32_16x16x32_bf16 v[94:97], v[66:69], v[114:117], v[94:97]
	v_mfma_f32_16x16x32_bf16 v[86:89], v[74:77], v[114:117], v[86:89]
	v_mfma_f32_16x16x32_bf16 v[78:81], v[82:85], v[114:117], v[78:81]
	v_mfma_f32_16x16x32_bf16 v[70:73], v[90:93], v[114:117], v[70:73]
	ds_read_b128 v[110:113], v125 offset:4096
	global_load_lds_dwordx4 v105, s[2:3]
	s_add_u32 m0, s6, 0x9000
	s_waitcnt lgkmcnt(1)
	v_mfma_f32_16x16x32_bf16 v[62:65], v[66:69], v[118:121], v[62:65]
	v_mfma_f32_16x16x32_bf16 v[54:57], v[74:77], v[118:121], v[54:57]
	v_mfma_f32_16x16x32_bf16 v[46:49], v[82:85], v[118:121], v[46:49]
	v_mfma_f32_16x16x32_bf16 v[38:41], v[90:93], v[118:121], v[38:41]
	ds_read_b128 v[114:117], v125 offset:6144
	global_load_lds_dwordx4 v106, s[2:3]
	s_add_u32 m0, s6, 0xa000
	s_waitcnt lgkmcnt(1)
	v_mfma_f32_16x16x32_bf16 v[30:33], v[66:69], v[110:113], v[30:33]
	v_mfma_f32_16x16x32_bf16 v[26:29], v[74:77], v[110:113], v[26:29]
	v_mfma_f32_16x16x32_bf16 v[22:25], v[82:85], v[110:113], v[22:25]
	v_mfma_f32_16x16x32_bf16 v[18:21], v[90:93], v[110:113], v[18:21]
	global_load_lds_dwordx4 v107, s[2:3]
	s_add_u32 m0, s6, 0xb000
	s_waitcnt lgkmcnt(0)
	v_mfma_f32_16x16x32_bf16 v[14:17], v[66:69], v[114:117], v[14:17]
	v_mfma_f32_16x16x32_bf16 v[10:13], v[74:77], v[114:117], v[10:13]
	v_mfma_f32_16x16x32_bf16 v[6:9], v[82:85], v[114:117], v[6:9]
	v_mfma_f32_16x16x32_bf16 v[2:5], v[90:93], v[114:117], v[2:5]
	global_load_lds_dwordx4 v108, s[2:3]
	s_add_u32 s2, s2, 0x80
	s_addc_u32 s3, s3, 0
	s_add_u32 s4, s4, 0x80
	s_addc_u32 s5, s5, 0
	s_waitcnt vmcnt(0) lgkmcnt(0)
	s_barrier
	ds_read_b128 v[34:37], v126 offset:49152
	ds_read_b128 v[42:45], v126 offset:51200
	ds_read_b128 v[50:53], v126 offset:53248
	ds_read_b128 v[58:61], v126 offset:55296
	ds_read_b128 v[110:113], v124 offset:32768
	ds_read_b128 v[114:117], v124 offset:34816
	s_waitcnt lgkmcnt(1)
	v_mfma_f32_16x16x32_bf16 v[94:97], v[34:37], v[110:113], v[94:97]
	v_mfma_f32_16x16x32_bf16 v[86:89], v[42:45], v[110:113], v[86:89]
	v_mfma_f32_16x16x32_bf16 v[78:81], v[50:53], v[110:113], v[78:81]
	v_mfma_f32_16x16x32_bf16 v[70:73], v[58:61], v[110:113], v[70:73]
	ds_read_b128 v[118:121], v124 offset:36864
	ds_read_b128 v[66:69], v127 offset:49152
	ds_read_b128 v[74:77], v127 offset:51200
	ds_read_b128 v[82:85], v127 offset:53248
	ds_read_b128 v[90:93], v127 offset:55296
	s_waitcnt lgkmcnt(5)
	v_mfma_f32_16x16x32_bf16 v[62:65], v[34:37], v[114:117], v[62:65]
	v_mfma_f32_16x16x32_bf16 v[54:57], v[42:45], v[114:117], v[54:57]
	v_mfma_f32_16x16x32_bf16 v[46:49], v[50:53], v[114:117], v[46:49]
	v_mfma_f32_16x16x32_bf16 v[38:41], v[58:61], v[114:117], v[38:41]
	ds_read_b128 v[110:113], v124 offset:38912
	s_waitcnt lgkmcnt(5)
	v_mfma_f32_16x16x32_bf16 v[30:33], v[34:37], v[118:121], v[30:33]
	v_mfma_f32_16x16x32_bf16 v[26:29], v[42:45], v[118:121], v[26:29]
	v_mfma_f32_16x16x32_bf16 v[22:25], v[50:53], v[118:121], v[22:25]
	v_mfma_f32_16x16x32_bf16 v[18:21], v[58:61], v[118:121], v[18:21]
	ds_read_b128 v[114:117], v125 offset:32768
	s_waitcnt lgkmcnt(1)
	v_mfma_f32_16x16x32_bf16 v[14:17], v[34:37], v[110:113], v[14:17]
	v_mfma_f32_16x16x32_bf16 v[10:13], v[42:45], v[110:113], v[10:13]
	v_mfma_f32_16x16x32_bf16 v[6:9], v[50:53], v[110:113], v[6:9]
	v_mfma_f32_16x16x32_bf16 v[2:5], v[58:61], v[110:113], v[2:5]
	ds_read_b128 v[118:121], v125 offset:34816
	s_waitcnt lgkmcnt(1)
	v_mfma_f32_16x16x32_bf16 v[94:97], v[66:69], v[114:117], v[94:97]
	v_mfma_f32_16x16x32_bf16 v[86:89], v[74:77], v[114:117], v[86:89]
	v_mfma_f32_16x16x32_bf16 v[78:81], v[82:85], v[114:117], v[78:81]
	v_mfma_f32_16x16x32_bf16 v[70:73], v[90:93], v[114:117], v[70:73]
	ds_read_b128 v[110:113], v125 offset:36864
	s_waitcnt lgkmcnt(1)
	v_mfma_f32_16x16x32_bf16 v[62:65], v[66:69], v[118:121], v[62:65]
	v_mfma_f32_16x16x32_bf16 v[54:57], v[74:77], v[118:121], v[54:57]
	v_mfma_f32_16x16x32_bf16 v[46:49], v[82:85], v[118:121], v[46:49]
	v_mfma_f32_16x16x32_bf16 v[38:41], v[90:93], v[118:121], v[38:41]
	ds_read_b128 v[114:117], v125 offset:38912
	s_waitcnt lgkmcnt(1)
	v_mfma_f32_16x16x32_bf16 v[30:33], v[66:69], v[110:113], v[30:33]
	v_mfma_f32_16x16x32_bf16 v[26:29], v[74:77], v[110:113], v[26:29]
	v_mfma_f32_16x16x32_bf16 v[22:25], v[82:85], v[110:113], v[22:25]
	v_mfma_f32_16x16x32_bf16 v[18:21], v[90:93], v[110:113], v[18:21]
	s_waitcnt lgkmcnt(0)
	v_mfma_f32_16x16x32_bf16 v[14:17], v[66:69], v[114:117], v[14:17]
	v_mfma_f32_16x16x32_bf16 v[10:13], v[74:77], v[114:117], v[10:13]
	v_mfma_f32_16x16x32_bf16 v[6:9], v[82:85], v[114:117], v[6:9]
	v_mfma_f32_16x16x32_bf16 v[2:5], v[90:93], v[114:117], v[2:5]
	s_waitcnt lgkmcnt(0)
	s_barrier
	s_nop 7
	s_nop 2
.LBB0_100:
	v_lshlrev_b32_e32 v184, 7, v104
	s_mov_b32 s2, 0x24000
	v_add_u32_e32 v0, 0x400, v184
	s_waitcnt vmcnt(7)
	v_mov_b64_e32 v[34:35], s[48:49]
	s_movk_i32 s4, 0x480
	v_mad_i64_i32 v[186:187], s[2:3], v104, s2, 0
	v_mad_i64_i32 v[36:37], s[2:3], v0, s4, v[34:35]
	v_mov_b32_e32 v34, v163
	s_mov_b32 s5, 0x1b000
	v_ashrrev_i32_e32 v35, 3, v34
	v_lshlrev_b32_e32 v0, 4, v34
	s_waitcnt vmcnt(6)
	v_mad_i64_i32 v[42:43], s[2:3], v35, s4, v[98:99]
	v_and_b32_e32 v0, 0x70, v0
	v_mad_i64_i32 v[36:37], s[2:3], v35, s4, v[36:37]
	v_lshl_add_u64 v[188:189], v[42:43], 0, v[0:1]
	s_mov_b32 s2, 0x9000
	v_lshl_add_u64 v[190:191], v[36:37], 0, v[0:1]
	v_and_b32_e32 v146, 7, v163
	v_bfe_u32 v147, v163, 4, 3
	v_xor_b32_e32 v147, v147, v146
	v_sub_u32_e32 v147, v147, v146
	v_lshlrev_b32_e32 v147, 4, v147
	v_lshrrev_b32_e32 v148, 6, v163
	v_lshlrev_b32_e32 v148, 10, v148
	v_readfirstlane_b32 s2, v188
	v_readfirstlane_b32 s3, v189
	v_readfirstlane_b32 s4, v190
	v_readfirstlane_b32 s5, v191
	v_readfirstlane_b32 s6, v148
	s_nop 3
	v_subrev_u32_e32 v220, s2, v188
	v_subrev_u32_e32 v224, s4, v190
	v_add_u32_e32 v220, v220, v147
	v_add_u32_e32 v224, v224, v147
	v_add_u32_e32 v221, 0x9000, v220
	v_add_u32_e32 v225, 0x9000, v224
	v_add_u32_e32 v222, 0x12000, v220
	v_add_u32_e32 v226, 0x12000, v224
	v_add_u32_e32 v223, 0x1b000, v220
	v_add_u32_e32 v227, 0x1b000, v224
	v_lshlrev_b32_e32 v146, 3, v163
	v_lshlrev_b32_e32 v147, 7, v163
	v_and_b32_e32 v148, 0x2000, v147
	v_and_b32_e32 v147, 0x780, v147
	v_and_b32_e32 v229, 64, v146
	v_xor_b32_e32 v146, v146, v163
	v_and_b32_e32 v146, 48, v146
	v_or3_b32 v146, v147, v229, v146
	v_lshlrev_b32_e32 v147, 6, v163
	v_and_b32_e32 v147, 0xffffe000, v147
	v_or_b32_e32 v230, v146, v148
	v_or_b32_e32 v228, v146, v147
	v_xor_b32_e32 v229, 64, v228
	v_xor_b32_e32 v231, 64, v230
	s_add_u32 m0, s6, 0x4000
	s_nop 0
	global_load_lds_dwordx4 v224, s[4:5]
	s_add_u32 m0, s6, 0x5000
	s_nop 0
	global_load_lds_dwordx4 v225, s[4:5]
	s_add_u32 m0, s6, 0x6000
	s_nop 0
	global_load_lds_dwordx4 v226, s[4:5]
	s_add_u32 m0, s6, 0x7000
	s_nop 0
	global_load_lds_dwordx4 v227, s[4:5]
	s_mov_b32 m0, s6
	s_nop 0
	global_load_lds_dwordx4 v220, s[2:3]
	s_add_u32 m0, s6, 0x1000
	s_nop 0
	global_load_lds_dwordx4 v221, s[2:3]
	s_add_u32 m0, s6, 0x2000
	s_nop 0
	global_load_lds_dwordx4 v222, s[2:3]
	s_add_u32 m0, s6, 0x3000
	s_nop 0
	global_load_lds_dwordx4 v223, s[2:3]
	s_add_u32 s2, s2, 0x80
	s_addc_u32 s3, s3, 0
	s_add_u32 s4, s4, 0x80
	s_addc_u32 s5, s5, 0
	s_waitcnt vmcnt(0)
	s_barrier
	ds_read_b128 v[130:133], v230 offset:16384
	ds_read_b128 v[134:137], v230 offset:18432
	ds_read_b128 v[138:141], v230 offset:20480
	ds_read_b128 v[142:145], v230 offset:22528
	ds_read_b128 v[208:211], v228
	ds_read_b128 v[212:215], v228 offset:2048
	s_add_u32 m0, s6, 0xc000
	s_waitcnt lgkmcnt(1)
	v_mfma_f32_16x16x32_bf16 v[126:129], v[130:133], v[208:211], 0
	v_mfma_f32_16x16x32_bf16 v[122:125], v[134:137], v[208:211], 0
	v_mfma_f32_16x16x32_bf16 v[118:121], v[138:141], v[208:211], 0
	v_mfma_f32_16x16x32_bf16 v[114:117], v[142:145], v[208:211], 0
	ds_read_b128 v[216:219], v228 offset:4096
	ds_read_b128 v[146:149], v231 offset:16384
	ds_read_b128 v[150:153], v231 offset:18432
	ds_read_b128 v[154:157], v231 offset:20480
	ds_read_b128 v[158:161], v231 offset:22528
	global_load_lds_dwordx4 v224, s[4:5]
	s_add_u32 m0, s6, 0xd000
	s_waitcnt lgkmcnt(5)
	v_mfma_f32_16x16x32_bf16 v[110:113], v[130:133], v[212:215], 0
	v_mfma_f32_16x16x32_bf16 v[106:109], v[134:137], v[212:215], 0
	v_mfma_f32_16x16x32_bf16 v[102:105], v[138:141], v[212:215], 0
	v_mfma_f32_16x16x32_bf16 v[98:101], v[142:145], v[212:215], 0
	ds_read_b128 v[208:211], v228 offset:6144
	global_load_lds_dwordx4 v225, s[4:5]
	s_add_u32 m0, s6, 0xe000
	s_waitcnt lgkmcnt(5)
	v_mfma_f32_16x16x32_bf16 v[90:93], v[130:133], v[216:219], 0
	v_mfma_f32_16x16x32_bf16 v[82:85], v[134:137], v[216:219], 0
	v_mfma_f32_16x16x32_bf16 v[74:77], v[138:141], v[216:219], 0
	v_mfma_f32_16x16x32_bf16 v[66:69], v[142:145], v[216:219], 0
	ds_read_b128 v[212:215], v229
	global_load_lds_dwordx4 v226, s[4:5]
	s_add_u32 m0, s6, 0xf000
	s_waitcnt lgkmcnt(1)
	v_mfma_f32_16x16x32_bf16 v[58:61], v[130:133], v[208:211], 0
	v_mfma_f32_16x16x32_bf16 v[50:53], v[134:137], v[208:211], 0
	v_mfma_f32_16x16x32_bf16 v[42:45], v[138:141], v[208:211], 0
	v_mfma_f32_16x16x32_bf16 v[34:37], v[142:145], v[208:211], 0
	ds_read_b128 v[216:219], v229 offset:2048
	global_load_lds_dwordx4 v227, s[4:5]
	s_add_u32 m0, s6, 0x8000
	s_waitcnt lgkmcnt(1)
	v_mfma_f32_16x16x32_bf16 v[126:129], v[146:149], v[212:215], v[126:129]
	v_mfma_f32_16x16x32_bf16 v[122:125], v[150:153], v[212:215], v[122:125]
	v_mfma_f32_16x16x32_bf16 v[118:121], v[154:157], v[212:215], v[118:121]
	v_mfma_f32_16x16x32_bf16 v[114:117], v[158:161], v[212:215], v[114:117]
	ds_read_b128 v[208:211], v229 offset:4096
	global_load_lds_dwordx4 v220, s[2:3]
	s_add_u32 m0, s6, 0x9000
	s_waitcnt lgkmcnt(1)
	v_mfma_f32_16x16x32_bf16 v[110:113], v[146:149], v[216:219], v[110:113]
	v_mfma_f32_16x16x32_bf16 v[106:109], v[150:153], v[216:219], v[106:109]
	v_mfma_f32_16x16x32_bf16 v[102:105], v[154:157], v[216:219], v[102:105]
	v_mfma_f32_16x16x32_bf16 v[98:101], v[158:161], v[216:219], v[98:101]
	ds_read_b128 v[212:215], v229 offset:6144
	global_load_lds_dwordx4 v221, s[2:3]
	s_add_u32 m0, s6, 0xa000
	s_waitcnt lgkmcnt(1)
	v_mfma_f32_16x16x32_bf16 v[90:93], v[146:149], v[208:211], v[90:93]
	v_mfma_f32_16x16x32_bf16 v[82:85], v[150:153], v[208:211], v[82:85]
	v_mfma_f32_16x16x32_bf16 v[74:77], v[154:157], v[208:211], v[74:77]
	v_mfma_f32_16x16x32_bf16 v[66:69], v[158:161], v[208:211], v[66:69]
	global_load_lds_dwordx4 v222, s[2:3]
	s_add_u32 m0, s6, 0xb000
	s_waitcnt lgkmcnt(0)
	v_mfma_f32_16x16x32_bf16 v[58:61], v[146:149], v[212:215], v[58:61]
	v_mfma_f32_16x16x32_bf16 v[50:53], v[150:153], v[212:215], v[50:53]
	v_mfma_f32_16x16x32_bf16 v[42:45], v[154:157], v[212:215], v[42:45]
	v_mfma_f32_16x16x32_bf16 v[34:37], v[158:161], v[212:215], v[34:37]
	global_load_lds_dwordx4 v223, s[2:3]
	s_add_u32 s2, s2, 0x80
	s_addc_u32 s3, s3, 0
	s_add_u32 s4, s4, 0x80
	s_addc_u32 s5, s5, 0
	s_waitcnt vmcnt(0) lgkmcnt(0)
	s_barrier
	ds_read_b128 v[130:133], v230 offset:49152
	ds_read_b128 v[134:137], v230 offset:51200
	ds_read_b128 v[138:141], v230 offset:53248
	ds_read_b128 v[142:145], v230 offset:55296
	ds_read_b128 v[208:211], v228 offset:32768
	ds_read_b128 v[212:215], v228 offset:34816
	s_add_u32 m0, s6, 0x4000
	s_waitcnt lgkmcnt(1)
	v_mfma_f32_16x16x32_bf16 v[126:129], v[130:133], v[208:211], v[126:129]
	v_mfma_f32_16x16x32_bf16 v[122:125], v[134:137], v[208:211], v[122:125]
	v_mfma_f32_16x16x32_bf16 v[118:121], v[138:141], v[208:211], v[118:121]
	v_mfma_f32_16x16x32_bf16 v[114:117], v[142:145], v[208:211], v[114:117]
	ds_read_b128 v[216:219], v228 offset:36864
	ds_read_b128 v[146:149], v231 offset:49152
	ds_read_b128 v[150:153], v231 offset:51200
	ds_read_b128 v[154:157], v231 offset:53248
	ds_read_b128 v[158:161], v231 offset:55296
	global_load_lds_dwordx4 v224, s[4:5]
	s_add_u32 m0, s6, 0x5000
	s_waitcnt lgkmcnt(5)
	v_mfma_f32_16x16x32_bf16 v[110:113], v[130:133], v[212:215], v[110:113]
	v_mfma_f32_16x16x32_bf16 v[106:109], v[134:137], v[212:215], v[106:109]
	v_mfma_f32_16x16x32_bf16 v[102:105], v[138:141], v[212:215], v[102:105]
	v_mfma_f32_16x16x32_bf16 v[98:101], v[142:145], v[212:215], v[98:101]
	ds_read_b128 v[208:211], v228 offset:38912
	global_load_lds_dwordx4 v225, s[4:5]
	s_add_u32 m0, s6, 0x6000
	s_waitcnt lgkmcnt(5)
	v_mfma_f32_16x16x32_bf16 v[90:93], v[130:133], v[216:219], v[90:93]
	v_mfma_f32_16x16x32_bf16 v[82:85], v[134:137], v[216:219], v[82:85]
	v_mfma_f32_16x16x32_bf16 v[74:77], v[138:141], v[216:219], v[74:77]
	v_mfma_f32_16x16x32_bf16 v[66:69], v[142:145], v[216:219], v[66:69]
	ds_read_b128 v[212:215], v229 offset:32768
	global_load_lds_dwordx4 v226, s[4:5]
	s_add_u32 m0, s6, 0x7000
	s_waitcnt lgkmcnt(1)
	v_mfma_f32_16x16x32_bf16 v[58:61], v[130:133], v[208:211], v[58:61]
	v_mfma_f32_16x16x32_bf16 v[50:53], v[134:137], v[208:211], v[50:53]
	v_mfma_f32_16x16x32_bf16 v[42:45], v[138:141], v[208:211], v[42:45]
	v_mfma_f32_16x16x32_bf16 v[34:37], v[142:145], v[208:211], v[34:37]
	ds_read_b128 v[216:219], v229 offset:34816
	global_load_lds_dwordx4 v227, s[4:5]
	s_mov_b32 m0, s6
	s_waitcnt lgkmcnt(1)
	v_mfma_f32_16x16x32_bf16 v[126:129], v[146:149], v[212:215], v[126:129]
	v_mfma_f32_16x16x32_bf16 v[122:125], v[150:153], v[212:215], v[122:125]
	v_mfma_f32_16x16x32_bf16 v[118:121], v[154:157], v[212:215], v[118:121]
	v_mfma_f32_16x16x32_bf16 v[114:117], v[158:161], v[212:215], v[114:117]
	ds_read_b128 v[208:211], v229 offset:36864
	global_load_lds_dwordx4 v220, s[2:3]
	s_add_u32 m0, s6, 0x1000
	s_waitcnt lgkmcnt(1)
	v_mfma_f32_16x16x32_bf16 v[110:113], v[146:149], v[216:219], v[110:113]
	v_mfma_f32_16x16x32_bf16 v[106:109], v[150:153], v[216:219], v[106:109]
	v_mfma_f32_16x16x32_bf16 v[102:105], v[154:157], v[216:219], v[102:105]
	v_mfma_f32_16x16x32_bf16 v[98:101], v[158:161], v[216:219], v[98:101]
	ds_read_b128 v[212:215], v229 offset:38912
	global_load_lds_dwordx4 v221, s[2:3]
	s_add_u32 m0, s6, 0x2000
	s_waitcnt lgkmcnt(1)
	v_mfma_f32_16x16x32_bf16 v[90:93], v[146:149], v[208:211], v[90:93]
	v_mfma_f32_16x16x32_bf16 v[82:85], v[150:153], v[208:211], v[82:85]
	v_mfma_f32_16x16x32_bf16 v[74:77], v[154:157], v[208:211], v[74:77]
	v_mfma_f32_16x16x32_bf16 v[66:69], v[158:161], v[208:211], v[66:69]
	global_load_lds_dwordx4 v222, s[2:3]
	s_add_u32 m0, s6, 0x3000
	s_waitcnt lgkmcnt(0)
	v_mfma_f32_16x16x32_bf16 v[58:61], v[146:149], v[212:215], v[58:61]
	v_mfma_f32_16x16x32_bf16 v[50:53], v[150:153], v[212:215], v[50:53]
	v_mfma_f32_16x16x32_bf16 v[42:45], v[154:157], v[212:215], v[42:45]
	v_mfma_f32_16x16x32_bf16 v[34:37], v[158:161], v[212:215], v[34:37]
	global_load_lds_dwordx4 v223, s[2:3]
	s_add_u32 s2, s2, 0x80
	s_addc_u32 s3, s3, 0
	s_add_u32 s4, s4, 0x80
	s_addc_u32 s5, s5, 0
	s_waitcnt vmcnt(0) lgkmcnt(0)
	s_barrier
	s_movk_i32 s7, 2
.Lm2_loop:
	ds_read_b128 v[130:133], v230 offset:16384
	ds_read_b128 v[134:137], v230 offset:18432
	ds_read_b128 v[138:141], v230 offset:20480
	ds_read_b128 v[142:145], v230 offset:22528
	ds_read_b128 v[208:211], v228
	ds_read_b128 v[212:215], v228 offset:2048
	s_add_u32 m0, s6, 0xc000
	s_waitcnt lgkmcnt(1)
	v_mfma_f32_16x16x32_bf16 v[126:129], v[130:133], v[208:211], v[126:129]
	v_mfma_f32_16x16x32_bf16 v[122:125], v[134:137], v[208:211], v[122:125]
	v_mfma_f32_16x16x32_bf16 v[118:121], v[138:141], v[208:211], v[118:121]
	v_mfma_f32_16x16x32_bf16 v[114:117], v[142:145], v[208:211], v[114:117]
	ds_read_b128 v[216:219], v228 offset:4096
	ds_read_b128 v[146:149], v231 offset:16384
	ds_read_b128 v[150:153], v231 offset:18432
	ds_read_b128 v[154:157], v231 offset:20480
	ds_read_b128 v[158:161], v231 offset:22528
	global_load_lds_dwordx4 v224, s[4:5]
	s_add_u32 m0, s6, 0xd000
	s_waitcnt lgkmcnt(5)
	v_mfma_f32_16x16x32_bf16 v[110:113], v[130:133], v[212:215], v[110:113]
	v_mfma_f32_16x16x32_bf16 v[106:109], v[134:137], v[212:215], v[106:109]
	v_mfma_f32_16x16x32_bf16 v[102:105], v[138:141], v[212:215], v[102:105]
	v_mfma_f32_16x16x32_bf16 v[98:101], v[142:145], v[212:215], v[98:101]
	ds_read_b128 v[208:211], v228 offset:6144
	global_load_lds_dwordx4 v225, s[4:5]
	s_add_u32 m0, s6, 0xe000
	s_waitcnt lgkmcnt(5)
	v_mfma_f32_16x16x32_bf16 v[90:93], v[130:133], v[216:219], v[90:93]
	v_mfma_f32_16x16x32_bf16 v[82:85], v[134:137], v[216:219], v[82:85]
	v_mfma_f32_16x16x32_bf16 v[74:77], v[138:141], v[216:219], v[74:77]
	v_mfma_f32_16x16x32_bf16 v[66:69], v[142:145], v[216:219], v[66:69]
	ds_read_b128 v[212:215], v229
	global_load_lds_dwordx4 v226, s[4:5]
	s_add_u32 m0, s6, 0xf000
	s_waitcnt lgkmcnt(1)
	v_mfma_f32_16x16x32_bf16 v[58:61], v[130:133], v[208:211], v[58:61]
	v_mfma_f32_16x16x32_bf16 v[50:53], v[134:137], v[208:211], v[50:53]
	v_mfma_f32_16x16x32_bf16 v[42:45], v[138:141], v[208:211], v[42:45]
	v_mfma_f32_16x16x32_bf16 v[34:37], v[142:145], v[208:211], v[34:37]
	ds_read_b128 v[216:219], v229 offset:2048
	global_load_lds_dwordx4 v227, s[4:5]
	s_add_u32 m0, s6, 0x8000
	s_waitcnt lgkmcnt(1)
	v_mfma_f32_16x16x32_bf16 v[126:129], v[146:149], v[212:215], v[126:129]
	v_mfma_f32_16x16x32_bf16 v[122:125], v[150:153], v[212:215], v[122:125]
	v_mfma_f32_16x16x32_bf16 v[118:121], v[154:157], v[212:215], v[118:121]
	v_mfma_f32_16x16x32_bf16 v[114:117], v[158:161], v[212:215], v[114:117]
	ds_read_b128 v[208:211], v229 offset:4096
	global_load_lds_dwordx4 v220, s[2:3]
	s_add_u32 m0, s6, 0x9000
	s_waitcnt lgkmcnt(1)
	v_mfma_f32_16x16x32_bf16 v[110:113], v[146:149], v[216:219], v[110:113]
	v_mfma_f32_16x16x32_bf16 v[106:109], v[150:153], v[216:219], v[106:109]
	v_mfma_f32_16x16x32_bf16 v[102:105], v[154:157], v[216:219], v[102:105]
	v_mfma_f32_16x16x32_bf16 v[98:101], v[158:161], v[216:219], v[98:101]
	ds_read_b128 v[212:215], v229 offset:6144
	global_load_lds_dwordx4 v221, s[2:3]
	s_add_u32 m0, s6, 0xa000
	s_waitcnt lgkmcnt(1)
	v_mfma_f32_16x16x32_bf16 v[90:93], v[146:149], v[208:211], v[90:93]
	v_mfma_f32_16x16x32_bf16 v[82:85], v[150:153], v[208:211], v[82:85]
	v_mfma_f32_16x16x32_bf16 v[74:77], v[154:157], v[208:211], v[74:77]
	v_mfma_f32_16x16x32_bf16 v[66:69], v[158:161], v[208:211], v[66:69]
	global_load_lds_dwordx4 v222, s[2:3]
	s_add_u32 m0, s6, 0xb000
	s_waitcnt lgkmcnt(0)
	v_mfma_f32_16x16x32_bf16 v[58:61], v[146:149], v[212:215], v[58:61]
	v_mfma_f32_16x16x32_bf16 v[50:53], v[150:153], v[212:215], v[50:53]
	v_mfma_f32_16x16x32_bf16 v[42:45], v[154:157], v[212:215], v[42:45]
	v_mfma_f32_16x16x32_bf16 v[34:37], v[158:161], v[212:215], v[34:37]
	global_load_lds_dwordx4 v223, s[2:3]
	s_add_u32 s2, s2, 0x80
	s_addc_u32 s3, s3, 0
	s_add_u32 s4, s4, 0x80
	s_addc_u32 s5, s5, 0
	s_waitcnt vmcnt(0) lgkmcnt(0)
	s_barrier
	ds_read_b128 v[130:133], v230 offset:49152
	ds_read_b128 v[134:137], v230 offset:51200
	ds_read_b128 v[138:141], v230 offset:53248
	ds_read_b128 v[142:145], v230 offset:55296
	ds_read_b128 v[208:211], v228 offset:32768
	ds_read_b128 v[212:215], v228 offset:34816
	s_add_u32 m0, s6, 0x4000
	s_waitcnt lgkmcnt(1)
	v_mfma_f32_16x16x32_bf16 v[126:129], v[130:133], v[208:211], v[126:129]
	v_mfma_f32_16x16x32_bf16 v[122:125], v[134:137], v[208:211], v[122:125]
	v_mfma_f32_16x16x32_bf16 v[118:121], v[138:141], v[208:211], v[118:121]
	v_mfma_f32_16x16x32_bf16 v[114:117], v[142:145], v[208:211], v[114:117]
	ds_read_b128 v[216:219], v228 offset:36864
	ds_read_b128 v[146:149], v231 offset:49152
	ds_read_b128 v[150:153], v231 offset:51200
	ds_read_b128 v[154:157], v231 offset:53248
	ds_read_b128 v[158:161], v231 offset:55296
	global_load_lds_dwordx4 v224, s[4:5]
	s_add_u32 m0, s6, 0x5000
	s_waitcnt lgkmcnt(5)
	v_mfma_f32_16x16x32_bf16 v[110:113], v[130:133], v[212:215], v[110:113]
	v_mfma_f32_16x16x32_bf16 v[106:109], v[134:137], v[212:215], v[106:109]
	v_mfma_f32_16x16x32_bf16 v[102:105], v[138:141], v[212:215], v[102:105]
	v_mfma_f32_16x16x32_bf16 v[98:101], v[142:145], v[212:215], v[98:101]
	ds_read_b128 v[208:211], v228 offset:38912
	global_load_lds_dwordx4 v225, s[4:5]
	s_add_u32 m0, s6, 0x6000
	s_waitcnt lgkmcnt(5)
	v_mfma_f32_16x16x32_bf16 v[90:93], v[130:133], v[216:219], v[90:93]
	v_mfma_f32_16x16x32_bf16 v[82:85], v[134:137], v[216:219], v[82:85]
	v_mfma_f32_16x16x32_bf16 v[74:77], v[138:141], v[216:219], v[74:77]
	v_mfma_f32_16x16x32_bf16 v[66:69], v[142:145], v[216:219], v[66:69]
	ds_read_b128 v[212:215], v229 offset:32768
	global_load_lds_dwordx4 v226, s[4:5]
	s_add_u32 m0, s6, 0x7000
	s_waitcnt lgkmcnt(1)
	v_mfma_f32_16x16x32_bf16 v[58:61], v[130:133], v[208:211], v[58:61]
	v_mfma_f32_16x16x32_bf16 v[50:53], v[134:137], v[208:211], v[50:53]
	v_mfma_f32_16x16x32_bf16 v[42:45], v[138:141], v[208:211], v[42:45]
	v_mfma_f32_16x16x32_bf16 v[34:37], v[142:145], v[208:211], v[34:37]
	ds_read_b128 v[216:219], v229 offset:34816
	global_load_lds_dwordx4 v227, s[4:5]
	s_mov_b32 m0, s6
	s_waitcnt lgkmcnt(1)
	v_mfma_f32_16x16x32_bf16 v[126:129], v[146:149], v[212:215], v[126:129]
	v_mfma_f32_16x16x32_bf16 v[122:125], v[150:153], v[212:215], v[122:125]
	v_mfma_f32_16x16x32_bf16 v[118:121], v[154:157], v[212:215], v[118:121]
	v_mfma_f32_16x16x32_bf16 v[114:117], v[158:161], v[212:215], v[114:117]
	ds_read_b128 v[208:211], v229 offset:36864
	global_load_lds_dwordx4 v220, s[2:3]
	s_add_u32 m0, s6, 0x1000
	s_waitcnt lgkmcnt(1)
	v_mfma_f32_16x16x32_bf16 v[110:113], v[146:149], v[216:219], v[110:113]
	v_mfma_f32_16x16x32_bf16 v[106:109], v[150:153], v[216:219], v[106:109]
	v_mfma_f32_16x16x32_bf16 v[102:105], v[154:157], v[216:219], v[102:105]
	v_mfma_f32_16x16x32_bf16 v[98:101], v[158:161], v[216:219], v[98:101]
	ds_read_b128 v[212:215], v229 offset:38912
	global_load_lds_dwordx4 v221, s[2:3]
	s_add_u32 m0, s6, 0x2000
	s_waitcnt lgkmcnt(1)
	v_mfma_f32_16x16x32_bf16 v[90:93], v[146:149], v[208:211], v[90:93]
	v_mfma_f32_16x16x32_bf16 v[82:85], v[150:153], v[208:211], v[82:85]
	v_mfma_f32_16x16x32_bf16 v[74:77], v[154:157], v[208:211], v[74:77]
	v_mfma_f32_16x16x32_bf16 v[66:69], v[158:161], v[208:211], v[66:69]
	global_load_lds_dwordx4 v222, s[2:3]
	s_add_u32 m0, s6, 0x3000
	s_waitcnt lgkmcnt(0)
	v_mfma_f32_16x16x32_bf16 v[58:61], v[146:149], v[212:215], v[58:61]
	v_mfma_f32_16x16x32_bf16 v[50:53], v[150:153], v[212:215], v[50:53]
	v_mfma_f32_16x16x32_bf16 v[42:45], v[154:157], v[212:215], v[42:45]
	v_mfma_f32_16x16x32_bf16 v[34:37], v[158:161], v[212:215], v[34:37]
	global_load_lds_dwordx4 v223, s[2:3]
	s_add_u32 s2, s2, 0x80
	s_addc_u32 s3, s3, 0
	s_add_u32 s4, s4, 0x80
	s_addc_u32 s5, s5, 0
	s_add_i32 s7, s7, -1
	s_waitcnt vmcnt(0) lgkmcnt(0)
	s_barrier
	s_cmp_lg_u32 s7, 0
	s_cbranch_scc1 .Lm2_loop
	ds_read_b128 v[130:133], v230 offset:16384
	ds_read_b128 v[134:137], v230 offset:18432
	ds_read_b128 v[138:141], v230 offset:20480
	ds_read_b128 v[142:145], v230 offset:22528
	ds_read_b128 v[208:211], v228
	ds_read_b128 v[212:215], v228 offset:2048
	s_add_u32 m0, s6, 0xc000
	s_waitcnt lgkmcnt(1)
	v_mfma_f32_16x16x32_bf16 v[126:129], v[130:133], v[208:211], v[126:129]
	v_mfma_f32_16x16x32_bf16 v[122:125], v[134:137], v[208:211], v[122:125]
	v_mfma_f32_16x16x32_bf16 v[118:121], v[138:141], v[208:211], v[118:121]
	v_mfma_f32_16x16x32_bf16 v[114:117], v[142:145], v[208:211], v[114:117]
	ds_read_b128 v[216:219], v228 offset:4096
	ds_read_b128 v[146:149], v231 offset:16384
	ds_read_b128 v[150:153], v231 offset:18432
	ds_read_b128 v[154:157], v231 offset:20480
	ds_read_b128 v[158:161], v231 offset:22528
	global_load_lds_dwordx4 v224, s[4:5]
	s_add_u32 m0, s6, 0xd000
	s_waitcnt lgkmcnt(5)
	v_mfma_f32_16x16x32_bf16 v[110:113], v[130:133], v[212:215], v[110:113]
	v_mfma_f32_16x16x32_bf16 v[106:109], v[134:137], v[212:215], v[106:109]
	v_mfma_f32_16x16x32_bf16 v[102:105], v[138:141], v[212:215], v[102:105]
	v_mfma_f32_16x16x32_bf16 v[98:101], v[142:145], v[212:215], v[98:101]
	ds_read_b128 v[208:211], v228 offset:6144
	global_load_lds_dwordx4 v225, s[4:5]
	s_add_u32 m0, s6, 0xe000
	s_waitcnt lgkmcnt(5)
	v_mfma_f32_16x16x32_bf16 v[90:93], v[130:133], v[216:219], v[90:93]
	v_mfma_f32_16x16x32_bf16 v[82:85], v[134:137], v[216:219], v[82:85]
	v_mfma_f32_16x16x32_bf16 v[74:77], v[138:141], v[216:219], v[74:77]
	v_mfma_f32_16x16x32_bf16 v[66:69], v[142:145], v[216:219], v[66:69]
	ds_read_b128 v[212:215], v229
	global_load_lds_dwordx4 v226, s[4:5]
	s_add_u32 m0, s6, 0xf000
	s_waitcnt lgkmcnt(1)
	v_mfma_f32_16x16x32_bf16 v[58:61], v[130:133], v[208:211], v[58:61]
	v_mfma_f32_16x16x32_bf16 v[50:53], v[134:137], v[208:211], v[50:53]
	v_mfma_f32_16x16x32_bf16 v[42:45], v[138:141], v[208:211], v[42:45]
	v_mfma_f32_16x16x32_bf16 v[34:37], v[142:145], v[208:211], v[34:37]
	ds_read_b128 v[216:219], v229 offset:2048
	global_load_lds_dwordx4 v227, s[4:5]
	s_add_u32 m0, s6, 0x8000
	s_waitcnt lgkmcnt(1)
	v_mfma_f32_16x16x32_bf16 v[126:129], v[146:149], v[212:215], v[126:129]
	v_mfma_f32_16x16x32_bf16 v[122:125], v[150:153], v[212:215], v[122:125]
	v_mfma_f32_16x16x32_bf16 v[118:121], v[154:157], v[212:215], v[118:121]
	v_mfma_f32_16x16x32_bf16 v[114:117], v[158:161], v[212:215], v[114:117]
	ds_read_b128 v[208:211], v229 offset:4096
	global_load_lds_dwordx4 v220, s[2:3]
	s_add_u32 m0, s6, 0x9000
	s_waitcnt lgkmcnt(1)
	v_mfma_f32_16x16x32_bf16 v[110:113], v[146:149], v[216:219], v[110:113]
	v_mfma_f32_16x16x32_bf16 v[106:109], v[150:153], v[216:219], v[106:109]
	v_mfma_f32_16x16x32_bf16 v[102:105], v[154:157], v[216:219], v[102:105]
	v_mfma_f32_16x16x32_bf16 v[98:101], v[158:161], v[216:219], v[98:101]
	ds_read_b128 v[212:215], v229 offset:6144
	global_load_lds_dwordx4 v221, s[2:3]
	s_add_u32 m0, s6, 0xa000
	s_waitcnt lgkmcnt(1)
	v_mfma_f32_16x16x32_bf16 v[90:93], v[146:149], v[208:211], v[90:93]
	v_mfma_f32_16x16x32_bf16 v[82:85], v[150:153], v[208:211], v[82:85]
	v_mfma_f32_16x16x32_bf16 v[74:77], v[154:157], v[208:211], v[74:77]
	v_mfma_f32_16x16x32_bf16 v[66:69], v[158:161], v[208:211], v[66:69]
	global_load_lds_dwordx4 v222, s[2:3]
	s_add_u32 m0, s6, 0xb000
	s_waitcnt lgkmcnt(0)
	v_mfma_f32_16x16x32_bf16 v[58:61], v[146:149], v[212:215], v[58:61]
	v_mfma_f32_16x16x32_bf16 v[50:53], v[150:153], v[212:215], v[50:53]
	v_mfma_f32_16x16x32_bf16 v[42:45], v[154:157], v[212:215], v[42:45]
	v_mfma_f32_16x16x32_bf16 v[34:37], v[158:161], v[212:215], v[34:37]
	global_load_lds_dwordx4 v223, s[2:3]
	s_add_u32 s2, s2, 0x80
	s_addc_u32 s3, s3, 0
	s_add_u32 s4, s4, 0x80
	s_addc_u32 s5, s5, 0
	s_waitcnt vmcnt(0) lgkmcnt(0)
	s_barrier
	ds_read_b128 v[130:133], v230 offset:49152
	ds_read_b128 v[134:137], v230 offset:51200
	ds_read_b128 v[138:141], v230 offset:53248
	ds_read_b128 v[142:145], v230 offset:55296
	ds_read_b128 v[208:211], v228 offset:32768
	ds_read_b128 v[212:215], v228 offset:34816
	s_waitcnt lgkmcnt(1)
	v_mfma_f32_16x16x32_bf16 v[126:129], v[130:133], v[208:211], v[126:129]
	v_mfma_f32_16x16x32_bf16 v[122:125], v[134:137], v[208:211], v[122:125]
	v_mfma_f32_16x16x32_bf16 v[118:121], v[138:141], v[208:211], v[118:121]
	v_mfma_f32_16x16x32_bf16 v[114:117], v[142:145], v[208:211], v[114:117]
	ds_read_b128 v[216:219], v228 offset:36864
	ds_read_b128 v[146:149], v231 offset:49152
	ds_read_b128 v[150:153], v231 offset:51200
	ds_read_b128 v[154:157], v231 offset:53248
	ds_read_b128 v[158:161], v231 offset:55296
	s_waitcnt lgkmcnt(5)
	v_mfma_f32_16x16x32_bf16 v[110:113], v[130:133], v[212:215], v[110:113]
	v_mfma_f32_16x16x32_bf16 v[106:109], v[134:137], v[212:215], v[106:109]
	v_mfma_f32_16x16x32_bf16 v[102:105], v[138:141], v[212:215], v[102:105]
	v_mfma_f32_16x16x32_bf16 v[98:101], v[142:145], v[212:215], v[98:101]
	ds_read_b128 v[208:211], v228 offset:38912
	s_waitcnt lgkmcnt(5)
	v_mfma_f32_16x16x32_bf16 v[90:93], v[130:133], v[216:219], v[90:93]
	v_mfma_f32_16x16x32_bf16 v[82:85], v[134:137], v[216:219], v[82:85]
	v_mfma_f32_16x16x32_bf16 v[74:77], v[138:141], v[216:219], v[74:77]
	v_mfma_f32_16x16x32_bf16 v[66:69], v[142:145], v[216:219], v[66:69]
	ds_read_b128 v[212:215], v229 offset:32768
	s_waitcnt lgkmcnt(1)
	v_mfma_f32_16x16x32_bf16 v[58:61], v[130:133], v[208:211], v[58:61]
	v_mfma_f32_16x16x32_bf16 v[50:53], v[134:137], v[208:211], v[50:53]
	v_mfma_f32_16x16x32_bf16 v[42:45], v[138:141], v[208:211], v[42:45]
	v_mfma_f32_16x16x32_bf16 v[34:37], v[142:145], v[208:211], v[34:37]
	ds_read_b128 v[216:219], v229 offset:34816
	s_waitcnt lgkmcnt(1)
	v_mfma_f32_16x16x32_bf16 v[126:129], v[146:149], v[212:215], v[126:129]
	v_mfma_f32_16x16x32_bf16 v[122:125], v[150:153], v[212:215], v[122:125]
	v_mfma_f32_16x16x32_bf16 v[118:121], v[154:157], v[212:215], v[118:121]
	v_mfma_f32_16x16x32_bf16 v[114:117], v[158:161], v[212:215], v[114:117]
	ds_read_b128 v[208:211], v229 offset:36864
	s_waitcnt lgkmcnt(1)
	v_mfma_f32_16x16x32_bf16 v[110:113], v[146:149], v[216:219], v[110:113]
	v_mfma_f32_16x16x32_bf16 v[106:109], v[150:153], v[216:219], v[106:109]
	v_mfma_f32_16x16x32_bf16 v[102:105], v[154:157], v[216:219], v[102:105]
	v_mfma_f32_16x16x32_bf16 v[98:101], v[158:161], v[216:219], v[98:101]
	ds_read_b128 v[212:215], v229 offset:38912
	s_waitcnt lgkmcnt(1)
	v_mfma_f32_16x16x32_bf16 v[90:93], v[146:149], v[208:211], v[90:93]
	v_mfma_f32_16x16x32_bf16 v[82:85], v[150:153], v[208:211], v[82:85]
	v_mfma_f32_16x16x32_bf16 v[74:77], v[154:157], v[208:211], v[74:77]
	v_mfma_f32_16x16x32_bf16 v[66:69], v[158:161], v[208:211], v[66:69]
	s_waitcnt lgkmcnt(0)
	v_mfma_f32_16x16x32_bf16 v[58:61], v[146:149], v[212:215], v[58:61]
	v_mfma_f32_16x16x32_bf16 v[50:53], v[150:153], v[212:215], v[50:53]
	v_mfma_f32_16x16x32_bf16 v[42:45], v[154:157], v[212:215], v[42:45]
	v_mfma_f32_16x16x32_bf16 v[34:37], v[158:161], v[212:215], v[34:37]
	s_waitcnt lgkmcnt(0)
	s_barrier
	s_nop 7
	s_nop 2
	s_movk_i32 s92, 0x480

.LBB0_112:
	s_cmp_eq_u32 s5, 1
	s_cselect_b32 s3, s85, s87
	s_cselect_b32 s2, s84, s86
	s_cselect_b32 s7, s51, s53
	s_cselect_b32 s6, s50, s52
	v_mov_b32_e32 v2, v163
	v_lshl_add_u64 v[4:5], s[2:3], 0, v[182:183]
	v_lshl_add_u64 v[6:7], s[6:7], 0, v[186:187]
	s_movk_i32 s6, 0x480
	v_ashrrev_i32_e32 v3, 3, v2
	v_lshlrev_b32_e32 v0, 4, v2
	v_mad_i64_i32 v[4:5], s[2:3], v3, s6, v[4:5]
	v_and_b32_e32 v0, 0x70, v0
	v_lshl_add_u64 v[132:133], v[4:5], 0, v[0:1]
	v_mad_i64_i32 v[4:5], s[2:3], v3, s6, v[6:7]
	s_mov_b32 s2, 0x9000
	v_lshl_add_u64 v[134:135], v[4:5], 0, v[0:1]
	v_and_b32_e32 v82, 7, v163
	v_bfe_u32 v83, v163, 4, 3
	v_xor_b32_e32 v83, v83, v82
	v_sub_u32_e32 v83, v83, v82
	v_lshlrev_b32_e32 v83, 4, v83
	v_lshrrev_b32_e32 v84, 6, v163
	v_lshlrev_b32_e32 v84, 10, v84
	v_readfirstlane_b32 s2, v132
	v_readfirstlane_b32 s3, v133
	v_readfirstlane_b32 s6, v134
	v_readfirstlane_b32 s7, v135
	v_readfirstlane_b32 s8, v84
	s_nop 3
	v_subrev_u32_e32 v154, s2, v132
	v_subrev_u32_e32 v158, s6, v134
	v_add_u32_e32 v154, v154, v83
	v_add_u32_e32 v158, v158, v83
	v_add_u32_e32 v155, 0x9000, v154
	v_add_u32_e32 v159, 0x9000, v158
	v_add_u32_e32 v156, 0x12000, v154
	v_add_u32_e32 v160, 0x12000, v158
	v_add_u32_e32 v157, 0x1b000, v154
	v_add_u32_e32 v161, 0x1b000, v158
	v_lshlrev_b32_e32 v82, 3, v163
	v_lshlrev_b32_e32 v83, 7, v163
	v_and_b32_e32 v84, 0x2000, v83
	v_and_b32_e32 v83, 0x780, v83
	v_and_b32_e32 v189, 64, v82
	v_xor_b32_e32 v82, v82, v163
	v_and_b32_e32 v82, 48, v82
	v_or3_b32 v82, v83, v189, v82
	v_lshlrev_b32_e32 v83, 6, v163
	v_and_b32_e32 v83, 0xffffe000, v83
	v_or_b32_e32 v190, v82, v84
	v_or_b32_e32 v188, v82, v83
	v_xor_b32_e32 v189, 64, v188
	v_xor_b32_e32 v191, 64, v190
	s_add_u32 m0, s8, 0x4000
	s_nop 0
	global_load_lds_dwordx4 v158, s[6:7]
	s_add_u32 m0, s8, 0x5000
	s_nop 0
	global_load_lds_dwordx4 v159, s[6:7]
	s_add_u32 m0, s8, 0x6000
	s_nop 0
	global_load_lds_dwordx4 v160, s[6:7]
	s_add_u32 m0, s8, 0x7000
	s_nop 0
	global_load_lds_dwordx4 v161, s[6:7]
	s_mov_b32 m0, s8
	s_nop 0
	global_load_lds_dwordx4 v154, s[2:3]
	s_add_u32 m0, s8, 0x1000
	s_nop 0
	global_load_lds_dwordx4 v155, s[2:3]
	s_add_u32 m0, s8, 0x2000
	s_nop 0
	global_load_lds_dwordx4 v156, s[2:3]
	s_add_u32 m0, s8, 0x3000
	s_nop 0
	global_load_lds_dwordx4 v157, s[2:3]
	s_add_u32 s2, s2, 0x80
	s_addc_u32 s3, s3, 0
	s_add_u32 s6, s6, 0x80
	s_addc_u32 s7, s7, 0
	s_waitcnt vmcnt(0)
	s_barrier
	ds_read_b128 v[66:69], v190 offset:16384
	ds_read_b128 v[70:73], v190 offset:18432
	ds_read_b128 v[74:77], v190 offset:20480
	ds_read_b128 v[78:81], v190 offset:22528
	ds_read_b128 v[142:145], v188
	ds_read_b128 v[146:149], v188 offset:2048
	s_add_u32 m0, s8, 0xc000
	s_waitcnt lgkmcnt(1)
	v_mfma_f32_16x16x32_bf16 v[62:65], v[66:69], v[142:145], 0
	v_mfma_f32_16x16x32_bf16 v[58:61], v[70:73], v[142:145], 0
	v_mfma_f32_16x16x32_bf16 v[54:57], v[74:77], v[142:145], 0
	v_mfma_f32_16x16x32_bf16 v[50:53], v[78:81], v[142:145], 0
	ds_read_b128 v[150:153], v188 offset:4096
	ds_read_b128 v[82:85], v191 offset:16384
	ds_read_b128 v[86:89], v191 offset:18432
	ds_read_b128 v[90:93], v191 offset:20480
	ds_read_b128 v[94:97], v191 offset:22528
	global_load_lds_dwordx4 v158, s[6:7]
	s_add_u32 m0, s8, 0xd000
	s_waitcnt lgkmcnt(5)
	v_mfma_f32_16x16x32_bf16 v[46:49], v[66:69], v[146:149], 0
	v_mfma_f32_16x16x32_bf16 v[42:45], v[70:73], v[146:149], 0
	v_mfma_f32_16x16x32_bf16 v[38:41], v[74:77], v[146:149], 0
	v_mfma_f32_16x16x32_bf16 v[34:37], v[78:81], v[146:149], 0
	ds_read_b128 v[142:145], v188 offset:6144
	global_load_lds_dwordx4 v159, s[6:7]
	s_add_u32 m0, s8, 0xe000
	s_waitcnt lgkmcnt(5)
	v_mfma_f32_16x16x32_bf16 v[30:33], v[66:69], v[150:153], 0
	v_mfma_f32_16x16x32_bf16 v[26:29], v[70:73], v[150:153], 0
	v_mfma_f32_16x16x32_bf16 v[22:25], v[74:77], v[150:153], 0
	v_mfma_f32_16x16x32_bf16 v[18:21], v[78:81], v[150:153], 0
	ds_read_b128 v[146:149], v189
	global_load_lds_dwordx4 v160, s[6:7]
	s_add_u32 m0, s8, 0xf000
	s_waitcnt lgkmcnt(1)
	v_mfma_f32_16x16x32_bf16 v[14:17], v[66:69], v[142:145], 0
	v_mfma_f32_16x16x32_bf16 v[10:13], v[70:73], v[142:145], 0
	v_mfma_f32_16x16x32_bf16 v[6:9], v[74:77], v[142:145], 0
	v_mfma_f32_16x16x32_bf16 v[2:5], v[78:81], v[142:145], 0
	ds_read_b128 v[150:153], v189 offset:2048
	global_load_lds_dwordx4 v161, s[6:7]
	s_add_u32 m0, s8, 0x8000
	s_waitcnt lgkmcnt(1)
	v_mfma_f32_16x16x32_bf16 v[62:65], v[82:85], v[146:149], v[62:65]
	v_mfma_f32_16x16x32_bf16 v[58:61], v[86:89], v[146:149], v[58:61]
	v_mfma_f32_16x16x32_bf16 v[54:57], v[90:93], v[146:149], v[54:57]
	v_mfma_f32_16x16x32_bf16 v[50:53], v[94:97], v[146:149], v[50:53]
	ds_read_b128 v[142:145], v189 offset:4096
	global_load_lds_dwordx4 v154, s[2:3]
	s_add_u32 m0, s8, 0x9000
	s_waitcnt lgkmcnt(1)
	v_mfma_f32_16x16x32_bf16 v[46:49], v[82:85], v[150:153], v[46:49]
	v_mfma_f32_16x16x32_bf16 v[42:45], v[86:89], v[150:153], v[42:45]
	v_mfma_f32_16x16x32_bf16 v[38:41], v[90:93], v[150:153], v[38:41]
	v_mfma_f32_16x16x32_bf16 v[34:37], v[94:97], v[150:153], v[34:37]
	ds_read_b128 v[146:149], v189 offset:6144
	global_load_lds_dwordx4 v155, s[2:3]
	s_add_u32 m0, s8, 0xa000
	s_waitcnt lgkmcnt(1)
	v_mfma_f32_16x16x32_bf16 v[30:33], v[82:85], v[142:145], v[30:33]
	v_mfma_f32_16x16x32_bf16 v[26:29], v[86:89], v[142:145], v[26:29]
	v_mfma_f32_16x16x32_bf16 v[22:25], v[90:93], v[142:145], v[22:25]
	v_mfma_f32_16x16x32_bf16 v[18:21], v[94:97], v[142:145], v[18:21]
	global_load_lds_dwordx4 v156, s[2:3]
	s_add_u32 m0, s8, 0xb000
	s_waitcnt lgkmcnt(0)
	v_mfma_f32_16x16x32_bf16 v[14:17], v[82:85], v[146:149], v[14:17]
	v_mfma_f32_16x16x32_bf16 v[10:13], v[86:89], v[146:149], v[10:13]
	v_mfma_f32_16x16x32_bf16 v[6:9], v[90:93], v[146:149], v[6:9]
	v_mfma_f32_16x16x32_bf16 v[2:5], v[94:97], v[146:149], v[2:5]
	global_load_lds_dwordx4 v157, s[2:3]
	s_add_u32 s2, s2, 0x80
	s_addc_u32 s3, s3, 0
	s_add_u32 s6, s6, 0x80
	s_addc_u32 s7, s7, 0
	s_waitcnt vmcnt(0) lgkmcnt(0)
	s_barrier
	ds_read_b128 v[66:69], v190 offset:49152
	ds_read_b128 v[70:73], v190 offset:51200
	ds_read_b128 v[74:77], v190 offset:53248
	ds_read_b128 v[78:81], v190 offset:55296
	ds_read_b128 v[142:145], v188 offset:32768
	ds_read_b128 v[146:149], v188 offset:34816
	s_add_u32 m0, s8, 0x4000
	s_waitcnt lgkmcnt(1)
	v_mfma_f32_16x16x32_bf16 v[62:65], v[66:69], v[142:145], v[62:65]
	v_mfma_f32_16x16x32_bf16 v[58:61], v[70:73], v[142:145], v[58:61]
	v_mfma_f32_16x16x32_bf16 v[54:57], v[74:77], v[142:145], v[54:57]
	v_mfma_f32_16x16x32_bf16 v[50:53], v[78:81], v[142:145], v[50:53]
	ds_read_b128 v[150:153], v188 offset:36864
	ds_read_b128 v[82:85], v191 offset:49152
	ds_read_b128 v[86:89], v191 offset:51200
	ds_read_b128 v[90:93], v191 offset:53248
	ds_read_b128 v[94:97], v191 offset:55296
	global_load_lds_dwordx4 v158, s[6:7]
	s_add_u32 m0, s8, 0x5000
	s_waitcnt lgkmcnt(5)
	v_mfma_f32_16x16x32_bf16 v[46:49], v[66:69], v[146:149], v[46:49]
	v_mfma_f32_16x16x32_bf16 v[42:45], v[70:73], v[146:149], v[42:45]
	v_mfma_f32_16x16x32_bf16 v[38:41], v[74:77], v[146:149], v[38:41]
	v_mfma_f32_16x16x32_bf16 v[34:37], v[78:81], v[146:149], v[34:37]
	ds_read_b128 v[142:145], v188 offset:38912
	global_load_lds_dwordx4 v159, s[6:7]
	s_add_u32 m0, s8, 0x6000
	s_waitcnt lgkmcnt(5)
	v_mfma_f32_16x16x32_bf16 v[30:33], v[66:69], v[150:153], v[30:33]
	v_mfma_f32_16x16x32_bf16 v[26:29], v[70:73], v[150:153], v[26:29]
	v_mfma_f32_16x16x32_bf16 v[22:25], v[74:77], v[150:153], v[22:25]
	v_mfma_f32_16x16x32_bf16 v[18:21], v[78:81], v[150:153], v[18:21]
	ds_read_b128 v[146:149], v189 offset:32768
	global_load_lds_dwordx4 v160, s[6:7]
	s_add_u32 m0, s8, 0x7000
	s_waitcnt lgkmcnt(1)
	v_mfma_f32_16x16x32_bf16 v[14:17], v[66:69], v[142:145], v[14:17]
	v_mfma_f32_16x16x32_bf16 v[10:13], v[70:73], v[142:145], v[10:13]
	v_mfma_f32_16x16x32_bf16 v[6:9], v[74:77], v[142:145], v[6:9]
	v_mfma_f32_16x16x32_bf16 v[2:5], v[78:81], v[142:145], v[2:5]
	ds_read_b128 v[150:153], v189 offset:34816
	global_load_lds_dwordx4 v161, s[6:7]
	s_mov_b32 m0, s8
	s_waitcnt lgkmcnt(1)
	v_mfma_f32_16x16x32_bf16 v[62:65], v[82:85], v[146:149], v[62:65]
	v_mfma_f32_16x16x32_bf16 v[58:61], v[86:89], v[146:149], v[58:61]
	v_mfma_f32_16x16x32_bf16 v[54:57], v[90:93], v[146:149], v[54:57]
	v_mfma_f32_16x16x32_bf16 v[50:53], v[94:97], v[146:149], v[50:53]
	ds_read_b128 v[142:145], v189 offset:36864
	global_load_lds_dwordx4 v154, s[2:3]
	s_add_u32 m0, s8, 0x1000
	s_waitcnt lgkmcnt(1)
	v_mfma_f32_16x16x32_bf16 v[46:49], v[82:85], v[150:153], v[46:49]
	v_mfma_f32_16x16x32_bf16 v[42:45], v[86:89], v[150:153], v[42:45]
	v_mfma_f32_16x16x32_bf16 v[38:41], v[90:93], v[150:153], v[38:41]
	v_mfma_f32_16x16x32_bf16 v[34:37], v[94:97], v[150:153], v[34:37]
	ds_read_b128 v[146:149], v189 offset:38912
	global_load_lds_dwordx4 v155, s[2:3]
	s_add_u32 m0, s8, 0x2000
	s_waitcnt lgkmcnt(1)
	v_mfma_f32_16x16x32_bf16 v[30:33], v[82:85], v[142:145], v[30:33]
	v_mfma_f32_16x16x32_bf16 v[26:29], v[86:89], v[142:145], v[26:29]
	v_mfma_f32_16x16x32_bf16 v[22:25], v[90:93], v[142:145], v[22:25]
	v_mfma_f32_16x16x32_bf16 v[18:21], v[94:97], v[142:145], v[18:21]
	global_load_lds_dwordx4 v156, s[2:3]
	s_add_u32 m0, s8, 0x3000
	s_waitcnt lgkmcnt(0)
	v_mfma_f32_16x16x32_bf16 v[14:17], v[82:85], v[146:149], v[14:17]
	v_mfma_f32_16x16x32_bf16 v[10:13], v[86:89], v[146:149], v[10:13]
	v_mfma_f32_16x16x32_bf16 v[6:9], v[90:93], v[146:149], v[6:9]
	v_mfma_f32_16x16x32_bf16 v[2:5], v[94:97], v[146:149], v[2:5]
	global_load_lds_dwordx4 v157, s[2:3]
	s_add_u32 s2, s2, 0x80
	s_addc_u32 s3, s3, 0
	s_add_u32 s6, s6, 0x80
	s_addc_u32 s7, s7, 0
	s_waitcnt vmcnt(0) lgkmcnt(0)
	s_barrier
	s_movk_i32 s9, 2
.Lm3_loop:
	ds_read_b128 v[66:69], v190 offset:16384
	ds_read_b128 v[70:73], v190 offset:18432
	ds_read_b128 v[74:77], v190 offset:20480
	ds_read_b128 v[78:81], v190 offset:22528
	ds_read_b128 v[142:145], v188
	ds_read_b128 v[146:149], v188 offset:2048
	s_add_u32 m0, s8, 0xc000
	s_waitcnt lgkmcnt(1)
	v_mfma_f32_16x16x32_bf16 v[62:65], v[66:69], v[142:145], v[62:65]
	v_mfma_f32_16x16x32_bf16 v[58:61], v[70:73], v[142:145], v[58:61]
	v_mfma_f32_16x16x32_bf16 v[54:57], v[74:77], v[142:145], v[54:57]
	v_mfma_f32_16x16x32_bf16 v[50:53], v[78:81], v[142:145], v[50:53]
	ds_read_b128 v[150:153], v188 offset:4096
	ds_read_b128 v[82:85], v191 offset:16384
	ds_read_b128 v[86:89], v191 offset:18432
	ds_read_b128 v[90:93], v191 offset:20480
	ds_read_b128 v[94:97], v191 offset:22528
	global_load_lds_dwordx4 v158, s[6:7]
	s_add_u32 m0, s8, 0xd000
	s_waitcnt lgkmcnt(5)
	v_mfma_f32_16x16x32_bf16 v[46:49], v[66:69], v[146:149], v[46:49]
	v_mfma_f32_16x16x32_bf16 v[42:45], v[70:73], v[146:149], v[42:45]
	v_mfma_f32_16x16x32_bf16 v[38:41], v[74:77], v[146:149], v[38:41]
	v_mfma_f32_16x16x32_bf16 v[34:37], v[78:81], v[146:149], v[34:37]
	ds_read_b128 v[142:145], v188 offset:6144
	global_load_lds_dwordx4 v159, s[6:7]
	s_add_u32 m0, s8, 0xe000
	s_waitcnt lgkmcnt(5)
	v_mfma_f32_16x16x32_bf16 v[30:33], v[66:69], v[150:153], v[30:33]
	v_mfma_f32_16x16x32_bf16 v[26:29], v[70:73], v[150:153], v[26:29]
	v_mfma_f32_16x16x32_bf16 v[22:25], v[74:77], v[150:153], v[22:25]
	v_mfma_f32_16x16x32_bf16 v[18:21], v[78:81], v[150:153], v[18:21]
	ds_read_b128 v[146:149], v189
	global_load_lds_dwordx4 v160, s[6:7]
	s_add_u32 m0, s8, 0xf000
	s_waitcnt lgkmcnt(1)
	v_mfma_f32_16x16x32_bf16 v[14:17], v[66:69], v[142:145], v[14:17]
	v_mfma_f32_16x16x32_bf16 v[10:13], v[70:73], v[142:145], v[10:13]
	v_mfma_f32_16x16x32_bf16 v[6:9], v[74:77], v[142:145], v[6:9]
	v_mfma_f32_16x16x32_bf16 v[2:5], v[78:81], v[142:145], v[2:5]
	ds_read_b128 v[150:153], v189 offset:2048
	global_load_lds_dwordx4 v161, s[6:7]
	s_add_u32 m0, s8, 0x8000
	s_waitcnt lgkmcnt(1)
	v_mfma_f32_16x16x32_bf16 v[62:65], v[82:85], v[146:149], v[62:65]
	v_mfma_f32_16x16x32_bf16 v[58:61], v[86:89], v[146:149], v[58:61]
	v_mfma_f32_16x16x32_bf16 v[54:57], v[90:93], v[146:149], v[54:57]
	v_mfma_f32_16x16x32_bf16 v[50:53], v[94:97], v[146:149], v[50:53]
	ds_read_b128 v[142:145], v189 offset:4096
	global_load_lds_dwordx4 v154, s[2:3]
	s_add_u32 m0, s8, 0x9000
	s_waitcnt lgkmcnt(1)
	v_mfma_f32_16x16x32_bf16 v[46:49], v[82:85], v[150:153], v[46:49]
	v_mfma_f32_16x16x32_bf16 v[42:45], v[86:89], v[150:153], v[42:45]
	v_mfma_f32_16x16x32_bf16 v[38:41], v[90:93], v[150:153], v[38:41]
	v_mfma_f32_16x16x32_bf16 v[34:37], v[94:97], v[150:153], v[34:37]
	ds_read_b128 v[146:149], v189 offset:6144
	global_load_lds_dwordx4 v155, s[2:3]
	s_add_u32 m0, s8, 0xa000
	s_waitcnt lgkmcnt(1)
	v_mfma_f32_16x16x32_bf16 v[30:33], v[82:85], v[142:145], v[30:33]
	v_mfma_f32_16x16x32_bf16 v[26:29], v[86:89], v[142:145], v[26:29]
	v_mfma_f32_16x16x32_bf16 v[22:25], v[90:93], v[142:145], v[22:25]
	v_mfma_f32_16x16x32_bf16 v[18:21], v[94:97], v[142:145], v[18:21]
	global_load_lds_dwordx4 v156, s[2:3]
	s_add_u32 m0, s8, 0xb000
	s_waitcnt lgkmcnt(0)
	v_mfma_f32_16x16x32_bf16 v[14:17], v[82:85], v[146:149], v[14:17]
	v_mfma_f32_16x16x32_bf16 v[10:13], v[86:89], v[146:149], v[10:13]
	v_mfma_f32_16x16x32_bf16 v[6:9], v[90:93], v[146:149], v[6:9]
	v_mfma_f32_16x16x32_bf16 v[2:5], v[94:97], v[146:149], v[2:5]
	global_load_lds_dwordx4 v157, s[2:3]
	s_add_u32 s2, s2, 0x80
	s_addc_u32 s3, s3, 0
	s_add_u32 s6, s6, 0x80
	s_addc_u32 s7, s7, 0
	s_waitcnt vmcnt(0) lgkmcnt(0)
	s_barrier
	ds_read_b128 v[66:69], v190 offset:49152
	ds_read_b128 v[70:73], v190 offset:51200
	ds_read_b128 v[74:77], v190 offset:53248
	ds_read_b128 v[78:81], v190 offset:55296
	ds_read_b128 v[142:145], v188 offset:32768
	ds_read_b128 v[146:149], v188 offset:34816
	s_add_u32 m0, s8, 0x4000
	s_waitcnt lgkmcnt(1)
	v_mfma_f32_16x16x32_bf16 v[62:65], v[66:69], v[142:145], v[62:65]
	v_mfma_f32_16x16x32_bf16 v[58:61], v[70:73], v[142:145], v[58:61]
	v_mfma_f32_16x16x32_bf16 v[54:57], v[74:77], v[142:145], v[54:57]
	v_mfma_f32_16x16x32_bf16 v[50:53], v[78:81], v[142:145], v[50:53]
	ds_read_b128 v[150:153], v188 offset:36864
	ds_read_b128 v[82:85], v191 offset:49152
	ds_read_b128 v[86:89], v191 offset:51200
	ds_read_b128 v[90:93], v191 offset:53248
	ds_read_b128 v[94:97], v191 offset:55296
	global_load_lds_dwordx4 v158, s[6:7]
	s_add_u32 m0, s8, 0x5000
	s_waitcnt lgkmcnt(5)
	v_mfma_f32_16x16x32_bf16 v[46:49], v[66:69], v[146:149], v[46:49]
	v_mfma_f32_16x16x32_bf16 v[42:45], v[70:73], v[146:149], v[42:45]
	v_mfma_f32_16x16x32_bf16 v[38:41], v[74:77], v[146:149], v[38:41]
	v_mfma_f32_16x16x32_bf16 v[34:37], v[78:81], v[146:149], v[34:37]
	ds_read_b128 v[142:145], v188 offset:38912
	global_load_lds_dwordx4 v159, s[6:7]
	s_add_u32 m0, s8, 0x6000
	s_waitcnt lgkmcnt(5)
	v_mfma_f32_16x16x32_bf16 v[30:33], v[66:69], v[150:153], v[30:33]
	v_mfma_f32_16x16x32_bf16 v[26:29], v[70:73], v[150:153], v[26:29]
	v_mfma_f32_16x16x32_bf16 v[22:25], v[74:77], v[150:153], v[22:25]
	v_mfma_f32_16x16x32_bf16 v[18:21], v[78:81], v[150:153], v[18:21]
	ds_read_b128 v[146:149], v189 offset:32768
	global_load_lds_dwordx4 v160, s[6:7]
	s_add_u32 m0, s8, 0x7000
	s_waitcnt lgkmcnt(1)
	v_mfma_f32_16x16x32_bf16 v[14:17], v[66:69], v[142:145], v[14:17]
	v_mfma_f32_16x16x32_bf16 v[10:13], v[70:73], v[142:145], v[10:13]
	v_mfma_f32_16x16x32_bf16 v[6:9], v[74:77], v[142:145], v[6:9]
	v_mfma_f32_16x16x32_bf16 v[2:5], v[78:81], v[142:145], v[2:5]
	ds_read_b128 v[150:153], v189 offset:34816
	global_load_lds_dwordx4 v161, s[6:7]
	s_mov_b32 m0, s8
	s_waitcnt lgkmcnt(1)
	v_mfma_f32_16x16x32_bf16 v[62:65], v[82:85], v[146:149], v[62:65]
	v_mfma_f32_16x16x32_bf16 v[58:61], v[86:89], v[146:149], v[58:61]
	v_mfma_f32_16x16x32_bf16 v[54:57], v[90:93], v[146:149], v[54:57]
	v_mfma_f32_16x16x32_bf16 v[50:53], v[94:97], v[146:149], v[50:53]
	ds_read_b128 v[142:145], v189 offset:36864
	global_load_lds_dwordx4 v154, s[2:3]
	s_add_u32 m0, s8, 0x1000
	s_waitcnt lgkmcnt(1)
	v_mfma_f32_16x16x32_bf16 v[46:49], v[82:85], v[150:153], v[46:49]
	v_mfma_f32_16x16x32_bf16 v[42:45], v[86:89], v[150:153], v[42:45]
	v_mfma_f32_16x16x32_bf16 v[38:41], v[90:93], v[150:153], v[38:41]
	v_mfma_f32_16x16x32_bf16 v[34:37], v[94:97], v[150:153], v[34:37]
	ds_read_b128 v[146:149], v189 offset:38912
	global_load_lds_dwordx4 v155, s[2:3]
	s_add_u32 m0, s8, 0x2000
	s_waitcnt lgkmcnt(1)
	v_mfma_f32_16x16x32_bf16 v[30:33], v[82:85], v[142:145], v[30:33]
	v_mfma_f32_16x16x32_bf16 v[26:29], v[86:89], v[142:145], v[26:29]
	v_mfma_f32_16x16x32_bf16 v[22:25], v[90:93], v[142:145], v[22:25]
	v_mfma_f32_16x16x32_bf16 v[18:21], v[94:97], v[142:145], v[18:21]
	global_load_lds_dwordx4 v156, s[2:3]
	s_add_u32 m0, s8, 0x3000
	s_waitcnt lgkmcnt(0)
	v_mfma_f32_16x16x32_bf16 v[14:17], v[82:85], v[146:149], v[14:17]
	v_mfma_f32_16x16x32_bf16 v[10:13], v[86:89], v[146:149], v[10:13]
	v_mfma_f32_16x16x32_bf16 v[6:9], v[90:93], v[146:149], v[6:9]
	v_mfma_f32_16x16x32_bf16 v[2:5], v[94:97], v[146:149], v[2:5]
	global_load_lds_dwordx4 v157, s[2:3]
	s_add_u32 s2, s2, 0x80
	s_addc_u32 s3, s3, 0
	s_add_u32 s6, s6, 0x80
	s_addc_u32 s7, s7, 0
	s_add_i32 s9, s9, -1
	s_waitcnt vmcnt(0) lgkmcnt(0)
	s_barrier
	s_cmp_lg_u32 s9, 0
	s_cbranch_scc1 .Lm3_loop
	ds_read_b128 v[66:69], v190 offset:16384
	ds_read_b128 v[70:73], v190 offset:18432
	ds_read_b128 v[74:77], v190 offset:20480
	ds_read_b128 v[78:81], v190 offset:22528
	ds_read_b128 v[142:145], v188
	ds_read_b128 v[146:149], v188 offset:2048
	s_add_u32 m0, s8, 0xc000
	s_waitcnt lgkmcnt(1)
	v_mfma_f32_16x16x32_bf16 v[62:65], v[66:69], v[142:145], v[62:65]
	v_mfma_f32_16x16x32_bf16 v[58:61], v[70:73], v[142:145], v[58:61]
	v_mfma_f32_16x16x32_bf16 v[54:57], v[74:77], v[142:145], v[54:57]
	v_mfma_f32_16x16x32_bf16 v[50:53], v[78:81], v[142:145], v[50:53]
	ds_read_b128 v[150:153], v188 offset:4096
	ds_read_b128 v[82:85], v191 offset:16384
	ds_read_b128 v[86:89], v191 offset:18432
	ds_read_b128 v[90:93], v191 offset:20480
	ds_read_b128 v[94:97], v191 offset:22528
	global_load_lds_dwordx4 v158, s[6:7]
	s_add_u32 m0, s8, 0xd000
	s_waitcnt lgkmcnt(5)
	v_mfma_f32_16x16x32_bf16 v[46:49], v[66:69], v[146:149], v[46:49]
	v_mfma_f32_16x16x32_bf16 v[42:45], v[70:73], v[146:149], v[42:45]
	v_mfma_f32_16x16x32_bf16 v[38:41], v[74:77], v[146:149], v[38:41]
	v_mfma_f32_16x16x32_bf16 v[34:37], v[78:81], v[146:149], v[34:37]
	ds_read_b128 v[142:145], v188 offset:6144
	global_load_lds_dwordx4 v159, s[6:7]
	s_add_u32 m0, s8, 0xe000
	s_waitcnt lgkmcnt(5)
	v_mfma_f32_16x16x32_bf16 v[30:33], v[66:69], v[150:153], v[30:33]
	v_mfma_f32_16x16x32_bf16 v[26:29], v[70:73], v[150:153], v[26:29]
	v_mfma_f32_16x16x32_bf16 v[22:25], v[74:77], v[150:153], v[22:25]
	v_mfma_f32_16x16x32_bf16 v[18:21], v[78:81], v[150:153], v[18:21]
	ds_read_b128 v[146:149], v189
	global_load_lds_dwordx4 v160, s[6:7]
	s_add_u32 m0, s8, 0xf000
	s_waitcnt lgkmcnt(1)
	v_mfma_f32_16x16x32_bf16 v[14:17], v[66:69], v[142:145], v[14:17]
	v_mfma_f32_16x16x32_bf16 v[10:13], v[70:73], v[142:145], v[10:13]
	v_mfma_f32_16x16x32_bf16 v[6:9], v[74:77], v[142:145], v[6:9]
	v_mfma_f32_16x16x32_bf16 v[2:5], v[78:81], v[142:145], v[2:5]
	ds_read_b128 v[150:153], v189 offset:2048
	global_load_lds_dwordx4 v161, s[6:7]
	s_add_u32 m0, s8, 0x8000
	s_waitcnt lgkmcnt(1)
	v_mfma_f32_16x16x32_bf16 v[62:65], v[82:85], v[146:149], v[62:65]
	v_mfma_f32_16x16x32_bf16 v[58:61], v[86:89], v[146:149], v[58:61]
	v_mfma_f32_16x16x32_bf16 v[54:57], v[90:93], v[146:149], v[54:57]
	v_mfma_f32_16x16x32_bf16 v[50:53], v[94:97], v[146:149], v[50:53]
	ds_read_b128 v[142:145], v189 offset:4096
	global_load_lds_dwordx4 v154, s[2:3]
	s_add_u32 m0, s8, 0x9000
	s_waitcnt lgkmcnt(1)
	v_mfma_f32_16x16x32_bf16 v[46:49], v[82:85], v[150:153], v[46:49]
	v_mfma_f32_16x16x32_bf16 v[42:45], v[86:89], v[150:153], v[42:45]
	v_mfma_f32_16x16x32_bf16 v[38:41], v[90:93], v[150:153], v[38:41]
	v_mfma_f32_16x16x32_bf16 v[34:37], v[94:97], v[150:153], v[34:37]
	ds_read_b128 v[146:149], v189 offset:6144
	global_load_lds_dwordx4 v155, s[2:3]
	s_add_u32 m0, s8, 0xa000
	s_waitcnt lgkmcnt(1)
	v_mfma_f32_16x16x32_bf16 v[30:33], v[82:85], v[142:145], v[30:33]
	v_mfma_f32_16x16x32_bf16 v[26:29], v[86:89], v[142:145], v[26:29]
	v_mfma_f32_16x16x32_bf16 v[22:25], v[90:93], v[142:145], v[22:25]
	v_mfma_f32_16x16x32_bf16 v[18:21], v[94:97], v[142:145], v[18:21]
	global_load_lds_dwordx4 v156, s[2:3]
	s_add_u32 m0, s8, 0xb000
	s_waitcnt lgkmcnt(0)
	v_mfma_f32_16x16x32_bf16 v[14:17], v[82:85], v[146:149], v[14:17]
	v_mfma_f32_16x16x32_bf16 v[10:13], v[86:89], v[146:149], v[10:13]
	v_mfma_f32_16x16x32_bf16 v[6:9], v[90:93], v[146:149], v[6:9]
	v_mfma_f32_16x16x32_bf16 v[2:5], v[94:97], v[146:149], v[2:5]
	global_load_lds_dwordx4 v157, s[2:3]
	s_add_u32 s2, s2, 0x80
	s_addc_u32 s3, s3, 0
	s_add_u32 s6, s6, 0x80
	s_addc_u32 s7, s7, 0
	s_waitcnt vmcnt(0) lgkmcnt(0)
	s_barrier
	ds_read_b128 v[66:69], v190 offset:49152
	ds_read_b128 v[70:73], v190 offset:51200
	ds_read_b128 v[74:77], v190 offset:53248
	ds_read_b128 v[78:81], v190 offset:55296
	ds_read_b128 v[142:145], v188 offset:32768
	ds_read_b128 v[146:149], v188 offset:34816
	s_waitcnt lgkmcnt(1)
	v_mfma_f32_16x16x32_bf16 v[62:65], v[66:69], v[142:145], v[62:65]
	v_mfma_f32_16x16x32_bf16 v[58:61], v[70:73], v[142:145], v[58:61]
	v_mfma_f32_16x16x32_bf16 v[54:57], v[74:77], v[142:145], v[54:57]
	v_mfma_f32_16x16x32_bf16 v[50:53], v[78:81], v[142:145], v[50:53]
	ds_read_b128 v[150:153], v188 offset:36864
	ds_read_b128 v[82:85], v191 offset:49152
	ds_read_b128 v[86:89], v191 offset:51200
	ds_read_b128 v[90:93], v191 offset:53248
	ds_read_b128 v[94:97], v191 offset:55296
	s_waitcnt lgkmcnt(5)
	v_mfma_f32_16x16x32_bf16 v[46:49], v[66:69], v[146:149], v[46:49]
	v_mfma_f32_16x16x32_bf16 v[42:45], v[70:73], v[146:149], v[42:45]
	v_mfma_f32_16x16x32_bf16 v[38:41], v[74:77], v[146:149], v[38:41]
	v_mfma_f32_16x16x32_bf16 v[34:37], v[78:81], v[146:149], v[34:37]
	ds_read_b128 v[142:145], v188 offset:38912
	s_waitcnt lgkmcnt(5)
	v_mfma_f32_16x16x32_bf16 v[30:33], v[66:69], v[150:153], v[30:33]
	v_mfma_f32_16x16x32_bf16 v[26:29], v[70:73], v[150:153], v[26:29]
	v_mfma_f32_16x16x32_bf16 v[22:25], v[74:77], v[150:153], v[22:25]
	v_mfma_f32_16x16x32_bf16 v[18:21], v[78:81], v[150:153], v[18:21]
	ds_read_b128 v[146:149], v189 offset:32768
	s_waitcnt lgkmcnt(1)
	v_mfma_f32_16x16x32_bf16 v[14:17], v[66:69], v[142:145], v[14:17]
	v_mfma_f32_16x16x32_bf16 v[10:13], v[70:73], v[142:145], v[10:13]
	v_mfma_f32_16x16x32_bf16 v[6:9], v[74:77], v[142:145], v[6:9]
	v_mfma_f32_16x16x32_bf16 v[2:5], v[78:81], v[142:145], v[2:5]
	ds_read_b128 v[150:153], v189 offset:34816
	s_waitcnt lgkmcnt(1)
	v_mfma_f32_16x16x32_bf16 v[62:65], v[82:85], v[146:149], v[62:65]
	v_mfma_f32_16x16x32_bf16 v[58:61], v[86:89], v[146:149], v[58:61]
	v_mfma_f32_16x16x32_bf16 v[54:57], v[90:93], v[146:149], v[54:57]
	v_mfma_f32_16x16x32_bf16 v[50:53], v[94:97], v[146:149], v[50:53]
	ds_read_b128 v[142:145], v189 offset:36864
	s_waitcnt lgkmcnt(1)
	v_mfma_f32_16x16x32_bf16 v[46:49], v[82:85], v[150:153], v[46:49]
	v_mfma_f32_16x16x32_bf16 v[42:45], v[86:89], v[150:153], v[42:45]
	v_mfma_f32_16x16x32_bf16 v[38:41], v[90:93], v[150:153], v[38:41]
	v_mfma_f32_16x16x32_bf16 v[34:37], v[94:97], v[150:153], v[34:37]
	ds_read_b128 v[146:149], v189 offset:38912
	s_waitcnt lgkmcnt(1)
	v_mfma_f32_16x16x32_bf16 v[30:33], v[82:85], v[142:145], v[30:33]
	v_mfma_f32_16x16x32_bf16 v[26:29], v[86:89], v[142:145], v[26:29]
	v_mfma_f32_16x16x32_bf16 v[22:25], v[90:93], v[142:145], v[22:25]
	v_mfma_f32_16x16x32_bf16 v[18:21], v[94:97], v[142:145], v[18:21]
	s_waitcnt lgkmcnt(0)
	v_mfma_f32_16x16x32_bf16 v[14:17], v[82:85], v[146:149], v[14:17]
	v_mfma_f32_16x16x32_bf16 v[10:13], v[86:89], v[146:149], v[10:13]
	v_mfma_f32_16x16x32_bf16 v[6:9], v[90:93], v[146:149], v[6:9]
	v_mfma_f32_16x16x32_bf16 v[2:5], v[94:97], v[146:149], v[2:5]
	s_waitcnt lgkmcnt(0)
	s_barrier
	s_nop 7
	s_nop 2
	s_movk_i32 s92, 0x480
	s_branch .LBB0_111

.LBB0_273:
	v_mov_b32_e32 v0, v163
	s_bfe_u32 s7, s3, 0x30002
	v_mov_b64_e32 v[4:5], s[78:79]
	v_ashrrev_i32_e32 v2, 4, v0
	v_lshl_add_u32 v2, s7, 6, v2
	v_ashrrev_i32_e32 v3, 31, v2
	v_lshlrev_b64 v[2:3], 5, v[2:3]
	v_or_b32_e32 v2, s0, v2
	s_ashr_i32 s4, s3, 6
	s_bfe_u32 s5, s3, 0x10005
	v_mad_u64_u32 v[4:5], s[8:9], v2, s93, v[4:5]
	s_cmp_lt_u32 s3, 64
	s_movk_i32 s8, 0x1400
	s_mul_i32 s9, s4, 0x108000
	s_cselect_b32 s40, s8, 0x1500
	s_mul_hi_i32 s8, s4, 0x108000
	s_add_u32 s9, s76, s9
	s_addc_u32 s8, s77, s8
	s_mul_i32 s10, s5, 0x84000
	v_mad_i32_i24 v5, v3, s93, v5
	s_add_u32 s9, s9, s10
	v_lshl_add_u64 v[2:3], v[4:5], 0, s[40:41]
	v_lshlrev_b32_e32 v4, 4, v0
	s_addc_u32 s10, s8, 0
	v_and_b32_e32 v0, 0x80, v4
	s_add_u32 s8, s9, s2
	v_lshl_add_u64 v[2:3], v[2:3], 0, v[0:1]
	v_and_b32_e32 v0, 0x70, v4
	s_addc_u32 s9, s10, 0
	v_mov_b32_e32 v30, v163
	v_lshl_add_u64 v[130:131], v[2:3], 0, v[0:1]
	v_mov_b64_e32 v[2:3], s[8:9]
	v_ashrrev_i32_e32 v31, 3, v30
	s_movk_i32 s8, 0x1080
	v_lshlrev_b32_e32 v0, 4, v30
	v_mad_i64_i32 v[2:3], s[8:9], v31, s8, v[2:3]
	v_and_b32_e32 v0, 0x70, v0
	s_mov_b32 s15, 0x660000
	v_lshl_add_u64 v[132:133], v[2:3], 0, v[0:1]
	v_and_b32_e32 v110, 7, v163
	v_bfe_u32 v111, v163, 4, 3
	v_xor_b32_e32 v111, v111, v110
	v_sub_u32_e32 v111, v111, v110
	v_lshlrev_b32_e32 v111, 4, v111
	v_lshrrev_b32_e32 v112, 6, v163
	v_lshlrev_b32_e32 v112, 10, v112
	v_readfirstlane_b32 s8, v130
	v_readfirstlane_b32 s9, v131
	v_readfirstlane_b32 s10, v132
	v_readfirstlane_b32 s11, v133
	v_readfirstlane_b32 s12, v112
	s_nop 3
	v_subrev_u32_e32 v98, s8, v130
	v_subrev_u32_e32 v102, s10, v132
	v_add_u32_e32 v98, v98, v111
	v_add_u32_e32 v102, v102, v111
	v_add_u32_e32 v99, 0x660000, v98
	v_add_u32_e32 v103, 0x21000, v102
	v_add_u32_e32 v100, 0xcc0000, v98
	v_add_u32_e32 v104, 0x42000, v102
	v_add_u32_e32 v101, 0x1320000, v98
	v_add_u32_e32 v105, 0x63000, v102
	v_lshlrev_b32_e32 v110, 3, v163
	v_lshlrev_b32_e32 v111, 7, v163
	v_and_b32_e32 v112, 0x2000, v111
	v_and_b32_e32 v111, 0x780, v111
	v_and_b32_e32 v107, 64, v110
	v_xor_b32_e32 v110, v110, v163
	v_and_b32_e32 v110, 48, v110
	v_or3_b32 v110, v111, v107, v110
	v_lshlrev_b32_e32 v111, 6, v163
	v_and_b32_e32 v111, 0xffffe000, v111
	v_or_b32_e32 v108, v110, v112
	v_or_b32_e32 v106, v110, v111
	v_xor_b32_e32 v107, 64, v106
	v_xor_b32_e32 v109, 64, v108
	s_add_u32 m0, s12, 0x4000
	s_nop 0
	global_load_lds_dwordx4 v102, s[10:11]
	s_add_u32 m0, s12, 0x5000
	s_nop 0
	global_load_lds_dwordx4 v103, s[10:11]
	s_add_u32 m0, s12, 0x6000
	s_nop 0
	global_load_lds_dwordx4 v104, s[10:11]
	s_add_u32 m0, s12, 0x7000
	s_nop 0
	global_load_lds_dwordx4 v105, s[10:11]
	s_mov_b32 m0, s12
	s_nop 0
	global_load_lds_dwordx4 v98, s[8:9]
	s_add_u32 m0, s12, 0x1000
	s_nop 0
	global_load_lds_dwordx4 v99, s[8:9]
	s_add_u32 m0, s12, 0x2000
	s_nop 0
	global_load_lds_dwordx4 v100, s[8:9]
	s_add_u32 m0, s12, 0x3000
	s_nop 0
	global_load_lds_dwordx4 v101, s[8:9]
	s_waitcnt vmcnt(0)
	s_add_u32 s8, s8, 0x3300
	s_addc_u32 s9, s9, 0
	s_add_u32 s10, s10, 0x80
	s_addc_u32 s11, s11, 0
	s_barrier
	s_add_u32 m0, s12, 0xc000
	ds_read_b128 v[138:141], v106
	ds_read_b128 v[154:157], v108 offset:16384
	s_nop 0
	global_load_lds_dwordx4 v102, s[10:11]
	s_add_u32 m0, s12, 0xd000
	ds_read_b128 v[158:161], v108 offset:18432
	ds_read_b128 v[182:185], v108 offset:20480
	s_nop 0
	global_load_lds_dwordx4 v103, s[10:11]
	s_add_u32 m0, s12, 0xe000
	ds_read_b128 v[186:189], v108 offset:22528
	ds_read_b128 v[142:145], v106 offset:2048
	s_nop 0
	global_load_lds_dwordx4 v104, s[10:11]
	s_add_u32 m0, s12, 0xf000
	ds_read_b128 v[146:149], v106 offset:4096
	ds_read_b128 v[150:153], v106 offset:6144
	s_nop 0
	global_load_lds_dwordx4 v105, s[10:11]
	s_add_u32 m0, s12, 0x8000
	s_nop 0
	global_load_lds_dwordx4 v98, s[8:9]
	s_add_u32 m0, s12, 0x9000
	s_nop 0
	global_load_lds_dwordx4 v99, s[8:9]
	s_add_u32 m0, s12, 0xa000
	s_nop 0
	global_load_lds_dwordx4 v100, s[8:9]
	s_add_u32 m0, s12, 0xb000
	s_nop 0
	global_load_lds_dwordx4 v101, s[8:9]
	s_add_u32 s8, s8, 0x3300
	s_addc_u32 s9, s9, 0
	s_add_u32 s10, s10, 0x80
	s_addc_u32 s11, s11, 0
	s_waitcnt lgkmcnt(0)
	v_mfma_f32_16x16x32_bf16 v[94:97], v[154:157], v[138:141], 0
	ds_read_b128 v[2:5], v107
	ds_read_b128 v[18:21], v109 offset:16384
	v_mfma_f32_16x16x32_bf16 v[90:93], v[158:161], v[138:141], 0
	v_mfma_f32_16x16x32_bf16 v[86:89], v[182:185], v[138:141], 0
	ds_read_b128 v[22:25], v109 offset:18432
	ds_read_b128 v[26:29], v109 offset:20480
	v_mfma_f32_16x16x32_bf16 v[82:85], v[186:189], v[138:141], 0
	v_mfma_f32_16x16x32_bf16 v[78:81], v[154:157], v[142:145], 0
	ds_read_b128 v[54:57], v109 offset:22528
	ds_read_b128 v[6:9], v107 offset:2048
	v_mfma_f32_16x16x32_bf16 v[70:73], v[158:161], v[142:145], 0
	v_mfma_f32_16x16x32_bf16 v[66:69], v[182:185], v[142:145], 0
	ds_read_b128 v[10:13], v107 offset:4096
	ds_read_b128 v[14:17], v107 offset:6144
	v_mfma_f32_16x16x32_bf16 v[62:65], v[186:189], v[142:145], 0
	v_mfma_f32_16x16x32_bf16 v[58:61], v[154:157], v[146:149], 0
	v_mfma_f32_16x16x32_bf16 v[50:53], v[158:161], v[146:149], 0
	v_mfma_f32_16x16x32_bf16 v[46:49], v[182:185], v[146:149], 0
	v_mfma_f32_16x16x32_bf16 v[42:45], v[186:189], v[146:149], 0
	v_mfma_f32_16x16x32_bf16 v[38:41], v[154:157], v[150:153], 0
	v_mfma_f32_16x16x32_bf16 v[34:37], v[158:161], v[150:153], 0
	v_mfma_f32_16x16x32_bf16 v[30:33], v[182:185], v[150:153], 0
	v_mfma_f32_16x16x32_bf16 v[74:77], v[186:189], v[150:153], 0
	s_waitcnt vmcnt(0) lgkmcnt(0)
	s_barrier
	s_movk_i32 s13, 3
.Lgc_loop:
	v_mfma_f32_16x16x32_bf16 v[94:97], v[18:21], v[2:5], v[94:97]
	s_add_u32 m0, s12, 0x4000
	ds_read_b128 v[138:141], v106 offset:32768
	ds_read_b128 v[154:157], v108 offset:49152
	v_mfma_f32_16x16x32_bf16 v[90:93], v[22:25], v[2:5], v[90:93]
	global_load_lds_dwordx4 v102, s[10:11]
	v_mfma_f32_16x16x32_bf16 v[86:89], v[26:29], v[2:5], v[86:89]
	s_add_u32 m0, s12, 0x5000
	ds_read_b128 v[158:161], v108 offset:51200
	ds_read_b128 v[182:185], v108 offset:53248
	v_mfma_f32_16x16x32_bf16 v[82:85], v[54:57], v[2:5], v[82:85]
	global_load_lds_dwordx4 v103, s[10:11]
	v_mfma_f32_16x16x32_bf16 v[78:81], v[18:21], v[6:9], v[78:81]
	s_add_u32 m0, s12, 0x6000
	ds_read_b128 v[186:189], v108 offset:55296
	ds_read_b128 v[142:145], v106 offset:34816
	v_mfma_f32_16x16x32_bf16 v[70:73], v[22:25], v[6:9], v[70:73]
	global_load_lds_dwordx4 v104, s[10:11]
	v_mfma_f32_16x16x32_bf16 v[66:69], v[26:29], v[6:9], v[66:69]
	s_add_u32 m0, s12, 0x7000
	ds_read_b128 v[146:149], v106 offset:36864
	ds_read_b128 v[150:153], v106 offset:38912
	v_mfma_f32_16x16x32_bf16 v[62:65], v[54:57], v[6:9], v[62:65]
	global_load_lds_dwordx4 v105, s[10:11]
	v_mfma_f32_16x16x32_bf16 v[58:61], v[18:21], v[10:13], v[58:61]
	s_mov_b32 m0, s12
	v_mfma_f32_16x16x32_bf16 v[50:53], v[22:25], v[10:13], v[50:53]
	global_load_lds_dwordx4 v98, s[8:9]
	v_mfma_f32_16x16x32_bf16 v[46:49], v[26:29], v[10:13], v[46:49]
	s_add_u32 m0, s12, 0x1000
	v_mfma_f32_16x16x32_bf16 v[42:45], v[54:57], v[10:13], v[42:45]
	global_load_lds_dwordx4 v99, s[8:9]
	v_mfma_f32_16x16x32_bf16 v[38:41], v[18:21], v[14:17], v[38:41]
	s_add_u32 m0, s12, 0x2000
	v_mfma_f32_16x16x32_bf16 v[34:37], v[22:25], v[14:17], v[34:37]
	global_load_lds_dwordx4 v100, s[8:9]
	v_mfma_f32_16x16x32_bf16 v[30:33], v[26:29], v[14:17], v[30:33]
	s_add_u32 m0, s12, 0x3000
	v_mfma_f32_16x16x32_bf16 v[74:77], v[54:57], v[14:17], v[74:77]
	global_load_lds_dwordx4 v101, s[8:9]
	s_add_u32 s8, s8, 0x3300
	s_addc_u32 s9, s9, 0
	s_add_u32 s10, s10, 0x80
	s_addc_u32 s11, s11, 0
	s_waitcnt lgkmcnt(0)
	v_mfma_f32_16x16x32_bf16 v[94:97], v[154:157], v[138:141], v[94:97]
	ds_read_b128 v[2:5], v107 offset:32768
	ds_read_b128 v[18:21], v109 offset:49152
	v_mfma_f32_16x16x32_bf16 v[90:93], v[158:161], v[138:141], v[90:93]
	v_mfma_f32_16x16x32_bf16 v[86:89], v[182:185], v[138:141], v[86:89]
	ds_read_b128 v[22:25], v109 offset:51200
	ds_read_b128 v[26:29], v109 offset:53248
	v_mfma_f32_16x16x32_bf16 v[82:85], v[186:189], v[138:141], v[82:85]
	v_mfma_f32_16x16x32_bf16 v[78:81], v[154:157], v[142:145], v[78:81]
	ds_read_b128 v[54:57], v109 offset:55296
	ds_read_b128 v[6:9], v107 offset:34816
	v_mfma_f32_16x16x32_bf16 v[70:73], v[158:161], v[142:145], v[70:73]
	v_mfma_f32_16x16x32_bf16 v[66:69], v[182:185], v[142:145], v[66:69]
	ds_read_b128 v[10:13], v107 offset:36864
	ds_read_b128 v[14:17], v107 offset:38912
	v_mfma_f32_16x16x32_bf16 v[62:65], v[186:189], v[142:145], v[62:65]
	v_mfma_f32_16x16x32_bf16 v[58:61], v[154:157], v[146:149], v[58:61]
	v_mfma_f32_16x16x32_bf16 v[50:53], v[158:161], v[146:149], v[50:53]
	v_mfma_f32_16x16x32_bf16 v[46:49], v[182:185], v[146:149], v[46:49]
	v_mfma_f32_16x16x32_bf16 v[42:45], v[186:189], v[146:149], v[42:45]
	v_mfma_f32_16x16x32_bf16 v[38:41], v[154:157], v[150:153], v[38:41]
	v_mfma_f32_16x16x32_bf16 v[34:37], v[158:161], v[150:153], v[34:37]
	v_mfma_f32_16x16x32_bf16 v[30:33], v[182:185], v[150:153], v[30:33]
	v_mfma_f32_16x16x32_bf16 v[74:77], v[186:189], v[150:153], v[74:77]
	s_waitcnt vmcnt(0) lgkmcnt(0)
	s_barrier
	v_mfma_f32_16x16x32_bf16 v[94:97], v[18:21], v[2:5], v[94:97]
	s_add_u32 m0, s12, 0xc000
	ds_read_b128 v[138:141], v106
	ds_read_b128 v[154:157], v108 offset:16384
	v_mfma_f32_16x16x32_bf16 v[90:93], v[22:25], v[2:5], v[90:93]
	global_load_lds_dwordx4 v102, s[10:11]
	v_mfma_f32_16x16x32_bf16 v[86:89], v[26:29], v[2:5], v[86:89]
	s_add_u32 m0, s12, 0xd000
	ds_read_b128 v[158:161], v108 offset:18432
	ds_read_b128 v[182:185], v108 offset:20480
	v_mfma_f32_16x16x32_bf16 v[82:85], v[54:57], v[2:5], v[82:85]
	global_load_lds_dwordx4 v103, s[10:11]
	v_mfma_f32_16x16x32_bf16 v[78:81], v[18:21], v[6:9], v[78:81]
	s_add_u32 m0, s12, 0xe000
	ds_read_b128 v[186:189], v108 offset:22528
	ds_read_b128 v[142:145], v106 offset:2048
	v_mfma_f32_16x16x32_bf16 v[70:73], v[22:25], v[6:9], v[70:73]
	global_load_lds_dwordx4 v104, s[10:11]
	v_mfma_f32_16x16x32_bf16 v[66:69], v[26:29], v[6:9], v[66:69]
	s_add_u32 m0, s12, 0xf000
	ds_read_b128 v[146:149], v106 offset:4096
	ds_read_b128 v[150:153], v106 offset:6144
	v_mfma_f32_16x16x32_bf16 v[62:65], v[54:57], v[6:9], v[62:65]
	global_load_lds_dwordx4 v105, s[10:11]
	v_mfma_f32_16x16x32_bf16 v[58:61], v[18:21], v[10:13], v[58:61]
	s_add_u32 m0, s12, 0x8000
	v_mfma_f32_16x16x32_bf16 v[50:53], v[22:25], v[10:13], v[50:53]
	global_load_lds_dwordx4 v98, s[8:9]
	v_mfma_f32_16x16x32_bf16 v[46:49], v[26:29], v[10:13], v[46:49]
	s_add_u32 m0, s12, 0x9000
	v_mfma_f32_16x16x32_bf16 v[42:45], v[54:57], v[10:13], v[42:45]
	global_load_lds_dwordx4 v99, s[8:9]
	v_mfma_f32_16x16x32_bf16 v[38:41], v[18:21], v[14:17], v[38:41]
	s_add_u32 m0, s12, 0xa000
	v_mfma_f32_16x16x32_bf16 v[34:37], v[22:25], v[14:17], v[34:37]
	global_load_lds_dwordx4 v100, s[8:9]
	v_mfma_f32_16x16x32_bf16 v[30:33], v[26:29], v[14:17], v[30:33]
	s_add_u32 m0, s12, 0xb000
	v_mfma_f32_16x16x32_bf16 v[74:77], v[54:57], v[14:17], v[74:77]
	global_load_lds_dwordx4 v101, s[8:9]
	s_add_u32 s8, s8, 0x3300
	s_addc_u32 s9, s9, 0
	s_add_u32 s10, s10, 0x80
	s_addc_u32 s11, s11, 0
	s_waitcnt lgkmcnt(0)
	v_mfma_f32_16x16x32_bf16 v[94:97], v[154:157], v[138:141], v[94:97]
	ds_read_b128 v[2:5], v107
	ds_read_b128 v[18:21], v109 offset:16384
	v_mfma_f32_16x16x32_bf16 v[90:93], v[158:161], v[138:141], v[90:93]
	v_mfma_f32_16x16x32_bf16 v[86:89], v[182:185], v[138:141], v[86:89]
	ds_read_b128 v[22:25], v109 offset:18432
	ds_read_b128 v[26:29], v109 offset:20480
	v_mfma_f32_16x16x32_bf16 v[82:85], v[186:189], v[138:141], v[82:85]
	v_mfma_f32_16x16x32_bf16 v[78:81], v[154:157], v[142:145], v[78:81]
	ds_read_b128 v[54:57], v109 offset:22528
	ds_read_b128 v[6:9], v107 offset:2048
	v_mfma_f32_16x16x32_bf16 v[70:73], v[158:161], v[142:145], v[70:73]
	v_mfma_f32_16x16x32_bf16 v[66:69], v[182:185], v[142:145], v[66:69]
	ds_read_b128 v[10:13], v107 offset:4096
	ds_read_b128 v[14:17], v107 offset:6144
	v_mfma_f32_16x16x32_bf16 v[62:65], v[186:189], v[142:145], v[62:65]
	v_mfma_f32_16x16x32_bf16 v[58:61], v[154:157], v[146:149], v[58:61]
	v_mfma_f32_16x16x32_bf16 v[50:53], v[158:161], v[146:149], v[50:53]
	v_mfma_f32_16x16x32_bf16 v[46:49], v[182:185], v[146:149], v[46:49]
	v_mfma_f32_16x16x32_bf16 v[42:45], v[186:189], v[146:149], v[42:45]
	v_mfma_f32_16x16x32_bf16 v[38:41], v[154:157], v[150:153], v[38:41]
	v_mfma_f32_16x16x32_bf16 v[34:37], v[158:161], v[150:153], v[34:37]
	v_mfma_f32_16x16x32_bf16 v[30:33], v[182:185], v[150:153], v[30:33]
	v_mfma_f32_16x16x32_bf16 v[74:77], v[186:189], v[150:153], v[74:77]
	s_add_i32 s13, s13, -1
	s_waitcnt vmcnt(0) lgkmcnt(0)
	s_barrier
	s_cmp_lg_u32 s13, 0
	s_cbranch_scc1 .Lgc_loop
	v_mfma_f32_16x16x32_bf16 v[94:97], v[18:21], v[2:5], v[94:97]
	ds_read_b128 v[138:141], v106 offset:32768
	ds_read_b128 v[154:157], v108 offset:49152
	v_mfma_f32_16x16x32_bf16 v[90:93], v[22:25], v[2:5], v[90:93]
	v_mfma_f32_16x16x32_bf16 v[86:89], v[26:29], v[2:5], v[86:89]
	ds_read_b128 v[158:161], v108 offset:51200
	ds_read_b128 v[182:185], v108 offset:53248
	v_mfma_f32_16x16x32_bf16 v[82:85], v[54:57], v[2:5], v[82:85]
	v_mfma_f32_16x16x32_bf16 v[78:81], v[18:21], v[6:9], v[78:81]
	ds_read_b128 v[186:189], v108 offset:55296
	ds_read_b128 v[142:145], v106 offset:34816
	v_mfma_f32_16x16x32_bf16 v[70:73], v[22:25], v[6:9], v[70:73]
	v_mfma_f32_16x16x32_bf16 v[66:69], v[26:29], v[6:9], v[66:69]
	ds_read_b128 v[146:149], v106 offset:36864
	ds_read_b128 v[150:153], v106 offset:38912
	v_mfma_f32_16x16x32_bf16 v[62:65], v[54:57], v[6:9], v[62:65]
	v_mfma_f32_16x16x32_bf16 v[58:61], v[18:21], v[10:13], v[58:61]
	v_mfma_f32_16x16x32_bf16 v[50:53], v[22:25], v[10:13], v[50:53]
	v_mfma_f32_16x16x32_bf16 v[46:49], v[26:29], v[10:13], v[46:49]
	v_mfma_f32_16x16x32_bf16 v[42:45], v[54:57], v[10:13], v[42:45]
	v_mfma_f32_16x16x32_bf16 v[38:41], v[18:21], v[14:17], v[38:41]
	v_mfma_f32_16x16x32_bf16 v[34:37], v[22:25], v[14:17], v[34:37]
	v_mfma_f32_16x16x32_bf16 v[30:33], v[26:29], v[14:17], v[30:33]
	v_mfma_f32_16x16x32_bf16 v[74:77], v[54:57], v[14:17], v[74:77]
	s_waitcnt lgkmcnt(0)
	v_mfma_f32_16x16x32_bf16 v[94:97], v[154:157], v[138:141], v[94:97]
	ds_read_b128 v[2:5], v107 offset:32768
	ds_read_b128 v[18:21], v109 offset:49152
	v_mfma_f32_16x16x32_bf16 v[90:93], v[158:161], v[138:141], v[90:93]
	v_mfma_f32_16x16x32_bf16 v[86:89], v[182:185], v[138:141], v[86:89]
	ds_read_b128 v[22:25], v109 offset:51200
	ds_read_b128 v[26:29], v109 offset:53248
	v_mfma_f32_16x16x32_bf16 v[82:85], v[186:189], v[138:141], v[82:85]
	v_mfma_f32_16x16x32_bf16 v[78:81], v[154:157], v[142:145], v[78:81]
	ds_read_b128 v[54:57], v109 offset:55296
	ds_read_b128 v[6:9], v107 offset:34816
	v_mfma_f32_16x16x32_bf16 v[70:73], v[158:161], v[142:145], v[70:73]
	v_mfma_f32_16x16x32_bf16 v[66:69], v[182:185], v[142:145], v[66:69]
	ds_read_b128 v[10:13], v107 offset:36864
	ds_read_b128 v[14:17], v107 offset:38912
	v_mfma_f32_16x16x32_bf16 v[62:65], v[186:189], v[142:145], v[62:65]
	v_mfma_f32_16x16x32_bf16 v[58:61], v[154:157], v[146:149], v[58:61]
	v_mfma_f32_16x16x32_bf16 v[50:53], v[158:161], v[146:149], v[50:53]
	v_mfma_f32_16x16x32_bf16 v[46:49], v[182:185], v[146:149], v[46:49]
	v_mfma_f32_16x16x32_bf16 v[42:45], v[186:189], v[146:149], v[42:45]
	v_mfma_f32_16x16x32_bf16 v[38:41], v[154:157], v[150:153], v[38:41]
	v_mfma_f32_16x16x32_bf16 v[34:37], v[158:161], v[150:153], v[34:37]
	v_mfma_f32_16x16x32_bf16 v[30:33], v[182:185], v[150:153], v[30:33]
	v_mfma_f32_16x16x32_bf16 v[74:77], v[186:189], v[150:153], v[74:77]
	s_waitcnt lgkmcnt(0)
	s_barrier
	v_mfma_f32_16x16x32_bf16 v[94:97], v[18:21], v[2:5], v[94:97]
	v_mfma_f32_16x16x32_bf16 v[90:93], v[22:25], v[2:5], v[90:93]
	v_mfma_f32_16x16x32_bf16 v[86:89], v[26:29], v[2:5], v[86:89]
	v_mfma_f32_16x16x32_bf16 v[82:85], v[54:57], v[2:5], v[82:85]
	v_mfma_f32_16x16x32_bf16 v[78:81], v[18:21], v[6:9], v[78:81]
	v_mfma_f32_16x16x32_bf16 v[70:73], v[22:25], v[6:9], v[70:73]
	v_mfma_f32_16x16x32_bf16 v[66:69], v[26:29], v[6:9], v[66:69]
	v_mfma_f32_16x16x32_bf16 v[62:65], v[54:57], v[6:9], v[62:65]
	v_mfma_f32_16x16x32_bf16 v[58:61], v[18:21], v[10:13], v[58:61]
	v_mfma_f32_16x16x32_bf16 v[50:53], v[22:25], v[10:13], v[50:53]
	v_mfma_f32_16x16x32_bf16 v[46:49], v[26:29], v[10:13], v[46:49]
	v_mfma_f32_16x16x32_bf16 v[42:45], v[54:57], v[10:13], v[42:45]
	v_mfma_f32_16x16x32_bf16 v[38:41], v[18:21], v[14:17], v[38:41]
	v_mfma_f32_16x16x32_bf16 v[34:37], v[22:25], v[14:17], v[34:37]
	v_mfma_f32_16x16x32_bf16 v[30:33], v[26:29], v[14:17], v[30:33]
	v_mfma_f32_16x16x32_bf16 v[74:77], v[54:57], v[14:17], v[74:77]
	s_nop 7
	s_nop 2
	s_branch .LBB0_272

.LBB0_398:
	v_mov_b64_e32 v[2:3], s[80:81]
	s_mov_b32 s4, 0x44000
	v_mad_u64_u32 v[4:5], s[0:1], v136, s4, v[2:3]
	v_mov_b64_e32 v[2:3], s[46:47]
	v_mad_i64_i32 v[6:7], s[0:1], v135, s4, v[2:3]
	v_mov_b32_e32 v2, v163
	s_mov_b32 s4, 0x22000
	v_ashrrev_i32_e32 v3, 3, v2
	v_lshlrev_b32_e32 v0, 4, v2
	v_mad_i64_i32 v[4:5], s[0:1], v3, s43, v[4:5]
	v_and_b32_e32 v0, 0x70, v0
	v_lshl_add_u64 v[130:131], v[4:5], 0, v[0:1]
	v_mad_i64_i32 v[4:5], s[0:1], v3, s43, v[6:7]
	v_lshl_add_u64 v[132:133], v[4:5], 0, v[0:1]
	v_and_b32_e32 v110, 7, v163
	v_bfe_u32 v111, v163, 4, 3
	v_xor_b32_e32 v111, v111, v110
	v_sub_u32_e32 v111, v111, v110
	v_lshlrev_b32_e32 v111, 4, v111
	v_lshrrev_b32_e32 v112, 6, v163
	v_lshlrev_b32_e32 v112, 10, v112
	v_readfirstlane_b32 s0, v130
	v_readfirstlane_b32 s1, v131
	v_readfirstlane_b32 s4, v132
	v_readfirstlane_b32 s5, v133
	v_readfirstlane_b32 s8, v112
	s_nop 3
	v_subrev_u32_e32 v98, s0, v130
	v_subrev_u32_e32 v102, s4, v132
	v_add_u32_e32 v98, v98, v111
	v_add_u32_e32 v102, v102, v111
	v_add_u32_e32 v99, 0x11000, v98
	v_add_u32_e32 v103, 0x11000, v102
	v_add_u32_e32 v100, 0x22000, v98
	v_add_u32_e32 v104, 0x22000, v102
	v_add_u32_e32 v101, 0x33000, v98
	v_add_u32_e32 v105, 0x33000, v102
	v_lshlrev_b32_e32 v110, 3, v163
	v_lshlrev_b32_e32 v111, 7, v163
	v_and_b32_e32 v112, 0x2000, v111
	v_and_b32_e32 v111, 0x780, v111
	v_and_b32_e32 v107, 64, v110
	v_xor_b32_e32 v110, v110, v163
	v_and_b32_e32 v110, 48, v110
	v_or3_b32 v110, v111, v107, v110
	v_lshlrev_b32_e32 v111, 6, v163
	v_and_b32_e32 v111, 0xffffe000, v111
	v_or_b32_e32 v108, v110, v112
	v_or_b32_e32 v106, v110, v111
	v_xor_b32_e32 v107, 64, v106
	v_xor_b32_e32 v109, 64, v108
	s_add_u32 m0, s8, 0x4000
	s_nop 0
	global_load_lds_dwordx4 v102, s[4:5]
	s_add_u32 m0, s8, 0x5000
	s_nop 0
	global_load_lds_dwordx4 v103, s[4:5]
	s_add_u32 m0, s8, 0x6000
	s_nop 0
	global_load_lds_dwordx4 v104, s[4:5]
	s_add_u32 m0, s8, 0x7000
	s_nop 0
	global_load_lds_dwordx4 v105, s[4:5]
	s_mov_b32 m0, s8
	s_nop 0
	global_load_lds_dwordx4 v98, s[0:1]
	s_add_u32 m0, s8, 0x1000
	s_nop 0
	global_load_lds_dwordx4 v99, s[0:1]
	s_add_u32 m0, s8, 0x2000
	s_nop 0
	global_load_lds_dwordx4 v100, s[0:1]
	s_add_u32 m0, s8, 0x3000
	s_nop 0
	global_load_lds_dwordx4 v101, s[0:1]
	s_waitcnt vmcnt(0)
	s_add_u32 s0, s0, 0x80
	s_addc_u32 s1, s1, 0
	s_add_u32 s4, s4, 0x80
	s_addc_u32 s5, s5, 0
	s_barrier
	s_add_u32 m0, s8, 0xc000
	ds_read_b128 v[142:145], v106
	ds_read_b128 v[158:161], v108 offset:16384
	s_nop 0
	global_load_lds_dwordx4 v102, s[4:5]
	s_add_u32 m0, s8, 0xd000
	ds_read_b128 v[182:185], v108 offset:18432
	ds_read_b128 v[186:189], v108 offset:20480
	s_nop 0
	global_load_lds_dwordx4 v103, s[4:5]
	s_add_u32 m0, s8, 0xe000
	ds_read_b128 v[206:209], v108 offset:22528
	ds_read_b128 v[146:149], v106 offset:2048
	s_nop 0
	global_load_lds_dwordx4 v104, s[4:5]
	s_add_u32 m0, s8, 0xf000
	ds_read_b128 v[150:153], v106 offset:4096
	ds_read_b128 v[154:157], v106 offset:6144
	s_nop 0
	global_load_lds_dwordx4 v105, s[4:5]
	s_add_u32 m0, s8, 0x8000
	s_nop 0
	global_load_lds_dwordx4 v98, s[0:1]
	s_add_u32 m0, s8, 0x9000
	s_nop 0
	global_load_lds_dwordx4 v99, s[0:1]
	s_add_u32 m0, s8, 0xa000
	s_nop 0
	global_load_lds_dwordx4 v100, s[0:1]
	s_add_u32 m0, s8, 0xb000
	s_nop 0
	global_load_lds_dwordx4 v101, s[0:1]
	s_add_u32 s0, s0, 0x80
	s_addc_u32 s1, s1, 0
	s_add_u32 s4, s4, 0x80
	s_addc_u32 s5, s5, 0
	s_waitcnt lgkmcnt(0)
	v_mfma_f32_16x16x32_bf16 v[94:97], v[158:161], v[142:145], 0
	ds_read_b128 v[50:53], v107
	ds_read_b128 v[66:69], v109 offset:16384
	v_mfma_f32_16x16x32_bf16 v[90:93], v[182:185], v[142:145], 0
	v_mfma_f32_16x16x32_bf16 v[86:89], v[186:189], v[142:145], 0
	ds_read_b128 v[70:73], v109 offset:18432
	ds_read_b128 v[78:81], v109 offset:20480
	v_mfma_f32_16x16x32_bf16 v[74:77], v[206:209], v[142:145], 0
	v_mfma_f32_16x16x32_bf16 v[46:49], v[158:161], v[146:149], 0
	ds_read_b128 v[82:85], v109 offset:22528
	ds_read_b128 v[54:57], v107 offset:2048
	v_mfma_f32_16x16x32_bf16 v[42:45], v[182:185], v[146:149], 0
	v_mfma_f32_16x16x32_bf16 v[38:41], v[186:189], v[146:149], 0
	ds_read_b128 v[58:61], v107 offset:4096
	ds_read_b128 v[62:65], v107 offset:6144
	v_mfma_f32_16x16x32_bf16 v[34:37], v[206:209], v[146:149], 0
	v_mfma_f32_16x16x32_bf16 v[30:33], v[158:161], v[150:153], 0
	v_mfma_f32_16x16x32_bf16 v[26:29], v[182:185], v[150:153], 0
	v_mfma_f32_16x16x32_bf16 v[22:25], v[186:189], v[150:153], 0
	v_mfma_f32_16x16x32_bf16 v[18:21], v[206:209], v[150:153], 0
	v_mfma_f32_16x16x32_bf16 v[14:17], v[158:161], v[154:157], 0
	v_mfma_f32_16x16x32_bf16 v[10:13], v[182:185], v[154:157], 0
	v_mfma_f32_16x16x32_bf16 v[2:5], v[186:189], v[154:157], 0
	v_mfma_f32_16x16x32_bf16 v[6:9], v[206:209], v[154:157], 0
	s_waitcnt vmcnt(0) lgkmcnt(0)
	s_barrier
	s_movk_i32 s9, 7
.Lg1_loop:
	v_mfma_f32_16x16x32_bf16 v[94:97], v[66:69], v[50:53], v[94:97]
	s_add_u32 m0, s8, 0x4000
	ds_read_b128 v[142:145], v106 offset:32768
	ds_read_b128 v[158:161], v108 offset:49152
	v_mfma_f32_16x16x32_bf16 v[90:93], v[70:73], v[50:53], v[90:93]
	global_load_lds_dwordx4 v102, s[4:5]
	v_mfma_f32_16x16x32_bf16 v[86:89], v[78:81], v[50:53], v[86:89]
	s_add_u32 m0, s8, 0x5000
	ds_read_b128 v[182:185], v108 offset:51200
	ds_read_b128 v[186:189], v108 offset:53248
	v_mfma_f32_16x16x32_bf16 v[74:77], v[82:85], v[50:53], v[74:77]
	global_load_lds_dwordx4 v103, s[4:5]
	v_mfma_f32_16x16x32_bf16 v[46:49], v[66:69], v[54:57], v[46:49]
	s_add_u32 m0, s8, 0x6000
	ds_read_b128 v[206:209], v108 offset:55296
	ds_read_b128 v[146:149], v106 offset:34816
	v_mfma_f32_16x16x32_bf16 v[42:45], v[70:73], v[54:57], v[42:45]
	global_load_lds_dwordx4 v104, s[4:5]
	v_mfma_f32_16x16x32_bf16 v[38:41], v[78:81], v[54:57], v[38:41]
	s_add_u32 m0, s8, 0x7000
	ds_read_b128 v[150:153], v106 offset:36864
	ds_read_b128 v[154:157], v106 offset:38912
	v_mfma_f32_16x16x32_bf16 v[34:37], v[82:85], v[54:57], v[34:37]
	global_load_lds_dwordx4 v105, s[4:5]
	v_mfma_f32_16x16x32_bf16 v[30:33], v[66:69], v[58:61], v[30:33]
	s_mov_b32 m0, s8
	v_mfma_f32_16x16x32_bf16 v[26:29], v[70:73], v[58:61], v[26:29]
	global_load_lds_dwordx4 v98, s[0:1]
	v_mfma_f32_16x16x32_bf16 v[22:25], v[78:81], v[58:61], v[22:25]
	s_add_u32 m0, s8, 0x1000
	v_mfma_f32_16x16x32_bf16 v[18:21], v[82:85], v[58:61], v[18:21]
	global_load_lds_dwordx4 v99, s[0:1]
	v_mfma_f32_16x16x32_bf16 v[14:17], v[66:69], v[62:65], v[14:17]
	s_add_u32 m0, s8, 0x2000
	v_mfma_f32_16x16x32_bf16 v[10:13], v[70:73], v[62:65], v[10:13]
	global_load_lds_dwordx4 v100, s[0:1]
	v_mfma_f32_16x16x32_bf16 v[2:5], v[78:81], v[62:65], v[2:5]
	s_add_u32 m0, s8, 0x3000
	v_mfma_f32_16x16x32_bf16 v[6:9], v[82:85], v[62:65], v[6:9]
	global_load_lds_dwordx4 v101, s[0:1]
	s_add_u32 s0, s0, 0x80
	s_addc_u32 s1, s1, 0
	s_add_u32 s4, s4, 0x80
	s_addc_u32 s5, s5, 0
	s_waitcnt lgkmcnt(0)
	v_mfma_f32_16x16x32_bf16 v[94:97], v[158:161], v[142:145], v[94:97]
	ds_read_b128 v[50:53], v107 offset:32768
	ds_read_b128 v[66:69], v109 offset:49152
	v_mfma_f32_16x16x32_bf16 v[90:93], v[182:185], v[142:145], v[90:93]
	v_mfma_f32_16x16x32_bf16 v[86:89], v[186:189], v[142:145], v[86:89]
	ds_read_b128 v[70:73], v109 offset:51200
	ds_read_b128 v[78:81], v109 offset:53248
	v_mfma_f32_16x16x32_bf16 v[74:77], v[206:209], v[142:145], v[74:77]
	v_mfma_f32_16x16x32_bf16 v[46:49], v[158:161], v[146:149], v[46:49]
	ds_read_b128 v[82:85], v109 offset:55296
	ds_read_b128 v[54:57], v107 offset:34816
	v_mfma_f32_16x16x32_bf16 v[42:45], v[182:185], v[146:149], v[42:45]
	v_mfma_f32_16x16x32_bf16 v[38:41], v[186:189], v[146:149], v[38:41]
	ds_read_b128 v[58:61], v107 offset:36864
	ds_read_b128 v[62:65], v107 offset:38912
	v_mfma_f32_16x16x32_bf16 v[34:37], v[206:209], v[146:149], v[34:37]
	v_mfma_f32_16x16x32_bf16 v[30:33], v[158:161], v[150:153], v[30:33]
	v_mfma_f32_16x16x32_bf16 v[26:29], v[182:185], v[150:153], v[26:29]
	v_mfma_f32_16x16x32_bf16 v[22:25], v[186:189], v[150:153], v[22:25]
	v_mfma_f32_16x16x32_bf16 v[18:21], v[206:209], v[150:153], v[18:21]
	v_mfma_f32_16x16x32_bf16 v[14:17], v[158:161], v[154:157], v[14:17]
	v_mfma_f32_16x16x32_bf16 v[10:13], v[182:185], v[154:157], v[10:13]
	v_mfma_f32_16x16x32_bf16 v[2:5], v[186:189], v[154:157], v[2:5]
	v_mfma_f32_16x16x32_bf16 v[6:9], v[206:209], v[154:157], v[6:9]
	s_waitcnt vmcnt(0) lgkmcnt(0)
	s_barrier
	v_mfma_f32_16x16x32_bf16 v[94:97], v[66:69], v[50:53], v[94:97]
	s_add_u32 m0, s8, 0xc000
	ds_read_b128 v[142:145], v106
	ds_read_b128 v[158:161], v108 offset:16384
	v_mfma_f32_16x16x32_bf16 v[90:93], v[70:73], v[50:53], v[90:93]
	global_load_lds_dwordx4 v102, s[4:5]
	v_mfma_f32_16x16x32_bf16 v[86:89], v[78:81], v[50:53], v[86:89]
	s_add_u32 m0, s8, 0xd000
	ds_read_b128 v[182:185], v108 offset:18432
	ds_read_b128 v[186:189], v108 offset:20480
	v_mfma_f32_16x16x32_bf16 v[74:77], v[82:85], v[50:53], v[74:77]
	global_load_lds_dwordx4 v103, s[4:5]
	v_mfma_f32_16x16x32_bf16 v[46:49], v[66:69], v[54:57], v[46:49]
	s_add_u32 m0, s8, 0xe000
	ds_read_b128 v[206:209], v108 offset:22528
	ds_read_b128 v[146:149], v106 offset:2048
	v_mfma_f32_16x16x32_bf16 v[42:45], v[70:73], v[54:57], v[42:45]
	global_load_lds_dwordx4 v104, s[4:5]
	v_mfma_f32_16x16x32_bf16 v[38:41], v[78:81], v[54:57], v[38:41]
	s_add_u32 m0, s8, 0xf000
	ds_read_b128 v[150:153], v106 offset:4096
	ds_read_b128 v[154:157], v106 offset:6144
	v_mfma_f32_16x16x32_bf16 v[34:37], v[82:85], v[54:57], v[34:37]
	global_load_lds_dwordx4 v105, s[4:5]
	v_mfma_f32_16x16x32_bf16 v[30:33], v[66:69], v[58:61], v[30:33]
	s_add_u32 m0, s8, 0x8000
	v_mfma_f32_16x16x32_bf16 v[26:29], v[70:73], v[58:61], v[26:29]
	global_load_lds_dwordx4 v98, s[0:1]
	v_mfma_f32_16x16x32_bf16 v[22:25], v[78:81], v[58:61], v[22:25]
	s_add_u32 m0, s8, 0x9000
	v_mfma_f32_16x16x32_bf16 v[18:21], v[82:85], v[58:61], v[18:21]
	global_load_lds_dwordx4 v99, s[0:1]
	v_mfma_f32_16x16x32_bf16 v[14:17], v[66:69], v[62:65], v[14:17]
	s_add_u32 m0, s8, 0xa000
	v_mfma_f32_16x16x32_bf16 v[10:13], v[70:73], v[62:65], v[10:13]
	global_load_lds_dwordx4 v100, s[0:1]
	v_mfma_f32_16x16x32_bf16 v[2:5], v[78:81], v[62:65], v[2:5]
	s_add_u32 m0, s8, 0xb000
	v_mfma_f32_16x16x32_bf16 v[6:9], v[82:85], v[62:65], v[6:9]
	global_load_lds_dwordx4 v101, s[0:1]
	s_add_u32 s0, s0, 0x80
	s_addc_u32 s1, s1, 0
	s_add_u32 s4, s4, 0x80
	s_addc_u32 s5, s5, 0
	s_waitcnt lgkmcnt(0)
	v_mfma_f32_16x16x32_bf16 v[94:97], v[158:161], v[142:145], v[94:97]
	ds_read_b128 v[50:53], v107
	ds_read_b128 v[66:69], v109 offset:16384
	v_mfma_f32_16x16x32_bf16 v[90:93], v[182:185], v[142:145], v[90:93]
	v_mfma_f32_16x16x32_bf16 v[86:89], v[186:189], v[142:145], v[86:89]
	ds_read_b128 v[70:73], v109 offset:18432
	ds_read_b128 v[78:81], v109 offset:20480
	v_mfma_f32_16x16x32_bf16 v[74:77], v[206:209], v[142:145], v[74:77]
	v_mfma_f32_16x16x32_bf16 v[46:49], v[158:161], v[146:149], v[46:49]
	ds_read_b128 v[82:85], v109 offset:22528
	ds_read_b128 v[54:57], v107 offset:2048
	v_mfma_f32_16x16x32_bf16 v[42:45], v[182:185], v[146:149], v[42:45]
	v_mfma_f32_16x16x32_bf16 v[38:41], v[186:189], v[146:149], v[38:41]
	ds_read_b128 v[58:61], v107 offset:4096
	ds_read_b128 v[62:65], v107 offset:6144
	v_mfma_f32_16x16x32_bf16 v[34:37], v[206:209], v[146:149], v[34:37]
	v_mfma_f32_16x16x32_bf16 v[30:33], v[158:161], v[150:153], v[30:33]
	v_mfma_f32_16x16x32_bf16 v[26:29], v[182:185], v[150:153], v[26:29]
	v_mfma_f32_16x16x32_bf16 v[22:25], v[186:189], v[150:153], v[22:25]
	v_mfma_f32_16x16x32_bf16 v[18:21], v[206:209], v[150:153], v[18:21]
	v_mfma_f32_16x16x32_bf16 v[14:17], v[158:161], v[154:157], v[14:17]
	v_mfma_f32_16x16x32_bf16 v[10:13], v[182:185], v[154:157], v[10:13]
	v_mfma_f32_16x16x32_bf16 v[2:5], v[186:189], v[154:157], v[2:5]
	v_mfma_f32_16x16x32_bf16 v[6:9], v[206:209], v[154:157], v[6:9]
	s_add_i32 s9, s9, -1
	s_waitcnt vmcnt(0) lgkmcnt(0)
	s_barrier
	s_cmp_lg_u32 s9, 0
	s_cbranch_scc1 .Lg1_loop
	v_mfma_f32_16x16x32_bf16 v[94:97], v[66:69], v[50:53], v[94:97]
	ds_read_b128 v[142:145], v106 offset:32768
	ds_read_b128 v[158:161], v108 offset:49152
	v_mfma_f32_16x16x32_bf16 v[90:93], v[70:73], v[50:53], v[90:93]
	v_mfma_f32_16x16x32_bf16 v[86:89], v[78:81], v[50:53], v[86:89]
	ds_read_b128 v[182:185], v108 offset:51200
	ds_read_b128 v[186:189], v108 offset:53248
	v_mfma_f32_16x16x32_bf16 v[74:77], v[82:85], v[50:53], v[74:77]
	v_mfma_f32_16x16x32_bf16 v[46:49], v[66:69], v[54:57], v[46:49]
	ds_read_b128 v[206:209], v108 offset:55296
	ds_read_b128 v[146:149], v106 offset:34816
	v_mfma_f32_16x16x32_bf16 v[42:45], v[70:73], v[54:57], v[42:45]
	v_mfma_f32_16x16x32_bf16 v[38:41], v[78:81], v[54:57], v[38:41]
	ds_read_b128 v[150:153], v106 offset:36864
	ds_read_b128 v[154:157], v106 offset:38912
	v_mfma_f32_16x16x32_bf16 v[34:37], v[82:85], v[54:57], v[34:37]
	v_mfma_f32_16x16x32_bf16 v[30:33], v[66:69], v[58:61], v[30:33]
	v_mfma_f32_16x16x32_bf16 v[26:29], v[70:73], v[58:61], v[26:29]
	v_mfma_f32_16x16x32_bf16 v[22:25], v[78:81], v[58:61], v[22:25]
	v_mfma_f32_16x16x32_bf16 v[18:21], v[82:85], v[58:61], v[18:21]
	v_mfma_f32_16x16x32_bf16 v[14:17], v[66:69], v[62:65], v[14:17]
	v_mfma_f32_16x16x32_bf16 v[10:13], v[70:73], v[62:65], v[10:13]
	v_mfma_f32_16x16x32_bf16 v[2:5], v[78:81], v[62:65], v[2:5]
	v_mfma_f32_16x16x32_bf16 v[6:9], v[82:85], v[62:65], v[6:9]
	s_waitcnt lgkmcnt(0)
	v_mfma_f32_16x16x32_bf16 v[94:97], v[158:161], v[142:145], v[94:97]
	ds_read_b128 v[50:53], v107 offset:32768
	ds_read_b128 v[66:69], v109 offset:49152
	v_mfma_f32_16x16x32_bf16 v[90:93], v[182:185], v[142:145], v[90:93]
	v_mfma_f32_16x16x32_bf16 v[86:89], v[186:189], v[142:145], v[86:89]
	ds_read_b128 v[70:73], v109 offset:51200
	ds_read_b128 v[78:81], v109 offset:53248
	v_mfma_f32_16x16x32_bf16 v[74:77], v[206:209], v[142:145], v[74:77]
	v_mfma_f32_16x16x32_bf16 v[46:49], v[158:161], v[146:149], v[46:49]
	ds_read_b128 v[82:85], v109 offset:55296
	ds_read_b128 v[54:57], v107 offset:34816
	v_mfma_f32_16x16x32_bf16 v[42:45], v[182:185], v[146:149], v[42:45]
	v_mfma_f32_16x16x32_bf16 v[38:41], v[186:189], v[146:149], v[38:41]
	ds_read_b128 v[58:61], v107 offset:36864
	ds_read_b128 v[62:65], v107 offset:38912
	v_mfma_f32_16x16x32_bf16 v[34:37], v[206:209], v[146:149], v[34:37]
	v_mfma_f32_16x16x32_bf16 v[30:33], v[158:161], v[150:153], v[30:33]
	v_mfma_f32_16x16x32_bf16 v[26:29], v[182:185], v[150:153], v[26:29]
	v_mfma_f32_16x16x32_bf16 v[22:25], v[186:189], v[150:153], v[22:25]
	v_mfma_f32_16x16x32_bf16 v[18:21], v[206:209], v[150:153], v[18:21]
	v_mfma_f32_16x16x32_bf16 v[14:17], v[158:161], v[154:157], v[14:17]
	v_mfma_f32_16x16x32_bf16 v[10:13], v[182:185], v[154:157], v[10:13]
	v_mfma_f32_16x16x32_bf16 v[2:5], v[186:189], v[154:157], v[2:5]
	v_mfma_f32_16x16x32_bf16 v[6:9], v[206:209], v[154:157], v[6:9]
	s_waitcnt lgkmcnt(0)
	s_barrier
	v_mfma_f32_16x16x32_bf16 v[94:97], v[66:69], v[50:53], v[94:97]
	v_mfma_f32_16x16x32_bf16 v[90:93], v[70:73], v[50:53], v[90:93]
	v_mfma_f32_16x16x32_bf16 v[86:89], v[78:81], v[50:53], v[86:89]
	v_mfma_f32_16x16x32_bf16 v[74:77], v[82:85], v[50:53], v[74:77]
	v_mfma_f32_16x16x32_bf16 v[46:49], v[66:69], v[54:57], v[46:49]
	v_mfma_f32_16x16x32_bf16 v[42:45], v[70:73], v[54:57], v[42:45]
	v_mfma_f32_16x16x32_bf16 v[38:41], v[78:81], v[54:57], v[38:41]
	v_mfma_f32_16x16x32_bf16 v[34:37], v[82:85], v[54:57], v[34:37]
	v_mfma_f32_16x16x32_bf16 v[30:33], v[66:69], v[58:61], v[30:33]
	v_mfma_f32_16x16x32_bf16 v[26:29], v[70:73], v[58:61], v[26:29]
	v_mfma_f32_16x16x32_bf16 v[22:25], v[78:81], v[58:61], v[22:25]
	v_mfma_f32_16x16x32_bf16 v[18:21], v[82:85], v[58:61], v[18:21]
	v_mfma_f32_16x16x32_bf16 v[14:17], v[66:69], v[62:65], v[14:17]
	v_mfma_f32_16x16x32_bf16 v[10:13], v[70:73], v[62:65], v[10:13]
	v_mfma_f32_16x16x32_bf16 v[2:5], v[78:81], v[62:65], v[2:5]
	v_mfma_f32_16x16x32_bf16 v[6:9], v[82:85], v[62:65], v[6:9]
	s_nop 7
	s_nop 2
